# GEMM K-loops: loader half-wave delayed by s_sleep 2 at the start of each load segment (keeps its LDS/DMA burst out of the partner MFMA segment head); on top of v12
# speedup vs baseline: 1.0074x; 1.0074x over previous
; #define PG8_STAGE(bufoff, gbase, voff) do { _Pragma("unroll") for (int _i = 0; _i < 2; ++_i) \
;         __builtin_amdgcn_global_load_lds((const unsigned*)((const char*)(gbase) + (voff)[_i]), (PG8_LAS unsigned*)(lds + (bufoff) + ldsw + _i * 8192), 16, 0, 0); } while (0)
; #define PG8_LDA(dst, b, h) do { _Pragma("unroll") for (int m = 0; m < 4; ++m) _Pragma("unroll") for (int k = 0; k < 2; ++k) dst[m][k] = *(const PG8_LAS bf16x8*)(lds + PG8_SA(b, h) + aoff + m * 2048 + k * 1024); } while (0)
; #define PG8_LDB(dst, b, h) do { _Pragma("unroll") for (int n = 0; n < 2; ++n) _Pragma("unroll") for (int k = 0; k < 2; ++k) dst[n][k] = *(const PG8_LAS bf16x8*)(lds + PG8_SB(b, h) + boff + n * 2048 + k * 1024); } while (0)
; template <class Epi, class Sched, bool ALIGN_EPI = false, bool SP2 = false>
; __device__ __forceinline__ void gemm_phase(PG8_LAS unsigned char* lds, const Gemm g, const Sched& S, const Epi& E) {
;     ...
;         for (int t = 0; t < nt; t += 2) {
;             const bool last = (t == nt - 2);
;             const char* a1 = cA + (size_t)(t + 1) * kstep;
;             const char* a2 = last ? nA : cA + (size_t)(t + 2) * kstep; const char* b2 = last ? nB : cB + (size_t)(t + 2) * kstep;
;             const char* a3 = a2 + kstep; const char* b3 = b2 + kstep;
;             if (last && has_next) S.a_ready(nxt);
;             if constexpr (SP2) {
;             PG8_LDB(B0, 0, 0); PG8_LDB(B1, 0, 1); PG8_SCHED; PG8_LDA(At, 0, 0); PG8_STAGE(PG8_SA(1, 1), a1 + hstep, voffA);
;             PG8_WAIT_V(8); PG8_WAIT_L(0); PG8_BAR; PG8_MMA(0, 0, At, B0); PG8_MMA(0, 1, At, B1); PG8_BAR; PG8_SCHED;
;             PG8_LDA(At, 0, 1); PG8_STAGE(PG8_SB(0, 0), b2, voffB); PG8_STAGE(PG8_SB(0, 1), b2 + hstep, voffB); PG8_STAGE(PG8_SA(0, 0), a2, voffA);
;             PG8_WAIT_V(8); PG8_WAIT_L(0); PG8_BAR; PG8_MMA(1, 0, At, B0); PG8_MMA(1, 1, At, B1); PG8_BAR; PG8_SCHED;
;             PG8_LDB(B0, 1, 0); PG8_LDB(B1, 1, 1); PG8_SCHED; PG8_LDA(At, 1, 0); PG8_STAGE(PG8_SA(0, 1), a2 + hstep, voffA);
;             PG8_WAIT_V(8); PG8_WAIT_L(0); PG8_BAR; PG8_MMA(0, 0, At, B0); PG8_MMA(0, 1, At, B1); PG8_BAR; PG8_SCHED;
;             PG8_LDA(At, 1, 1); PG8_STAGE(PG8_SB(1, 0), b3, voffB); PG8_STAGE(PG8_SB(1, 1), b3 + hstep, voffB); PG8_STAGE(PG8_SA(1, 0), a3, voffA);
;             PG8_WAIT_V(8); PG8_WAIT_L(0); PG8_BAR; PG8_MMA(1, 0, At, B0); PG8_MMA(1, 1, At, B1); PG8_BAR; PG8_SCHED;
.LBB0_93:
	ds_read_b128 v[146:149], v153
	ds_read_b128 v[156:159], v153 offset:1024
	ds_read_b128 v[160:163], v153 offset:2048
	ds_read_b128 v[164:167], v153 offset:3072
	ds_read_b128 v[168:171], v154
	ds_read_b128 v[172:175], v154 offset:1024
	ds_read_b128 v[176:179], v154 offset:2048
	ds_read_b128 v[184:187], v154 offset:3072
	s_add_u32 s48, s44, 0xfff80080
	s_addc_u32 s49, s45, -1
	s_cmp_eq_u32 s89, 28
	s_cselect_b32 s59, s25, s49
	s_cselect_b32 s58, s84, s48
	s_cselect_b32 s49, s13, s87
	s_cselect_b32 s48, s85, s86
	v_lshl_add_u64 v[180:181], s[44:45], 0, v[136:137]
	s_add_i32 m0, s35, 0xc000
	ds_read_b128 v[188:191], v155
	ds_read_b128 v[192:195], v155 offset:1024
	ds_read_b128 v[196:199], v155 offset:2048
	ds_read_b128 v[200:203], v155 offset:3072
	ds_read_b128 v[204:207], v155 offset:4096
	ds_read_b128 v[208:211], v155 offset:5120
	ds_read_b128 v[212:215], v155 offset:6144
	ds_read_b128 v[216:219], v155 offset:7168
	global_load_lds_dwordx4 v[180:181], off
	v_lshl_add_u64 v[180:181], s[44:45], 0, v[138:139]
	s_add_i32 m0, s35, 0xe000
	s_nop 0
	global_load_lds_dwordx4 v[180:181], off
	s_waitcnt vmcnt(8)
	s_waitcnt lgkmcnt(0)
	s_barrier
	s_setprio 1
	s_waitcnt lgkmcnt(0)
	v_mfma_f32_16x16x32_bf16 v[124:127], v[146:149], v[188:191], v[124:127]
	v_mfma_f32_16x16x32_bf16 v[120:123], v[160:163], v[188:191], v[120:123]
	v_mfma_f32_16x16x32_bf16 v[108:111], v[146:149], v[196:199], v[108:111]
	v_mfma_f32_16x16x32_bf16 v[104:107], v[160:163], v[196:199], v[104:107]
	v_mfma_f32_16x16x32_bf16 v[92:95], v[146:149], v[204:207], v[92:95]
	v_mfma_f32_16x16x32_bf16 v[88:91], v[160:163], v[204:207], v[88:91]
	v_mfma_f32_16x16x32_bf16 v[76:79], v[146:149], v[212:215], v[76:79]
	v_mfma_f32_16x16x32_bf16 v[72:75], v[160:163], v[212:215], v[72:75]
	v_mfma_f32_16x16x32_bf16 v[124:127], v[156:159], v[192:195], v[124:127]
	v_mfma_f32_16x16x32_bf16 v[120:123], v[164:167], v[192:195], v[120:123]
	v_mfma_f32_16x16x32_bf16 v[108:111], v[156:159], v[200:203], v[108:111]
	v_mfma_f32_16x16x32_bf16 v[104:107], v[164:167], v[200:203], v[104:107]
	v_mfma_f32_16x16x32_bf16 v[92:95], v[156:159], v[208:211], v[92:95]
	v_mfma_f32_16x16x32_bf16 v[88:91], v[164:167], v[208:211], v[88:91]
	v_mfma_f32_16x16x32_bf16 v[76:79], v[156:159], v[216:219], v[76:79]
	v_mfma_f32_16x16x32_bf16 v[72:75], v[164:167], v[216:219], v[72:75]
	s_setprio 0
	s_setprio 1
	v_mfma_f32_16x16x32_bf16 v[116:119], v[168:171], v[188:191], v[116:119]
	v_mfma_f32_16x16x32_bf16 v[112:115], v[176:179], v[188:191], v[112:115]
	v_mfma_f32_16x16x32_bf16 v[100:103], v[168:171], v[196:199], v[100:103]
	v_mfma_f32_16x16x32_bf16 v[96:99], v[176:179], v[196:199], v[96:99]
	v_mfma_f32_16x16x32_bf16 v[84:87], v[168:171], v[204:207], v[84:87]
	v_mfma_f32_16x16x32_bf16 v[80:83], v[176:179], v[204:207], v[80:83]
	v_mfma_f32_16x16x32_bf16 v[68:71], v[168:171], v[212:215], v[68:71]
	v_mfma_f32_16x16x32_bf16 v[64:67], v[176:179], v[212:215], v[64:67]
	v_mfma_f32_16x16x32_bf16 v[116:119], v[172:175], v[192:195], v[116:119]
	v_mfma_f32_16x16x32_bf16 v[112:115], v[184:187], v[192:195], v[112:115]
	v_mfma_f32_16x16x32_bf16 v[100:103], v[172:175], v[200:203], v[100:103]
	v_mfma_f32_16x16x32_bf16 v[96:99], v[184:187], v[200:203], v[96:99]
	v_mfma_f32_16x16x32_bf16 v[84:87], v[172:175], v[208:211], v[84:87]
	v_mfma_f32_16x16x32_bf16 v[80:83], v[184:187], v[208:211], v[80:83]
	v_mfma_f32_16x16x32_bf16 v[68:71], v[172:175], v[216:219], v[68:71]
	v_mfma_f32_16x16x32_bf16 v[64:67], v[184:187], v[216:219], v[64:67]
	s_setprio 0
	s_barrier
	s_sleep 2
	s_add_i32 s90, s66, s29
	v_lshl_add_u64 v[180:181], s[48:49], 0, v[130:131]
	s_mov_b32 m0, s90
	ds_read_b128 v[188:191], v155 offset:16384
	ds_read_b128 v[192:195], v155 offset:17408
	ds_read_b128 v[196:199], v155 offset:18432
	ds_read_b128 v[200:203], v155 offset:19456
	ds_read_b128 v[204:207], v155 offset:20480
	ds_read_b128 v[208:211], v155 offset:21504
	ds_read_b128 v[212:215], v155 offset:22528
	ds_read_b128 v[216:219], v155 offset:23552
	global_load_lds_dwordx4 v[180:181], off
	s_add_i32 m0, s90, 0x2000
	s_add_u32 s92, s48, 0x80000
	v_lshl_add_u64 v[220:221], s[48:49], 0, v[134:135]
	s_addc_u32 s93, s49, 0
	s_add_i32 s90, s67, s29
	global_load_lds_dwordx4 v[220:221], off
	v_lshl_add_u64 v[222:223], s[92:93], 0, v[130:131]
	s_mov_b32 m0, s90
	v_lshl_add_u64 v[224:225], s[58:59], 0, v[132:133]
	global_load_lds_dwordx4 v[222:223], off
	v_lshl_add_u64 v[222:223], s[92:93], 0, v[134:135]
	s_add_i32 m0, s90, 0x2000
	s_nop 0
	global_load_lds_dwordx4 v[222:223], off
	v_lshl_add_u64 v[222:223], s[58:59], 0, v[128:129]
	s_mov_b32 m0, s35
	s_nop 0
	global_load_lds_dwordx4 v[222:223], off
	s_mov_b32 m0, s43
	s_nop 0
	global_load_lds_dwordx4 v[224:225], off
	s_waitcnt vmcnt(8)
	s_waitcnt lgkmcnt(0)
	s_barrier
; #define PG8_STAGE(bufoff, gbase, voff) do { _Pragma("unroll") for (int _i = 0; _i < 2; ++_i) \
;         __builtin_amdgcn_global_load_lds((const unsigned*)((const char*)(gbase) + (voff)[_i]), (PG8_LAS unsigned*)(lds + (bufoff) + ldsw + _i * 8192), 16, 0, 0); } while (0)
; #define PG8_LDA(dst, b, h) do { _Pragma("unroll") for (int m = 0; m < 4; ++m) _Pragma("unroll") for (int k = 0; k < 2; ++k) dst[m][k] = *(const PG8_LAS bf16x8*)(lds + PG8_SA(b, h) + aoff + m * 2048 + k * 1024); } while (0)
; #define PG8_LDB(dst, b, h) do { _Pragma("unroll") for (int n = 0; n < 2; ++n) _Pragma("unroll") for (int k = 0; k < 2; ++k) dst[n][k] = *(const PG8_LAS bf16x8*)(lds + PG8_SB(b, h) + boff + n * 2048 + k * 1024); } while (0)
; #define PG8_MMA(ai, bj, At, Bt) do { __builtin_amdgcn_s_setprio(1); _Pragma("unroll") for (int m = 0; m < 4; ++m) _Pragma("unroll") for (int n = 0; n < 2; ++n) _Pragma("unroll") for (int k = 0; k < 2; ++k) \
;         acc[ai][bj][m][n] = __builtin_amdgcn_mfma_f32_16x16x32_bf16(Bt[n][k], At[m][k], acc[ai][bj][m][n], 0, 0, 0); __builtin_amdgcn_s_setprio(0); } while (0)
; #define PG8_WAIT_V(n) asm volatile("s_waitcnt vmcnt(" #n ")" ::: "memory")
; template <class Epi, class Sched, bool ALIGN_EPI = false, bool SP2 = false>
; __device__ __forceinline__ void gemm_phase(PG8_LAS unsigned char* lds, const Gemm g, const Sched& S, const Epi& E) {
;     ...
;             PG8_LDB(B0, 0, 0); PG8_LDB(B1, 0, 1); PG8_SCHED; PG8_LDA(At, 0, 0); PG8_STAGE(PG8_SA(1, 1), a1 + hstep, voffA);
;             PG8_WAIT_V(8); PG8_WAIT_L(0); PG8_BAR; PG8_MMA(0, 0, At, B0); PG8_MMA(0, 1, At, B1); PG8_BAR; PG8_SCHED;
;             PG8_LDA(At, 0, 1); PG8_STAGE(PG8_SB(0, 0), b2, voffB); PG8_STAGE(PG8_SB(0, 1), b2 + hstep, voffB); PG8_STAGE(PG8_SA(0, 0), a2, voffA);
;             PG8_WAIT_V(8); PG8_WAIT_L(0); PG8_BAR; PG8_MMA(1, 0, At, B0); PG8_MMA(1, 1, At, B1); PG8_BAR; PG8_SCHED;
;             PG8_LDB(B0, 1, 0); PG8_LDB(B1, 1, 1); PG8_SCHED; PG8_LDA(At, 1, 0); PG8_STAGE(PG8_SA(0, 1), a2 + hstep, voffA);
;             PG8_WAIT_V(8); PG8_WAIT_L(0); PG8_BAR; PG8_MMA(0, 0, At, B0); PG8_MMA(0, 1, At, B1); PG8_BAR; PG8_SCHED;
;             PG8_LDA(At, 1, 1); PG8_STAGE(PG8_SB(1, 0), b3, voffB); PG8_STAGE(PG8_SB(1, 1), b3 + hstep, voffB); PG8_STAGE(PG8_SA(1, 0), a3, voffA);
;             PG8_WAIT_V(8); PG8_WAIT_L(0); PG8_BAR; PG8_MMA(1, 0, At, B0); PG8_MMA(1, 1, At, B1); PG8_BAR; PG8_SCHED;
	s_setprio 1
	s_waitcnt lgkmcnt(0)
	v_mfma_f32_16x16x32_bf16 v[60:63], v[146:149], v[188:191], v[60:63]
	v_mfma_f32_16x16x32_bf16 v[56:59], v[160:163], v[188:191], v[56:59]
	v_mfma_f32_16x16x32_bf16 v[44:47], v[146:149], v[196:199], v[44:47]
	v_mfma_f32_16x16x32_bf16 v[40:43], v[160:163], v[196:199], v[40:43]
	v_mfma_f32_16x16x32_bf16 v[28:31], v[146:149], v[204:207], v[28:31]
	v_mfma_f32_16x16x32_bf16 v[24:27], v[160:163], v[204:207], v[24:27]
	v_mfma_f32_16x16x32_bf16 v[12:15], v[146:149], v[212:215], v[12:15]
	v_mfma_f32_16x16x32_bf16 v[8:11], v[160:163], v[212:215], v[8:11]
	v_mfma_f32_16x16x32_bf16 v[60:63], v[156:159], v[192:195], v[60:63]
	v_mfma_f32_16x16x32_bf16 v[56:59], v[164:167], v[192:195], v[56:59]
	v_mfma_f32_16x16x32_bf16 v[44:47], v[156:159], v[200:203], v[44:47]
	v_mfma_f32_16x16x32_bf16 v[40:43], v[164:167], v[200:203], v[40:43]
	v_mfma_f32_16x16x32_bf16 v[28:31], v[156:159], v[208:211], v[28:31]
	v_mfma_f32_16x16x32_bf16 v[24:27], v[164:167], v[208:211], v[24:27]
	v_mfma_f32_16x16x32_bf16 v[12:15], v[156:159], v[216:219], v[12:15]
	v_mfma_f32_16x16x32_bf16 v[8:11], v[164:167], v[216:219], v[8:11]
	s_setprio 0
	s_setprio 1
	v_mfma_f32_16x16x32_bf16 v[52:55], v[168:171], v[188:191], v[52:55]
	v_mfma_f32_16x16x32_bf16 v[48:51], v[176:179], v[188:191], v[48:51]
	v_mfma_f32_16x16x32_bf16 v[36:39], v[168:171], v[196:199], v[36:39]
	v_mfma_f32_16x16x32_bf16 v[32:35], v[176:179], v[196:199], v[32:35]
	v_mfma_f32_16x16x32_bf16 v[20:23], v[168:171], v[204:207], v[20:23]
	v_mfma_f32_16x16x32_bf16 v[16:19], v[176:179], v[204:207], v[16:19]
	v_mfma_f32_16x16x32_bf16 v[4:7], v[168:171], v[212:215], v[4:7]
	v_mfma_f32_16x16x32_bf16 v[0:3], v[176:179], v[212:215], v[0:3]
	v_mfma_f32_16x16x32_bf16 v[52:55], v[172:175], v[192:195], v[52:55]
	v_mfma_f32_16x16x32_bf16 v[48:51], v[184:187], v[192:195], v[48:51]
	v_mfma_f32_16x16x32_bf16 v[36:39], v[172:175], v[200:203], v[36:39]
	v_mfma_f32_16x16x32_bf16 v[32:35], v[184:187], v[200:203], v[32:35]
	v_mfma_f32_16x16x32_bf16 v[20:23], v[172:175], v[208:211], v[20:23]
	v_mfma_f32_16x16x32_bf16 v[16:19], v[184:187], v[208:211], v[16:19]
	v_mfma_f32_16x16x32_bf16 v[4:7], v[172:175], v[216:219], v[4:7]
	v_mfma_f32_16x16x32_bf16 v[0:3], v[184:187], v[216:219], v[0:3]
	s_setprio 0
	s_barrier
	s_sleep 2
	s_add_i32 s90, 0, 0x18000
	s_add_i32 s92, 0, 0x1c000
	v_add_u32_e32 v164, s90, v151
	v_add_u32_e32 v184, s92, v151
	ds_read_b128 v[146:149], v164
	ds_read_b128 v[156:159], v164 offset:1024
	ds_read_b128 v[160:163], v164 offset:2048
	ds_read_b128 v[164:167], v164 offset:3072
	ds_read_b128 v[168:171], v184
	ds_read_b128 v[172:175], v184 offset:1024
	ds_read_b128 v[176:179], v184 offset:2048
	ds_read_b128 v[184:187], v184 offset:3072
	s_add_u32 s58, s58, 0x80000
	s_addc_u32 s59, s59, 0
	s_mov_b32 m0, s60
	v_lshl_add_u64 v[226:227], s[58:59], 0, v[128:129]
	ds_read_b128 v[188:191], v155 offset:32768
	ds_read_b128 v[192:195], v155 offset:33792
	ds_read_b128 v[196:199], v155 offset:34816
	ds_read_b128 v[200:203], v155 offset:35840
	ds_read_b128 v[204:207], v155 offset:36864
	ds_read_b128 v[208:211], v155 offset:37888
	ds_read_b128 v[212:215], v155 offset:38912
	ds_read_b128 v[216:219], v155 offset:39936
	global_load_lds_dwordx4 v[226:227], off
	v_lshl_add_u64 v[226:227], s[58:59], 0, v[132:133]
	s_mov_b32 m0, s61
	s_nop 0
	global_load_lds_dwordx4 v[226:227], off
	s_waitcnt vmcnt(8)
	s_waitcnt lgkmcnt(0)
	s_barrier
	s_setprio 1
	s_waitcnt lgkmcnt(0)
	v_mfma_f32_16x16x32_bf16 v[124:127], v[146:149], v[188:191], v[124:127]
	v_mfma_f32_16x16x32_bf16 v[120:123], v[160:163], v[188:191], v[120:123]
	v_mfma_f32_16x16x32_bf16 v[108:111], v[146:149], v[196:199], v[108:111]
	v_mfma_f32_16x16x32_bf16 v[104:107], v[160:163], v[196:199], v[104:107]
	v_mfma_f32_16x16x32_bf16 v[92:95], v[146:149], v[204:207], v[92:95]
	v_mfma_f32_16x16x32_bf16 v[88:91], v[160:163], v[204:207], v[88:91]
	v_mfma_f32_16x16x32_bf16 v[76:79], v[146:149], v[212:215], v[76:79]
	v_mfma_f32_16x16x32_bf16 v[72:75], v[160:163], v[212:215], v[72:75]
	v_mfma_f32_16x16x32_bf16 v[124:127], v[156:159], v[192:195], v[124:127]
	v_mfma_f32_16x16x32_bf16 v[120:123], v[164:167], v[192:195], v[120:123]
	v_mfma_f32_16x16x32_bf16 v[108:111], v[156:159], v[200:203], v[108:111]
	v_mfma_f32_16x16x32_bf16 v[104:107], v[164:167], v[200:203], v[104:107]
	v_mfma_f32_16x16x32_bf16 v[92:95], v[156:159], v[208:211], v[92:95]
	v_mfma_f32_16x16x32_bf16 v[88:91], v[164:167], v[208:211], v[88:91]
	v_mfma_f32_16x16x32_bf16 v[76:79], v[156:159], v[216:219], v[76:79]
	v_mfma_f32_16x16x32_bf16 v[72:75], v[164:167], v[216:219], v[72:75]
	s_setprio 0
	s_setprio 1
	v_mfma_f32_16x16x32_bf16 v[116:119], v[168:171], v[188:191], v[116:119]
	v_mfma_f32_16x16x32_bf16 v[112:115], v[176:179], v[188:191], v[112:115]
	v_mfma_f32_16x16x32_bf16 v[100:103], v[168:171], v[196:199], v[100:103]
	v_mfma_f32_16x16x32_bf16 v[96:99], v[176:179], v[196:199], v[96:99]
	v_mfma_f32_16x16x32_bf16 v[84:87], v[168:171], v[204:207], v[84:87]
	v_mfma_f32_16x16x32_bf16 v[80:83], v[176:179], v[204:207], v[80:83]
	v_mfma_f32_16x16x32_bf16 v[68:71], v[168:171], v[212:215], v[68:71]
	v_mfma_f32_16x16x32_bf16 v[64:67], v[176:179], v[212:215], v[64:67]
	v_mfma_f32_16x16x32_bf16 v[116:119], v[172:175], v[192:195], v[116:119]
	v_mfma_f32_16x16x32_bf16 v[112:115], v[184:187], v[192:195], v[112:115]
	v_mfma_f32_16x16x32_bf16 v[100:103], v[172:175], v[200:203], v[100:103]
	v_mfma_f32_16x16x32_bf16 v[96:99], v[184:187], v[200:203], v[96:99]
	v_mfma_f32_16x16x32_bf16 v[84:87], v[172:175], v[208:211], v[84:87]
	v_mfma_f32_16x16x32_bf16 v[80:83], v[184:187], v[208:211], v[80:83]
	v_mfma_f32_16x16x32_bf16 v[68:71], v[172:175], v[216:219], v[68:71]
	v_mfma_f32_16x16x32_bf16 v[64:67], v[184:187], v[216:219], v[64:67]
	s_setprio 0
	s_barrier
; #define PG8_STAGE(bufoff, gbase, voff) do { _Pragma("unroll") for (int _i = 0; _i < 2; ++_i) \
;         __builtin_amdgcn_global_load_lds((const unsigned*)((const char*)(gbase) + (voff)[_i]), (PG8_LAS unsigned*)(lds + (bufoff) + ldsw + _i * 8192), 16, 0, 0); } while (0)
; #define PG8_LDA(dst, b, h) do { _Pragma("unroll") for (int m = 0; m < 4; ++m) _Pragma("unroll") for (int k = 0; k < 2; ++k) dst[m][k] = *(const PG8_LAS bf16x8*)(lds + PG8_SA(b, h) + aoff + m * 2048 + k * 1024); } while (0)
; #define PG8_WAIT_V(n) asm volatile("s_waitcnt vmcnt(" #n ")" ::: "memory")
; template <class Epi, class Sched, bool ALIGN_EPI = false, bool SP2 = false>
; __device__ __forceinline__ void gemm_phase(PG8_LAS unsigned char* lds, const Gemm g, const Sched& S, const Epi& E) {
;     ...
;             PG8_LDA(At, 1, 1); PG8_STAGE(PG8_SB(1, 0), b3, voffB); PG8_STAGE(PG8_SB(1, 1), b3 + hstep, voffB); PG8_STAGE(PG8_SA(1, 0), a3, voffA);
;             PG8_WAIT_V(8); PG8_WAIT_L(0); PG8_BAR; PG8_MMA(1, 0, At, B0); PG8_MMA(1, 1, At, B1); PG8_BAR; PG8_SCHED;
;             } else {
;             PG8_LDB(B0, 0, 0); PG8_SCHED; PG8_LDA(At, 0, 0); PG8_STAGE(PG8_SA(1, 1), a1 + hstep, voffA);
;             PG8_WAIT_L(8); PG8_BAR; PG8_WAIT_L(0); PG8_MMA(0, 0, At, B0); PG8_BAR; PG8_SCHED;
;             PG8_LDB(B1, 0, 1); PG8_STAGE(PG8_SB(0, 0), b2, voffB);
;             PG8_BAR; PG8_WAIT_L(0); PG8_MMA(0, 1, At, B1); PG8_BAR;
;             PG8_LDA(At, 0, 1); PG8_STAGE(PG8_SA(0, 0), a2, voffA);
;             PG8_BAR; PG8_WAIT_L(0); PG8_MMA(1, 0, At, B0); PG8_BAR; PG8_SCHED;
;             PG8_STAGE(PG8_SB(0, 1), b2 + hstep, voffB);
;             PG8_WAIT_V(6); PG8_BAR; PG8_MMA(1, 1, At, B1); PG8_BAR;
;             PG8_LDB(B0, 1, 0); PG8_SCHED; PG8_LDA(At, 1, 0); PG8_STAGE(PG8_SA(0, 1), a2 + hstep, voffA);
;             PG8_WAIT_L(8); PG8_BAR; PG8_WAIT_L(0); PG8_MMA(0, 0, At, B0); PG8_BAR; PG8_SCHED;
;             PG8_LDB(B1, 1, 1); PG8_STAGE(PG8_SB(1, 0), b3, voffB);
;             PG8_BAR; PG8_WAIT_L(0); PG8_MMA(0, 1, At, B1); PG8_BAR;
;             PG8_LDA(At, 1, 1); PG8_STAGE(PG8_SA(1, 0), a3, voffA);
;             PG8_BAR; PG8_WAIT_L(0); PG8_MMA(1, 0, At, B0); PG8_BAR; PG8_SCHED;
;             PG8_STAGE(PG8_SB(1, 1), b3 + hstep, voffB);
;             PG8_WAIT_V(6); PG8_BAR; PG8_MMA(1, 1, At, B1); PG8_BAR;
;             }
;         }
;         if constexpr (ALIGN_EPI) { if (wr == 0) PG8_BAR; }
	s_sleep 2
	s_add_i32 s58, s90, s29
	v_lshl_add_u64 v[180:181], v[180:181], 0, s[8:9]
	s_mov_b32 m0, s58
	ds_read_b128 v[188:191], v155 offset:49152
	ds_read_b128 v[192:195], v155 offset:50176
	ds_read_b128 v[196:199], v155 offset:51200
	ds_read_b128 v[200:203], v155 offset:52224
	ds_read_b128 v[204:207], v155 offset:53248
	ds_read_b128 v[208:211], v155 offset:54272
	ds_read_b128 v[212:215], v155 offset:55296
	ds_read_b128 v[216:219], v155 offset:56320
	global_load_lds_dwordx4 v[180:181], off
	s_add_i32 m0, s58, 0x2000
	s_add_u32 s48, s48, 0x80080
	v_lshl_add_u64 v[180:181], v[220:221], 0, s[8:9]
	s_addc_u32 s49, s49, 0
	s_add_i32 s58, s92, s29
	global_load_lds_dwordx4 v[180:181], off
	v_lshl_add_u64 v[180:181], s[48:49], 0, v[130:131]
	s_mov_b32 m0, s58
	s_nop 0
	global_load_lds_dwordx4 v[180:181], off
	v_lshl_add_u64 v[180:181], s[48:49], 0, v[134:135]
	s_add_i32 m0, s58, 0x2000
	s_nop 0
	global_load_lds_dwordx4 v[180:181], off
	v_lshl_add_u64 v[180:181], v[222:223], 0, s[8:9]
	s_mov_b32 m0, s64
	s_nop 0
	global_load_lds_dwordx4 v[180:181], off
	v_lshl_add_u64 v[180:181], v[224:225], 0, s[8:9]
	s_mov_b32 m0, s65
	s_nop 0
	global_load_lds_dwordx4 v[180:181], off
	s_waitcnt vmcnt(8)
	s_waitcnt lgkmcnt(0)
	s_barrier
	s_setprio 1
	s_waitcnt lgkmcnt(0)
	v_mfma_f32_16x16x32_bf16 v[60:63], v[146:149], v[188:191], v[60:63]
	v_mfma_f32_16x16x32_bf16 v[56:59], v[160:163], v[188:191], v[56:59]
	v_mfma_f32_16x16x32_bf16 v[44:47], v[146:149], v[196:199], v[44:47]
	v_mfma_f32_16x16x32_bf16 v[40:43], v[160:163], v[196:199], v[40:43]
	v_mfma_f32_16x16x32_bf16 v[28:31], v[146:149], v[204:207], v[28:31]
	v_mfma_f32_16x16x32_bf16 v[24:27], v[160:163], v[204:207], v[24:27]
	v_mfma_f32_16x16x32_bf16 v[12:15], v[146:149], v[212:215], v[12:15]
	v_mfma_f32_16x16x32_bf16 v[8:11], v[160:163], v[212:215], v[8:11]
	v_mfma_f32_16x16x32_bf16 v[60:63], v[156:159], v[192:195], v[60:63]
	v_mfma_f32_16x16x32_bf16 v[56:59], v[164:167], v[192:195], v[56:59]
	v_mfma_f32_16x16x32_bf16 v[44:47], v[156:159], v[200:203], v[44:47]
	v_mfma_f32_16x16x32_bf16 v[40:43], v[164:167], v[200:203], v[40:43]
	v_mfma_f32_16x16x32_bf16 v[28:31], v[156:159], v[208:211], v[28:31]
	v_mfma_f32_16x16x32_bf16 v[24:27], v[164:167], v[208:211], v[24:27]
	v_mfma_f32_16x16x32_bf16 v[12:15], v[156:159], v[216:219], v[12:15]
	v_mfma_f32_16x16x32_bf16 v[8:11], v[164:167], v[216:219], v[8:11]
	s_setprio 0
	s_setprio 1
	v_mfma_f32_16x16x32_bf16 v[52:55], v[168:171], v[188:191], v[52:55]
	v_mfma_f32_16x16x32_bf16 v[48:51], v[176:179], v[188:191], v[48:51]
	v_mfma_f32_16x16x32_bf16 v[36:39], v[168:171], v[196:199], v[36:39]
	v_mfma_f32_16x16x32_bf16 v[32:35], v[176:179], v[196:199], v[32:35]
	v_mfma_f32_16x16x32_bf16 v[20:23], v[168:171], v[204:207], v[20:23]
	v_mfma_f32_16x16x32_bf16 v[16:19], v[176:179], v[204:207], v[16:19]
	v_mfma_f32_16x16x32_bf16 v[4:7], v[168:171], v[212:215], v[4:7]
	v_mfma_f32_16x16x32_bf16 v[0:3], v[176:179], v[212:215], v[0:3]
	v_mfma_f32_16x16x32_bf16 v[52:55], v[172:175], v[192:195], v[52:55]
	v_mfma_f32_16x16x32_bf16 v[48:51], v[184:187], v[192:195], v[48:51]
	v_mfma_f32_16x16x32_bf16 v[36:39], v[172:175], v[200:203], v[36:39]
	v_mfma_f32_16x16x32_bf16 v[32:35], v[184:187], v[200:203], v[32:35]
	v_mfma_f32_16x16x32_bf16 v[20:23], v[172:175], v[208:211], v[20:23]
	v_mfma_f32_16x16x32_bf16 v[16:19], v[184:187], v[208:211], v[16:19]
	v_mfma_f32_16x16x32_bf16 v[4:7], v[172:175], v[216:219], v[4:7]
	v_mfma_f32_16x16x32_bf16 v[0:3], v[184:187], v[216:219], v[0:3]
	s_setprio 0
	s_barrier
	s_sleep 2
	s_add_i32 s89, s89, 2
	s_add_u32 s44, s44, 0x100
	s_addc_u32 s45, s45, 0
	s_add_u32 s86, s86, 0x100
	s_addc_u32 s87, s87, 0
	s_cmp_gt_u32 s89, 29
	s_cbranch_scc0 .LBB0_93
	s_and_b64 vcc, exec, s[10:11]
	s_cbranch_vccz .LBB0_96
	s_barrier

; #define PG8_STAGE(bufoff, gbase, voff) do { _Pragma("unroll") for (int _i = 0; _i < 2; ++_i) \
;         __builtin_amdgcn_global_load_lds((const unsigned*)((const char*)(gbase) + (voff)[_i]), (PG8_LAS unsigned*)(lds + (bufoff) + ldsw + _i * 8192), 16, 0, 0); } while (0)
; #define PG8_LDA(dst, b, h) do { _Pragma("unroll") for (int m = 0; m < 4; ++m) _Pragma("unroll") for (int k = 0; k < 2; ++k) dst[m][k] = *(const PG8_LAS bf16x8*)(lds + PG8_SA(b, h) + aoff + m * 2048 + k * 1024); } while (0)
; #define PG8_LDB(dst, b, h) do { _Pragma("unroll") for (int n = 0; n < 2; ++n) _Pragma("unroll") for (int k = 0; k < 2; ++k) dst[n][k] = *(const PG8_LAS bf16x8*)(lds + PG8_SB(b, h) + boff + n * 2048 + k * 1024); } while (0)
; template <class Epi, class Sched, bool ALIGN_EPI = false, bool SP2 = false>
; __device__ __forceinline__ void gemm_phase(PG8_LAS unsigned char* lds, const Gemm g, const Sched& S, const Epi& E) {
;     ...
;         for (int t = 0; t < nt; t += 2) {
;             const bool last = (t == nt - 2);
;             const char* a1 = cA + (size_t)(t + 1) * kstep;
;             const char* a2 = last ? nA : cA + (size_t)(t + 2) * kstep; const char* b2 = last ? nB : cB + (size_t)(t + 2) * kstep;
;             const char* a3 = a2 + kstep; const char* b3 = b2 + kstep;
;             if (last && has_next) S.a_ready(nxt);
;             if constexpr (SP2) {
;             PG8_LDB(B0, 0, 0); PG8_LDB(B1, 0, 1); PG8_SCHED; PG8_LDA(At, 0, 0); PG8_STAGE(PG8_SA(1, 1), a1 + hstep, voffA);
;             PG8_WAIT_V(8); PG8_WAIT_L(0); PG8_BAR; PG8_MMA(0, 0, At, B0); PG8_MMA(0, 1, At, B1); PG8_BAR; PG8_SCHED;
;             PG8_LDA(At, 0, 1); PG8_STAGE(PG8_SB(0, 0), b2, voffB); PG8_STAGE(PG8_SB(0, 1), b2 + hstep, voffB); PG8_STAGE(PG8_SA(0, 0), a2, voffA);
;             PG8_WAIT_V(8); PG8_WAIT_L(0); PG8_BAR; PG8_MMA(1, 0, At, B0); PG8_MMA(1, 1, At, B1); PG8_BAR; PG8_SCHED;
;             PG8_LDB(B0, 1, 0); PG8_LDB(B1, 1, 1); PG8_SCHED; PG8_LDA(At, 1, 0); PG8_STAGE(PG8_SA(0, 1), a2 + hstep, voffA);
;             PG8_WAIT_V(8); PG8_WAIT_L(0); PG8_BAR; PG8_MMA(0, 0, At, B0); PG8_MMA(0, 1, At, B1); PG8_BAR; PG8_SCHED;
;             PG8_LDA(At, 1, 1); PG8_STAGE(PG8_SB(1, 0), b3, voffB); PG8_STAGE(PG8_SB(1, 1), b3 + hstep, voffB); PG8_STAGE(PG8_SA(1, 0), a3, voffA);
;             PG8_WAIT_V(8); PG8_WAIT_L(0); PG8_BAR; PG8_MMA(1, 0, At, B0); PG8_MMA(1, 1, At, B1); PG8_BAR; PG8_SCHED;
.LBB0_121:
	ds_read_b128 v[174:177], v166
	ds_read_b128 v[178:181], v166 offset:1024
	ds_read_b128 v[190:193], v166 offset:2048
	ds_read_b128 v[194:197], v166 offset:3072
	ds_read_b128 v[198:201], v167
	ds_read_b128 v[202:205], v167 offset:1024
	ds_read_b128 v[206:209], v167 offset:2048
	ds_read_b128 v[210:213], v167 offset:3072
	s_add_u32 s46, s10, 0x100
	s_addc_u32 s47, s11, 0
	s_add_u32 s58, s90, s10
	s_addc_u32 s59, s92, s11
	s_cmpk_eq_i32 s93, 0x54
	s_cselect_b32 s60, s38, s58
	s_cselect_b32 s58, 0, s46
	s_cselect_b32 s61, s39, s59
	s_cselect_b32 s59, 0, s47
	s_add_u32 s58, s26, s58
	s_addc_u32 s59, s27, s59
	v_lshl_add_u64 v[246:247], v[142:143], 0, s[10:11]
	s_add_i32 m0, s3, 0xc000
	ds_read_b128 v[214:217], v168
	ds_read_b128 v[218:221], v168 offset:1024
	ds_read_b128 v[222:225], v168 offset:2048
	ds_read_b128 v[226:229], v168 offset:3072
	ds_read_b128 v[230:233], v168 offset:4096
	ds_read_b128 v[234:237], v168 offset:5120
	ds_read_b128 v[238:241], v168 offset:6144
	ds_read_b128 v[242:245], v168 offset:7168
	global_load_lds_dwordx4 v[246:247], off
	v_lshl_add_u64 v[246:247], v[146:147], 0, s[10:11]
	s_add_i32 m0, s3, 0xe000
	s_nop 0
	global_load_lds_dwordx4 v[246:247], off
	s_waitcnt vmcnt(8)
	s_waitcnt lgkmcnt(0)
	s_barrier
	s_setprio 1
	s_waitcnt lgkmcnt(0)
	v_mfma_f32_16x16x32_bf16 v[56:59], v[174:177], v[214:217], v[56:59]
	v_mfma_f32_16x16x32_bf16 v[60:63], v[190:193], v[214:217], v[60:63]
	v_mfma_f32_16x16x32_bf16 v[76:79], v[174:177], v[222:225], v[76:79]
	v_mfma_f32_16x16x32_bf16 v[80:83], v[190:193], v[222:225], v[80:83]
	v_mfma_f32_16x16x32_bf16 v[96:99], v[174:177], v[230:233], v[96:99]
	v_mfma_f32_16x16x32_bf16 v[100:103], v[190:193], v[230:233], v[100:103]
	v_mfma_f32_16x16x32_bf16 v[116:119], v[174:177], v[238:241], v[116:119]
	v_mfma_f32_16x16x32_bf16 v[120:123], v[190:193], v[238:241], v[120:123]
	v_mfma_f32_16x16x32_bf16 v[56:59], v[178:181], v[218:221], v[56:59]
	v_mfma_f32_16x16x32_bf16 v[60:63], v[194:197], v[218:221], v[60:63]
	v_mfma_f32_16x16x32_bf16 v[76:79], v[178:181], v[226:229], v[76:79]
	v_mfma_f32_16x16x32_bf16 v[80:83], v[194:197], v[226:229], v[80:83]
	v_mfma_f32_16x16x32_bf16 v[96:99], v[178:181], v[234:237], v[96:99]
	v_mfma_f32_16x16x32_bf16 v[100:103], v[194:197], v[234:237], v[100:103]
	v_mfma_f32_16x16x32_bf16 v[116:119], v[178:181], v[242:245], v[116:119]
	v_mfma_f32_16x16x32_bf16 v[120:123], v[194:197], v[242:245], v[120:123]
	s_setprio 0
	s_setprio 1
	v_mfma_f32_16x16x32_bf16 v[64:67], v[198:201], v[214:217], v[64:67]
	v_mfma_f32_16x16x32_bf16 v[68:71], v[206:209], v[214:217], v[68:71]
	v_mfma_f32_16x16x32_bf16 v[84:87], v[198:201], v[222:225], v[84:87]
	v_mfma_f32_16x16x32_bf16 v[92:95], v[206:209], v[222:225], v[92:95]
	v_mfma_f32_16x16x32_bf16 v[104:107], v[198:201], v[230:233], v[104:107]
	v_mfma_f32_16x16x32_bf16 v[108:111], v[206:209], v[230:233], v[108:111]
	v_mfma_f32_16x16x32_bf16 v[124:127], v[198:201], v[238:241], v[124:127]
	v_mfma_f32_16x16x32_bf16 v[112:115], v[206:209], v[238:241], v[112:115]
	v_mfma_f32_16x16x32_bf16 v[64:67], v[202:205], v[218:221], v[64:67]
	v_mfma_f32_16x16x32_bf16 v[68:71], v[210:213], v[218:221], v[68:71]
	v_mfma_f32_16x16x32_bf16 v[84:87], v[202:205], v[226:229], v[84:87]
	v_mfma_f32_16x16x32_bf16 v[92:95], v[210:213], v[226:229], v[92:95]
	v_mfma_f32_16x16x32_bf16 v[104:107], v[202:205], v[234:237], v[104:107]
	v_mfma_f32_16x16x32_bf16 v[108:111], v[210:213], v[234:237], v[108:111]
	v_mfma_f32_16x16x32_bf16 v[124:127], v[202:205], v[242:245], v[124:127]
	v_mfma_f32_16x16x32_bf16 v[112:115], v[210:213], v[242:245], v[112:115]
	s_setprio 0
	s_barrier
	s_sleep 2
	s_add_i32 s10, s79, s34
	v_lshl_add_u64 v[246:247], s[58:59], 0, v[128:129]
	s_mov_b32 m0, s10
	ds_read_b128 v[214:217], v168 offset:16384
	ds_read_b128 v[218:221], v168 offset:17408
	ds_read_b128 v[222:225], v168 offset:18432
	ds_read_b128 v[226:229], v168 offset:19456
	ds_read_b128 v[230:233], v168 offset:20480
	ds_read_b128 v[234:237], v168 offset:21504
	ds_read_b128 v[238:241], v168 offset:22528
	ds_read_b128 v[242:245], v168 offset:23552
	global_load_lds_dwordx4 v[246:247], off
	s_add_i32 m0, s10, 0x2000
	s_add_u32 s10, s58, 0x160000
	v_lshl_add_u64 v[248:249], s[58:59], 0, v[130:131]
	s_addc_u32 s11, s59, 0
	s_add_i32 s94, s84, s34
	global_load_lds_dwordx4 v[248:249], off
	v_lshl_add_u64 v[250:251], s[10:11], 0, v[128:129]
	s_mov_b32 m0, s94
	v_lshl_add_u64 v[252:253], s[60:61], 0, v[130:131]
	global_load_lds_dwordx4 v[250:251], off
	v_lshl_add_u64 v[250:251], s[10:11], 0, v[130:131]
	s_add_i32 m0, s94, 0x2000
	s_nop 0
	global_load_lds_dwordx4 v[250:251], off
	v_lshl_add_u64 v[250:251], s[60:61], 0, v[128:129]
	s_mov_b32 m0, s3
	s_nop 0
	global_load_lds_dwordx4 v[250:251], off
	s_mov_b32 m0, s28
	s_nop 0
	global_load_lds_dwordx4 v[252:253], off
	s_waitcnt vmcnt(8)
	s_waitcnt lgkmcnt(0)
	s_barrier
; #define PG8_STAGE(bufoff, gbase, voff) do { _Pragma("unroll") for (int _i = 0; _i < 2; ++_i) \
;         __builtin_amdgcn_global_load_lds((const unsigned*)((const char*)(gbase) + (voff)[_i]), (PG8_LAS unsigned*)(lds + (bufoff) + ldsw + _i * 8192), 16, 0, 0); } while (0)
; #define PG8_LDA(dst, b, h) do { _Pragma("unroll") for (int m = 0; m < 4; ++m) _Pragma("unroll") for (int k = 0; k < 2; ++k) dst[m][k] = *(const PG8_LAS bf16x8*)(lds + PG8_SA(b, h) + aoff + m * 2048 + k * 1024); } while (0)
; #define PG8_LDB(dst, b, h) do { _Pragma("unroll") for (int n = 0; n < 2; ++n) _Pragma("unroll") for (int k = 0; k < 2; ++k) dst[n][k] = *(const PG8_LAS bf16x8*)(lds + PG8_SB(b, h) + boff + n * 2048 + k * 1024); } while (0)
; #define PG8_MMA(ai, bj, At, Bt) do { __builtin_amdgcn_s_setprio(1); _Pragma("unroll") for (int m = 0; m < 4; ++m) _Pragma("unroll") for (int n = 0; n < 2; ++n) _Pragma("unroll") for (int k = 0; k < 2; ++k) \
;         acc[ai][bj][m][n] = __builtin_amdgcn_mfma_f32_16x16x32_bf16(Bt[n][k], At[m][k], acc[ai][bj][m][n], 0, 0, 0); __builtin_amdgcn_s_setprio(0); } while (0)
; #define PG8_WAIT_V(n) asm volatile("s_waitcnt vmcnt(" #n ")" ::: "memory")
; template <class Epi, class Sched, bool ALIGN_EPI = false, bool SP2 = false>
; __device__ __forceinline__ void gemm_phase(PG8_LAS unsigned char* lds, const Gemm g, const Sched& S, const Epi& E) {
;     ...
;             PG8_LDB(B0, 0, 0); PG8_LDB(B1, 0, 1); PG8_SCHED; PG8_LDA(At, 0, 0); PG8_STAGE(PG8_SA(1, 1), a1 + hstep, voffA);
;             PG8_WAIT_V(8); PG8_WAIT_L(0); PG8_BAR; PG8_MMA(0, 0, At, B0); PG8_MMA(0, 1, At, B1); PG8_BAR; PG8_SCHED;
;             PG8_LDA(At, 0, 1); PG8_STAGE(PG8_SB(0, 0), b2, voffB); PG8_STAGE(PG8_SB(0, 1), b2 + hstep, voffB); PG8_STAGE(PG8_SA(0, 0), a2, voffA);
;             PG8_WAIT_V(8); PG8_WAIT_L(0); PG8_BAR; PG8_MMA(1, 0, At, B0); PG8_MMA(1, 1, At, B1); PG8_BAR; PG8_SCHED;
;             PG8_LDB(B0, 1, 0); PG8_LDB(B1, 1, 1); PG8_SCHED; PG8_LDA(At, 1, 0); PG8_STAGE(PG8_SA(0, 1), a2 + hstep, voffA);
;             PG8_WAIT_V(8); PG8_WAIT_L(0); PG8_BAR; PG8_MMA(0, 0, At, B0); PG8_MMA(0, 1, At, B1); PG8_BAR; PG8_SCHED;
;             PG8_LDA(At, 1, 1); PG8_STAGE(PG8_SB(1, 0), b3, voffB); PG8_STAGE(PG8_SB(1, 1), b3 + hstep, voffB); PG8_STAGE(PG8_SA(1, 0), a3, voffA);
;             PG8_WAIT_V(8); PG8_WAIT_L(0); PG8_BAR; PG8_MMA(1, 0, At, B0); PG8_MMA(1, 1, At, B1); PG8_BAR; PG8_SCHED;
	s_setprio 1
	s_waitcnt lgkmcnt(0)
	v_mfma_f32_16x16x32_bf16 v[88:91], v[174:177], v[214:217], v[88:91]
	v_mfma_f32_16x16x32_bf16 v[72:75], v[190:193], v[214:217], v[72:75]
	v_mfma_f32_16x16x32_bf16 v[44:47], v[174:177], v[222:225], v[44:47]
	v_mfma_f32_16x16x32_bf16 v[40:43], v[190:193], v[222:225], v[40:43]
	v_mfma_f32_16x16x32_bf16 v[28:31], v[174:177], v[230:233], v[28:31]
	v_mfma_f32_16x16x32_bf16 v[24:27], v[190:193], v[230:233], v[24:27]
	v_mfma_f32_16x16x32_bf16 v[12:15], v[174:177], v[238:241], v[12:15]
	v_mfma_f32_16x16x32_bf16 v[8:11], v[190:193], v[238:241], v[8:11]
	v_mfma_f32_16x16x32_bf16 v[88:91], v[178:181], v[218:221], v[88:91]
	v_mfma_f32_16x16x32_bf16 v[72:75], v[194:197], v[218:221], v[72:75]
	v_mfma_f32_16x16x32_bf16 v[44:47], v[178:181], v[226:229], v[44:47]
	v_mfma_f32_16x16x32_bf16 v[40:43], v[194:197], v[226:229], v[40:43]
	v_mfma_f32_16x16x32_bf16 v[28:31], v[178:181], v[234:237], v[28:31]
	v_mfma_f32_16x16x32_bf16 v[24:27], v[194:197], v[234:237], v[24:27]
	v_mfma_f32_16x16x32_bf16 v[12:15], v[178:181], v[242:245], v[12:15]
	v_mfma_f32_16x16x32_bf16 v[8:11], v[194:197], v[242:245], v[8:11]
	s_setprio 0
	s_setprio 1
	v_mfma_f32_16x16x32_bf16 v[52:55], v[198:201], v[214:217], v[52:55]
	v_mfma_f32_16x16x32_bf16 v[48:51], v[206:209], v[214:217], v[48:51]
	v_mfma_f32_16x16x32_bf16 v[36:39], v[198:201], v[222:225], v[36:39]
	v_mfma_f32_16x16x32_bf16 v[32:35], v[206:209], v[222:225], v[32:35]
	v_mfma_f32_16x16x32_bf16 v[20:23], v[198:201], v[230:233], v[20:23]
	v_mfma_f32_16x16x32_bf16 v[16:19], v[206:209], v[230:233], v[16:19]
	v_mfma_f32_16x16x32_bf16 v[4:7], v[198:201], v[238:241], v[4:7]
	v_mfma_f32_16x16x32_bf16 v[0:3], v[206:209], v[238:241], v[0:3]
	v_mfma_f32_16x16x32_bf16 v[52:55], v[202:205], v[218:221], v[52:55]
	v_mfma_f32_16x16x32_bf16 v[48:51], v[210:213], v[218:221], v[48:51]
	v_mfma_f32_16x16x32_bf16 v[36:39], v[202:205], v[226:229], v[36:39]
	v_mfma_f32_16x16x32_bf16 v[32:35], v[210:213], v[226:229], v[32:35]
	v_mfma_f32_16x16x32_bf16 v[20:23], v[202:205], v[234:237], v[20:23]
	v_mfma_f32_16x16x32_bf16 v[16:19], v[210:213], v[234:237], v[16:19]
	v_mfma_f32_16x16x32_bf16 v[4:7], v[202:205], v[242:245], v[4:7]
	v_mfma_f32_16x16x32_bf16 v[0:3], v[210:213], v[242:245], v[0:3]
	s_setprio 0
	s_barrier
	s_sleep 2
	s_add_i32 s94, 0, 0x18000
	v_add_u32_e32 v173, s94, v148
	s_add_i32 s95, 0, 0x1c000
	ds_read_b128 v[174:177], v173
	ds_read_b128 v[178:181], v173 offset:1024
	ds_read_b128 v[190:193], v173 offset:2048
	ds_read_b128 v[194:197], v173 offset:3072
	v_add_u32_e32 v173, s95, v148
	ds_read_b128 v[198:201], v173
	ds_read_b128 v[202:205], v173 offset:1024
	ds_read_b128 v[206:209], v173 offset:2048
	ds_read_b128 v[210:213], v173 offset:3072
	s_add_u32 s10, s60, 0x160000
	s_addc_u32 s11, s61, 0
	s_mov_b32 m0, s35
	v_lshl_add_u64 v[188:189], s[10:11], 0, v[128:129]
	ds_read_b128 v[214:217], v168 offset:32768
	ds_read_b128 v[218:221], v168 offset:33792
	ds_read_b128 v[222:225], v168 offset:34816
	ds_read_b128 v[226:229], v168 offset:35840
	ds_read_b128 v[230:233], v168 offset:36864
	ds_read_b128 v[234:237], v168 offset:37888
	ds_read_b128 v[238:241], v168 offset:38912
	ds_read_b128 v[242:245], v168 offset:39936
	global_load_lds_dwordx4 v[188:189], off
	v_lshl_add_u64 v[188:189], s[10:11], 0, v[130:131]
	s_mov_b32 m0, s62
	s_nop 0
	global_load_lds_dwordx4 v[188:189], off
	s_waitcnt vmcnt(8)
	s_waitcnt lgkmcnt(0)
	s_barrier
	s_setprio 1
	s_waitcnt lgkmcnt(0)
	v_mfma_f32_16x16x32_bf16 v[56:59], v[174:177], v[214:217], v[56:59]
	v_mfma_f32_16x16x32_bf16 v[60:63], v[190:193], v[214:217], v[60:63]
	v_mfma_f32_16x16x32_bf16 v[76:79], v[174:177], v[222:225], v[76:79]
	v_mfma_f32_16x16x32_bf16 v[80:83], v[190:193], v[222:225], v[80:83]
	v_mfma_f32_16x16x32_bf16 v[96:99], v[174:177], v[230:233], v[96:99]
	v_mfma_f32_16x16x32_bf16 v[100:103], v[190:193], v[230:233], v[100:103]
	v_mfma_f32_16x16x32_bf16 v[116:119], v[174:177], v[238:241], v[116:119]
	v_mfma_f32_16x16x32_bf16 v[120:123], v[190:193], v[238:241], v[120:123]
	v_mfma_f32_16x16x32_bf16 v[56:59], v[178:181], v[218:221], v[56:59]
	v_mfma_f32_16x16x32_bf16 v[60:63], v[194:197], v[218:221], v[60:63]
	v_mfma_f32_16x16x32_bf16 v[76:79], v[178:181], v[226:229], v[76:79]
	v_mfma_f32_16x16x32_bf16 v[80:83], v[194:197], v[226:229], v[80:83]
	v_mfma_f32_16x16x32_bf16 v[96:99], v[178:181], v[234:237], v[96:99]
	v_mfma_f32_16x16x32_bf16 v[100:103], v[194:197], v[234:237], v[100:103]
	v_mfma_f32_16x16x32_bf16 v[116:119], v[178:181], v[242:245], v[116:119]
	v_mfma_f32_16x16x32_bf16 v[120:123], v[194:197], v[242:245], v[120:123]
	s_setprio 0
	s_setprio 1
	v_mfma_f32_16x16x32_bf16 v[64:67], v[198:201], v[214:217], v[64:67]
	v_mfma_f32_16x16x32_bf16 v[68:71], v[206:209], v[214:217], v[68:71]
	v_mfma_f32_16x16x32_bf16 v[84:87], v[198:201], v[222:225], v[84:87]
	v_mfma_f32_16x16x32_bf16 v[92:95], v[206:209], v[222:225], v[92:95]
	v_mfma_f32_16x16x32_bf16 v[104:107], v[198:201], v[230:233], v[104:107]
	v_mfma_f32_16x16x32_bf16 v[108:111], v[206:209], v[230:233], v[108:111]
	v_mfma_f32_16x16x32_bf16 v[124:127], v[198:201], v[238:241], v[124:127]
	v_mfma_f32_16x16x32_bf16 v[112:115], v[206:209], v[238:241], v[112:115]
	v_mfma_f32_16x16x32_bf16 v[64:67], v[202:205], v[218:221], v[64:67]
	v_mfma_f32_16x16x32_bf16 v[68:71], v[210:213], v[218:221], v[68:71]
	v_mfma_f32_16x16x32_bf16 v[84:87], v[202:205], v[226:229], v[84:87]
	v_mfma_f32_16x16x32_bf16 v[92:95], v[210:213], v[226:229], v[92:95]
	v_mfma_f32_16x16x32_bf16 v[104:107], v[202:205], v[234:237], v[104:107]
	v_mfma_f32_16x16x32_bf16 v[108:111], v[210:213], v[234:237], v[108:111]
	v_mfma_f32_16x16x32_bf16 v[124:127], v[202:205], v[242:245], v[124:127]
	v_mfma_f32_16x16x32_bf16 v[112:115], v[210:213], v[242:245], v[112:115]
	s_setprio 0
	s_barrier
; #define PG8_STAGE(bufoff, gbase, voff) do { _Pragma("unroll") for (int _i = 0; _i < 2; ++_i) \
;         __builtin_amdgcn_global_load_lds((const unsigned*)((const char*)(gbase) + (voff)[_i]), (PG8_LAS unsigned*)(lds + (bufoff) + ldsw + _i * 8192), 16, 0, 0); } while (0)
; #define PG8_LDA(dst, b, h) do { _Pragma("unroll") for (int m = 0; m < 4; ++m) _Pragma("unroll") for (int k = 0; k < 2; ++k) dst[m][k] = *(const PG8_LAS bf16x8*)(lds + PG8_SA(b, h) + aoff + m * 2048 + k * 1024); } while (0)
; #define PG8_WAIT_V(n) asm volatile("s_waitcnt vmcnt(" #n ")" ::: "memory")
; template <class Epi, class Sched, bool ALIGN_EPI = false, bool SP2 = false>
; __device__ __forceinline__ void gemm_phase(PG8_LAS unsigned char* lds, const Gemm g, const Sched& S, const Epi& E) {
;     ...
;             PG8_LDA(At, 1, 1); PG8_STAGE(PG8_SB(1, 0), b3, voffB); PG8_STAGE(PG8_SB(1, 1), b3 + hstep, voffB); PG8_STAGE(PG8_SA(1, 0), a3, voffA);
;             PG8_WAIT_V(8); PG8_WAIT_L(0); PG8_BAR; PG8_MMA(1, 0, At, B0); PG8_MMA(1, 1, At, B1); PG8_BAR; PG8_SCHED;
;             } else {
;             PG8_LDB(B0, 0, 0); PG8_SCHED; PG8_LDA(At, 0, 0); PG8_STAGE(PG8_SA(1, 1), a1 + hstep, voffA);
;             PG8_WAIT_L(8); PG8_BAR; PG8_WAIT_L(0); PG8_MMA(0, 0, At, B0); PG8_BAR; PG8_SCHED;
;             PG8_LDB(B1, 0, 1); PG8_STAGE(PG8_SB(0, 0), b2, voffB);
;             PG8_BAR; PG8_WAIT_L(0); PG8_MMA(0, 1, At, B1); PG8_BAR;
;             PG8_LDA(At, 0, 1); PG8_STAGE(PG8_SA(0, 0), a2, voffA);
;             PG8_BAR; PG8_WAIT_L(0); PG8_MMA(1, 0, At, B0); PG8_BAR; PG8_SCHED;
;             PG8_STAGE(PG8_SB(0, 1), b2 + hstep, voffB);
;             PG8_WAIT_V(6); PG8_BAR; PG8_MMA(1, 1, At, B1); PG8_BAR;
;             PG8_LDB(B0, 1, 0); PG8_SCHED; PG8_LDA(At, 1, 0); PG8_STAGE(PG8_SA(0, 1), a2 + hstep, voffA);
;             PG8_WAIT_L(8); PG8_BAR; PG8_WAIT_L(0); PG8_MMA(0, 0, At, B0); PG8_BAR; PG8_SCHED;
;             PG8_LDB(B1, 1, 1); PG8_STAGE(PG8_SB(1, 0), b3, voffB);
;             PG8_BAR; PG8_WAIT_L(0); PG8_MMA(0, 1, At, B1); PG8_BAR;
;             PG8_LDA(At, 1, 1); PG8_STAGE(PG8_SA(1, 0), a3, voffA);
;             PG8_BAR; PG8_WAIT_L(0); PG8_MMA(1, 0, At, B0); PG8_BAR; PG8_SCHED;
;             PG8_STAGE(PG8_SB(1, 1), b3 + hstep, voffB);
;             PG8_WAIT_V(6); PG8_BAR; PG8_MMA(1, 1, At, B1); PG8_BAR;
;             }
;         }
;         if constexpr (ALIGN_EPI) { if (wr == 0) PG8_BAR; }
	s_sleep 2
	s_add_i32 s10, s94, s34
	v_lshl_add_u64 v[188:189], v[246:247], 0, s[44:45]
	s_mov_b32 m0, s10
	ds_read_b128 v[214:217], v168 offset:49152
	ds_read_b128 v[218:221], v168 offset:50176
	ds_read_b128 v[222:225], v168 offset:51200
	ds_read_b128 v[226:229], v168 offset:52224
	ds_read_b128 v[230:233], v168 offset:53248
	ds_read_b128 v[234:237], v168 offset:54272
	ds_read_b128 v[238:241], v168 offset:55296
	ds_read_b128 v[242:245], v168 offset:56320
	global_load_lds_dwordx4 v[188:189], off
	s_add_i32 m0, s10, 0x2000
	s_add_u32 s10, s58, 0x160080
	v_lshl_add_u64 v[188:189], v[248:249], 0, s[44:45]
	s_addc_u32 s11, s59, 0
	s_add_i32 s58, s95, s34
	global_load_lds_dwordx4 v[188:189], off
	v_lshl_add_u64 v[188:189], s[10:11], 0, v[128:129]
	s_mov_b32 m0, s58
	s_nop 0
	global_load_lds_dwordx4 v[188:189], off
	v_lshl_add_u64 v[188:189], s[10:11], 0, v[130:131]
	s_add_i32 m0, s58, 0x2000
	s_nop 0
	global_load_lds_dwordx4 v[188:189], off
	v_lshl_add_u64 v[188:189], v[250:251], 0, s[44:45]
	s_mov_b32 m0, s65
	s_nop 0
	global_load_lds_dwordx4 v[188:189], off
	v_lshl_add_u64 v[188:189], v[252:253], 0, s[44:45]
	s_mov_b32 m0, s66
	s_nop 0
	global_load_lds_dwordx4 v[188:189], off
	s_waitcnt vmcnt(8)
	s_waitcnt lgkmcnt(0)
	s_barrier
	s_setprio 1
	s_waitcnt lgkmcnt(0)
	v_mfma_f32_16x16x32_bf16 v[88:91], v[174:177], v[214:217], v[88:91]
	v_mfma_f32_16x16x32_bf16 v[72:75], v[190:193], v[214:217], v[72:75]
	v_mfma_f32_16x16x32_bf16 v[44:47], v[174:177], v[222:225], v[44:47]
	v_mfma_f32_16x16x32_bf16 v[40:43], v[190:193], v[222:225], v[40:43]
	v_mfma_f32_16x16x32_bf16 v[28:31], v[174:177], v[230:233], v[28:31]
	v_mfma_f32_16x16x32_bf16 v[24:27], v[190:193], v[230:233], v[24:27]
	v_mfma_f32_16x16x32_bf16 v[12:15], v[174:177], v[238:241], v[12:15]
	v_mfma_f32_16x16x32_bf16 v[8:11], v[190:193], v[238:241], v[8:11]
	v_mfma_f32_16x16x32_bf16 v[88:91], v[178:181], v[218:221], v[88:91]
	v_mfma_f32_16x16x32_bf16 v[72:75], v[194:197], v[218:221], v[72:75]
	v_mfma_f32_16x16x32_bf16 v[44:47], v[178:181], v[226:229], v[44:47]
	v_mfma_f32_16x16x32_bf16 v[40:43], v[194:197], v[226:229], v[40:43]
	v_mfma_f32_16x16x32_bf16 v[28:31], v[178:181], v[234:237], v[28:31]
	v_mfma_f32_16x16x32_bf16 v[24:27], v[194:197], v[234:237], v[24:27]
	v_mfma_f32_16x16x32_bf16 v[12:15], v[178:181], v[242:245], v[12:15]
	v_mfma_f32_16x16x32_bf16 v[8:11], v[194:197], v[242:245], v[8:11]
	s_setprio 0
	s_setprio 1
	v_mfma_f32_16x16x32_bf16 v[52:55], v[198:201], v[214:217], v[52:55]
	v_mfma_f32_16x16x32_bf16 v[48:51], v[206:209], v[214:217], v[48:51]
	v_mfma_f32_16x16x32_bf16 v[36:39], v[198:201], v[222:225], v[36:39]
	v_mfma_f32_16x16x32_bf16 v[32:35], v[206:209], v[222:225], v[32:35]
	v_mfma_f32_16x16x32_bf16 v[20:23], v[198:201], v[230:233], v[20:23]
	v_mfma_f32_16x16x32_bf16 v[16:19], v[206:209], v[230:233], v[16:19]
	v_mfma_f32_16x16x32_bf16 v[4:7], v[198:201], v[238:241], v[4:7]
	v_mfma_f32_16x16x32_bf16 v[0:3], v[206:209], v[238:241], v[0:3]
	v_mfma_f32_16x16x32_bf16 v[52:55], v[202:205], v[218:221], v[52:55]
	v_mfma_f32_16x16x32_bf16 v[48:51], v[210:213], v[218:221], v[48:51]
	v_mfma_f32_16x16x32_bf16 v[36:39], v[202:205], v[226:229], v[36:39]
	v_mfma_f32_16x16x32_bf16 v[32:35], v[210:213], v[226:229], v[32:35]
	v_mfma_f32_16x16x32_bf16 v[20:23], v[202:205], v[234:237], v[20:23]
	v_mfma_f32_16x16x32_bf16 v[16:19], v[210:213], v[234:237], v[16:19]
	v_mfma_f32_16x16x32_bf16 v[4:7], v[202:205], v[242:245], v[4:7]
	v_mfma_f32_16x16x32_bf16 v[0:3], v[210:213], v[242:245], v[0:3]
	s_setprio 0
	s_barrier
	s_sleep 2
	s_add_i32 s93, s93, 2
	s_cmpk_gt_u32 s93, 0x55
	s_mov_b64 s[10:11], s[46:47]
	s_cbranch_scc0 .LBB0_121
	s_and_b64 vcc, exec, s[48:49]
	s_cbranch_vccz .LBB0_124
	s_barrier

;     __device__ __forceinline__ bool next(int i, Unit& u) const { if (i >= 5) return false; const int x = c & 7, k = c >> 3; u.pm = 32 * i + 4 * x + (k >> 3); u.pn = k & 7; return true; }
; #define PG8_STAGE(bufoff, gbase, voff) do { _Pragma("unroll") for (int _i = 0; _i < 2; ++_i) \
;         __builtin_amdgcn_global_load_lds((const unsigned*)((const char*)(gbase) + (voff)[_i]), (PG8_LAS unsigned*)(lds + (bufoff) + ldsw + _i * 8192), 16, 0, 0); } while (0)
; #define PG8_LDA(dst, b, h) do { _Pragma("unroll") for (int m = 0; m < 4; ++m) _Pragma("unroll") for (int k = 0; k < 2; ++k) dst[m][k] = *(const PG8_LAS bf16x8*)(lds + PG8_SA(b, h) + aoff + m * 2048 + k * 1024); } while (0)
; #define PG8_LDB(dst, b, h) do { _Pragma("unroll") for (int n = 0; n < 2; ++n) _Pragma("unroll") for (int k = 0; k < 2; ++k) dst[n][k] = *(const PG8_LAS bf16x8*)(lds + PG8_SB(b, h) + boff + n * 2048 + k * 1024); } while (0)
; #define PG8_WAIT_V(n) asm volatile("s_waitcnt vmcnt(" #n ")" ::: "memory")
; template <class Epi, class Sched, bool ALIGN_EPI = false, bool SP2 = false>
; __device__ __forceinline__ void gemm_phase(PG8_LAS unsigned char* lds, const Gemm g, const Sched& S, const Epi& E) {
;     ...
;         const bool has_next = S.next(ui + 1, nxt);
;         const char* nA = has_next ? (const char*)g.A + (size_t)nxt.pm * tstep : cA; const char* nB = has_next ? (const char*)g.Bt + (size_t)nxt.pn * tstep : cB;
;         for (int t = 0; t < nt; t += 2) {
;             const bool last = (t == nt - 2);
;             const char* a1 = cA + (size_t)(t + 1) * kstep;
;             const char* a2 = last ? nA : cA + (size_t)(t + 2) * kstep; const char* b2 = last ? nB : cB + (size_t)(t + 2) * kstep;
;             const char* a3 = a2 + kstep; const char* b3 = b2 + kstep;
;             if (last && has_next) S.a_ready(nxt);
;             if constexpr (SP2) {
;             PG8_LDB(B0, 0, 0); PG8_LDB(B1, 0, 1); PG8_SCHED; PG8_LDA(At, 0, 0); PG8_STAGE(PG8_SA(1, 1), a1 + hstep, voffA);
;             PG8_WAIT_V(8); PG8_WAIT_L(0); PG8_BAR; PG8_MMA(0, 0, At, B0); PG8_MMA(0, 1, At, B1); PG8_BAR; PG8_SCHED;
;             PG8_LDA(At, 0, 1); PG8_STAGE(PG8_SB(0, 0), b2, voffB); PG8_STAGE(PG8_SB(0, 1), b2 + hstep, voffB); PG8_STAGE(PG8_SA(0, 0), a2, voffA);
;             PG8_WAIT_V(8); PG8_WAIT_L(0); PG8_BAR; PG8_MMA(1, 0, At, B0); PG8_MMA(1, 1, At, B1); PG8_BAR; PG8_SCHED;
.LBB0_181:
	ds_read_b128 v[0:3], v147
	ds_read_b128 v[4:7], v147 offset:1024
	ds_read_b128 v[8:11], v147 offset:2048
	ds_read_b128 v[12:15], v147 offset:3072
	ds_read_b128 v[16:19], v148
	ds_read_b128 v[20:23], v148 offset:1024
	ds_read_b128 v[24:27], v148 offset:2048
	ds_read_b128 v[28:31], v148 offset:3072
	s_ashr_i32 s41, s40, 31
	s_lshl_b64 s[42:43], s[40:41], 17
	s_add_u32 s42, s28, s42
	s_addc_u32 s43, s29, s43
	s_and_b64 s[44:45], s[0:1], exec
	s_cselect_b32 s63, s43, s49
	s_cselect_b32 s62, s42, s48
	s_ashr_i32 s39, s38, 31
	s_lshl_b64 s[44:45], s[38:39], 17
	s_add_u32 s44, s82, s44
	s_addc_u32 s45, s83, s45
	s_and_b64 s[58:59], s[0:1], exec
	s_cselect_b32 s59, s45, s61
	s_cselect_b32 s58, s44, s60
	s_add_u32 s86, s48, 0x10080
	s_addc_u32 s87, s49, 0
	s_add_i32 s92, s35, 0xc000
	v_lshl_add_u64 v[64:65], s[86:87], 0, v[130:131]
	s_mov_b32 m0, s92
	s_add_i32 s39, s35, 0xe000
	ds_read_b128 v[32:35], v149
	ds_read_b128 v[36:39], v149 offset:1024
	ds_read_b128 v[40:43], v149 offset:2048
	ds_read_b128 v[44:47], v149 offset:3072
	ds_read_b128 v[48:51], v149 offset:4096
	ds_read_b128 v[52:55], v149 offset:5120
	ds_read_b128 v[56:59], v149 offset:6144
	ds_read_b128 v[60:63], v149 offset:7168
	global_load_lds_dwordx4 v[64:65], off
	v_lshl_add_u64 v[64:65], s[86:87], 0, v[128:129]
	s_mov_b32 m0, s39
	s_nop 0
	global_load_lds_dwordx4 v[64:65], off
	s_waitcnt vmcnt(8)
	s_waitcnt lgkmcnt(0)
	s_barrier
	s_setprio 1
	s_waitcnt lgkmcnt(0)
	v_mfma_f32_16x16x32_bf16 v[64:67], v[0:3], v[32:35], 0
	v_mfma_f32_16x16x32_bf16 v[68:71], v[8:11], v[32:35], 0
	v_mfma_f32_16x16x32_bf16 v[72:75], v[0:3], v[40:43], 0
	v_mfma_f32_16x16x32_bf16 v[76:79], v[8:11], v[40:43], 0
	v_mfma_f32_16x16x32_bf16 v[80:83], v[0:3], v[48:51], 0
	v_mfma_f32_16x16x32_bf16 v[84:87], v[8:11], v[48:51], 0
	v_mfma_f32_16x16x32_bf16 v[88:91], v[0:3], v[56:59], 0
	v_mfma_f32_16x16x32_bf16 v[92:95], v[8:11], v[56:59], 0
	v_mfma_f32_16x16x32_bf16 v[64:67], v[4:7], v[36:39], v[64:67]
	v_mfma_f32_16x16x32_bf16 v[68:71], v[12:15], v[36:39], v[68:71]
	v_mfma_f32_16x16x32_bf16 v[72:75], v[4:7], v[44:47], v[72:75]
	v_mfma_f32_16x16x32_bf16 v[76:79], v[12:15], v[44:47], v[76:79]
	v_mfma_f32_16x16x32_bf16 v[80:83], v[4:7], v[52:55], v[80:83]
	v_mfma_f32_16x16x32_bf16 v[84:87], v[12:15], v[52:55], v[84:87]
	v_mfma_f32_16x16x32_bf16 v[88:91], v[4:7], v[60:63], v[88:91]
	v_mfma_f32_16x16x32_bf16 v[92:95], v[12:15], v[60:63], v[92:95]
	s_setprio 0
	s_setprio 1
	v_mfma_f32_16x16x32_bf16 v[96:99], v[16:19], v[32:35], 0
	v_mfma_f32_16x16x32_bf16 v[32:35], v[24:27], v[32:35], 0
	v_mfma_f32_16x16x32_bf16 v[96:99], v[20:23], v[36:39], v[96:99]
	v_mfma_f32_16x16x32_bf16 v[32:35], v[28:31], v[36:39], v[32:35]
	v_mfma_f32_16x16x32_bf16 v[36:39], v[16:19], v[40:43], 0
	v_mfma_f32_16x16x32_bf16 v[40:43], v[24:27], v[40:43], 0
	v_mfma_f32_16x16x32_bf16 v[36:39], v[20:23], v[44:47], v[36:39]
	v_mfma_f32_16x16x32_bf16 v[40:43], v[28:31], v[44:47], v[40:43]
	v_mfma_f32_16x16x32_bf16 v[44:47], v[16:19], v[48:51], 0
	v_mfma_f32_16x16x32_bf16 v[48:51], v[24:27], v[48:51], 0
	v_mfma_f32_16x16x32_bf16 v[44:47], v[20:23], v[52:55], v[44:47]
	v_mfma_f32_16x16x32_bf16 v[48:51], v[28:31], v[52:55], v[48:51]
	v_mfma_f32_16x16x32_bf16 v[52:55], v[16:19], v[56:59], 0
	v_mfma_f32_16x16x32_bf16 v[56:59], v[24:27], v[56:59], 0
	v_mfma_f32_16x16x32_bf16 v[52:55], v[20:23], v[60:63], v[52:55]
	v_mfma_f32_16x16x32_bf16 v[56:59], v[28:31], v[60:63], v[56:59]
	s_setprio 0
	s_barrier
	s_sleep 2
	s_add_i32 s89, s79, s3
	v_lshl_add_u64 v[140:141], s[60:61], 0, v[130:131]
	s_add_i32 s41, s89, 0x2000
	v_lshl_add_u64 v[136:137], v[140:141], 0, s[12:13]
	s_mov_b32 m0, s89
	v_lshl_add_u64 v[180:181], s[60:61], 0, v[128:129]
	s_add_u32 s96, s60, 0x10100
	ds_read_b128 v[60:63], v149 offset:16384
	ds_read_b128 v[100:103], v149 offset:17408
	ds_read_b128 v[104:107], v149 offset:18432
	ds_read_b128 v[108:111], v149 offset:19456
	ds_read_b128 v[112:115], v149 offset:20480
	ds_read_b128 v[116:119], v149 offset:21504
	ds_read_b128 v[120:123], v149 offset:22528
	ds_read_b128 v[124:127], v149 offset:23552
	global_load_lds_dwordx4 v[136:137], off
	v_lshl_add_u64 v[136:137], v[180:181], 0, s[12:13]
	s_mov_b32 m0, s41
	s_addc_u32 s97, s61, 0
	s_add_i32 s86, s84, s3
	global_load_lds_dwordx4 v[136:137], off
	v_lshl_add_u64 v[136:137], s[96:97], 0, v[130:131]
	s_mov_b32 m0, s86
	s_add_i32 s87, s86, 0x2000
	global_load_lds_dwordx4 v[136:137], off
	v_lshl_add_u64 v[136:137], s[96:97], 0, v[128:129]
	s_mov_b32 m0, s87
	v_lshl_add_u64 v[188:189], s[48:49], 0, v[130:131]
	global_load_lds_dwordx4 v[136:137], off
	v_lshl_add_u64 v[136:137], v[188:189], 0, s[12:13]
	s_mov_b32 m0, s35
	v_lshl_add_u64 v[222:223], s[48:49], 0, v[128:129]
	global_load_lds_dwordx4 v[136:137], off
	v_lshl_add_u64 v[136:137], v[222:223], 0, s[12:13]
	s_mov_b32 m0, s47
	s_nop 0
	global_load_lds_dwordx4 v[136:137], off
	s_waitcnt vmcnt(8)
	s_waitcnt lgkmcnt(0)
	s_barrier
; #define PG8_STAGE(bufoff, gbase, voff) do { _Pragma("unroll") for (int _i = 0; _i < 2; ++_i) \
;         __builtin_amdgcn_global_load_lds((const unsigned*)((const char*)(gbase) + (voff)[_i]), (PG8_LAS unsigned*)(lds + (bufoff) + ldsw + _i * 8192), 16, 0, 0); } while (0)
; #define PG8_LDA(dst, b, h) do { _Pragma("unroll") for (int m = 0; m < 4; ++m) _Pragma("unroll") for (int k = 0; k < 2; ++k) dst[m][k] = *(const PG8_LAS bf16x8*)(lds + PG8_SA(b, h) + aoff + m * 2048 + k * 1024); } while (0)
; #define PG8_LDB(dst, b, h) do { _Pragma("unroll") for (int n = 0; n < 2; ++n) _Pragma("unroll") for (int k = 0; k < 2; ++k) dst[n][k] = *(const PG8_LAS bf16x8*)(lds + PG8_SB(b, h) + boff + n * 2048 + k * 1024); } while (0)
; #define PG8_MMA(ai, bj, At, Bt) do { __builtin_amdgcn_s_setprio(1); _Pragma("unroll") for (int m = 0; m < 4; ++m) _Pragma("unroll") for (int n = 0; n < 2; ++n) _Pragma("unroll") for (int k = 0; k < 2; ++k) \
;         acc[ai][bj][m][n] = __builtin_amdgcn_mfma_f32_16x16x32_bf16(Bt[n][k], At[m][k], acc[ai][bj][m][n], 0, 0, 0); __builtin_amdgcn_s_setprio(0); } while (0)
; #define PG8_BAR __builtin_amdgcn_s_barrier()
; template <class Epi, class Sched, bool ALIGN_EPI = false, bool SP2 = false>
; __device__ __forceinline__ void gemm_phase(PG8_LAS unsigned char* lds, const Gemm g, const Sched& S, const Epi& E) {
;     ...
;             if constexpr (SP2) {
;             PG8_LDB(B0, 0, 0); PG8_LDB(B1, 0, 1); PG8_SCHED; PG8_LDA(At, 0, 0); PG8_STAGE(PG8_SA(1, 1), a1 + hstep, voffA);
;             PG8_WAIT_V(8); PG8_WAIT_L(0); PG8_BAR; PG8_MMA(0, 0, At, B0); PG8_MMA(0, 1, At, B1); PG8_BAR; PG8_SCHED;
;             PG8_LDA(At, 0, 1); PG8_STAGE(PG8_SB(0, 0), b2, voffB); PG8_STAGE(PG8_SB(0, 1), b2 + hstep, voffB); PG8_STAGE(PG8_SA(0, 0), a2, voffA);
;             PG8_WAIT_V(8); PG8_WAIT_L(0); PG8_BAR; PG8_MMA(1, 0, At, B0); PG8_MMA(1, 1, At, B1); PG8_BAR; PG8_SCHED;
;             PG8_LDB(B0, 1, 0); PG8_LDB(B1, 1, 1); PG8_SCHED; PG8_LDA(At, 1, 0); PG8_STAGE(PG8_SA(0, 1), a2 + hstep, voffA);
;             PG8_WAIT_V(8); PG8_WAIT_L(0); PG8_BAR; PG8_MMA(0, 0, At, B0); PG8_MMA(0, 1, At, B1); PG8_BAR; PG8_SCHED;
;             PG8_LDA(At, 1, 1); PG8_STAGE(PG8_SB(1, 0), b3, voffB); PG8_STAGE(PG8_SB(1, 1), b3 + hstep, voffB); PG8_STAGE(PG8_SA(1, 0), a3, voffA);
;             PG8_WAIT_V(8); PG8_WAIT_L(0); PG8_BAR; PG8_MMA(1, 0, At, B0); PG8_MMA(1, 1, At, B1); PG8_BAR; PG8_SCHED;
	s_setprio 1
	s_waitcnt lgkmcnt(0)
	v_mfma_f32_16x16x32_bf16 v[136:139], v[0:3], v[60:63], 0
	v_mfma_f32_16x16x32_bf16 v[156:159], v[0:3], v[104:107], 0
	v_mfma_f32_16x16x32_bf16 v[164:167], v[0:3], v[112:115], 0
	v_mfma_f32_16x16x32_bf16 v[0:3], v[0:3], v[120:123], 0
	v_mfma_f32_16x16x32_bf16 v[136:139], v[4:7], v[100:103], v[136:139]
	v_mfma_f32_16x16x32_bf16 v[156:159], v[4:7], v[108:111], v[156:159]
	v_mfma_f32_16x16x32_bf16 v[164:167], v[4:7], v[116:119], v[164:167]
	v_mfma_f32_16x16x32_bf16 v[0:3], v[4:7], v[124:127], v[0:3]
	v_mfma_f32_16x16x32_bf16 v[4:7], v[8:11], v[120:123], 0
	v_mfma_f32_16x16x32_bf16 v[152:155], v[8:11], v[60:63], 0
	v_mfma_f32_16x16x32_bf16 v[160:163], v[8:11], v[104:107], 0
	v_mfma_f32_16x16x32_bf16 v[168:171], v[8:11], v[112:115], 0
	v_mfma_f32_16x16x32_bf16 v[4:7], v[12:15], v[124:127], v[4:7]
	v_mfma_f32_16x16x32_bf16 v[152:155], v[12:15], v[100:103], v[152:155]
	v_mfma_f32_16x16x32_bf16 v[160:163], v[12:15], v[108:111], v[160:163]
	v_mfma_f32_16x16x32_bf16 v[168:171], v[12:15], v[116:119], v[168:171]
	s_setprio 0
	s_setprio 1
	v_mfma_f32_16x16x32_bf16 v[8:11], v[16:19], v[60:63], 0
	v_mfma_f32_16x16x32_bf16 v[12:15], v[24:27], v[60:63], 0
	v_mfma_f32_16x16x32_bf16 v[8:11], v[20:23], v[100:103], v[8:11]
	v_mfma_f32_16x16x32_bf16 v[12:15], v[28:31], v[100:103], v[12:15]
	v_mfma_f32_16x16x32_bf16 v[60:63], v[16:19], v[104:107], 0
	v_mfma_f32_16x16x32_bf16 v[100:103], v[24:27], v[104:107], 0
	v_mfma_f32_16x16x32_bf16 v[104:107], v[16:19], v[112:115], 0
	v_mfma_f32_16x16x32_bf16 v[16:19], v[16:19], v[120:123], 0
	v_mfma_f32_16x16x32_bf16 v[60:63], v[20:23], v[108:111], v[60:63]
	v_mfma_f32_16x16x32_bf16 v[100:103], v[28:31], v[108:111], v[100:103]
	v_mfma_f32_16x16x32_bf16 v[104:107], v[20:23], v[116:119], v[104:107]
	v_mfma_f32_16x16x32_bf16 v[108:111], v[24:27], v[112:115], 0
	v_mfma_f32_16x16x32_bf16 v[16:19], v[20:23], v[124:127], v[16:19]
	v_mfma_f32_16x16x32_bf16 v[20:23], v[24:27], v[120:123], 0
	v_mfma_f32_16x16x32_bf16 v[108:111], v[28:31], v[116:119], v[108:111]
	v_mfma_f32_16x16x32_bf16 v[20:23], v[28:31], v[124:127], v[20:23]
	s_setprio 0
	s_barrier
	s_sleep 2
	s_add_i32 s93, 0, 0x18000
	s_add_i32 s94, 0, 0x1c000
	v_add_u32_e32 v226, s93, v143
	v_add_u32_e32 v227, s94, v143
	ds_read_b128 v[24:27], v226
	ds_read_b128 v[28:31], v226 offset:1024
	ds_read_b128 v[112:115], v226 offset:2048
	ds_read_b128 v[116:119], v226 offset:3072
	ds_read_b128 v[120:123], v227
	ds_read_b128 v[124:127], v227 offset:1024
	ds_read_b128 v[172:175], v227 offset:2048
	ds_read_b128 v[176:179], v227 offset:3072
	s_add_u32 s96, s48, 0x10100
	s_addc_u32 s97, s49, 0
	s_mov_b32 m0, s64
	v_lshl_add_u64 v[224:225], s[96:97], 0, v[130:131]
	ds_read_b128 v[190:193], v149 offset:32768
	ds_read_b128 v[194:197], v149 offset:33792
	ds_read_b128 v[198:201], v149 offset:34816
	ds_read_b128 v[202:205], v149 offset:35840
	ds_read_b128 v[206:209], v149 offset:36864
	ds_read_b128 v[210:213], v149 offset:37888
	ds_read_b128 v[214:217], v149 offset:38912
	ds_read_b128 v[218:221], v149 offset:39936
	global_load_lds_dwordx4 v[224:225], off
	v_lshl_add_u64 v[224:225], s[96:97], 0, v[128:129]
	s_mov_b32 m0, s65
	s_nop 0
	global_load_lds_dwordx4 v[224:225], off
	s_waitcnt vmcnt(8)
	s_waitcnt lgkmcnt(0)
	s_barrier
	s_setprio 1
	s_waitcnt lgkmcnt(0)
	v_mfma_f32_16x16x32_bf16 v[64:67], v[24:27], v[190:193], v[64:67]
	v_mfma_f32_16x16x32_bf16 v[68:71], v[112:115], v[190:193], v[68:71]
	v_mfma_f32_16x16x32_bf16 v[72:75], v[24:27], v[198:201], v[72:75]
	v_mfma_f32_16x16x32_bf16 v[76:79], v[112:115], v[198:201], v[76:79]
	v_mfma_f32_16x16x32_bf16 v[80:83], v[24:27], v[206:209], v[80:83]
	v_mfma_f32_16x16x32_bf16 v[84:87], v[112:115], v[206:209], v[84:87]
	v_mfma_f32_16x16x32_bf16 v[88:91], v[24:27], v[214:217], v[88:91]
	v_mfma_f32_16x16x32_bf16 v[92:95], v[112:115], v[214:217], v[92:95]
	v_mfma_f32_16x16x32_bf16 v[64:67], v[28:31], v[194:197], v[64:67]
	v_mfma_f32_16x16x32_bf16 v[68:71], v[116:119], v[194:197], v[68:71]
	v_mfma_f32_16x16x32_bf16 v[72:75], v[28:31], v[202:205], v[72:75]
	v_mfma_f32_16x16x32_bf16 v[76:79], v[116:119], v[202:205], v[76:79]
	v_mfma_f32_16x16x32_bf16 v[80:83], v[28:31], v[210:213], v[80:83]
	v_mfma_f32_16x16x32_bf16 v[84:87], v[116:119], v[210:213], v[84:87]
	v_mfma_f32_16x16x32_bf16 v[88:91], v[28:31], v[218:221], v[88:91]
	v_mfma_f32_16x16x32_bf16 v[92:95], v[116:119], v[218:221], v[92:95]
	s_setprio 0
	s_setprio 1
	v_mfma_f32_16x16x32_bf16 v[96:99], v[120:123], v[190:193], v[96:99]
	v_mfma_f32_16x16x32_bf16 v[32:35], v[172:175], v[190:193], v[32:35]
	v_mfma_f32_16x16x32_bf16 v[36:39], v[120:123], v[198:201], v[36:39]
	v_mfma_f32_16x16x32_bf16 v[40:43], v[172:175], v[198:201], v[40:43]
	v_mfma_f32_16x16x32_bf16 v[44:47], v[120:123], v[206:209], v[44:47]
	v_mfma_f32_16x16x32_bf16 v[48:51], v[172:175], v[206:209], v[48:51]
	v_mfma_f32_16x16x32_bf16 v[52:55], v[120:123], v[214:217], v[52:55]
	v_mfma_f32_16x16x32_bf16 v[56:59], v[172:175], v[214:217], v[56:59]
	v_mfma_f32_16x16x32_bf16 v[96:99], v[124:127], v[194:197], v[96:99]
	v_mfma_f32_16x16x32_bf16 v[32:35], v[176:179], v[194:197], v[32:35]
	v_mfma_f32_16x16x32_bf16 v[36:39], v[124:127], v[202:205], v[36:39]
	v_mfma_f32_16x16x32_bf16 v[40:43], v[176:179], v[202:205], v[40:43]
	v_mfma_f32_16x16x32_bf16 v[44:47], v[124:127], v[210:213], v[44:47]
	v_mfma_f32_16x16x32_bf16 v[48:51], v[176:179], v[210:213], v[48:51]
	v_mfma_f32_16x16x32_bf16 v[52:55], v[124:127], v[218:221], v[52:55]
	v_mfma_f32_16x16x32_bf16 v[56:59], v[176:179], v[218:221], v[56:59]
	s_setprio 0
	s_barrier
; #define PG8_STAGE(bufoff, gbase, voff) do { _Pragma("unroll") for (int _i = 0; _i < 2; ++_i) \
;         __builtin_amdgcn_global_load_lds((const unsigned*)((const char*)(gbase) + (voff)[_i]), (PG8_LAS unsigned*)(lds + (bufoff) + ldsw + _i * 8192), 16, 0, 0); } while (0)
; #define PG8_LDA(dst, b, h) do { _Pragma("unroll") for (int m = 0; m < 4; ++m) _Pragma("unroll") for (int k = 0; k < 2; ++k) dst[m][k] = *(const PG8_LAS bf16x8*)(lds + PG8_SA(b, h) + aoff + m * 2048 + k * 1024); } while (0)
; #define PG8_LDB(dst, b, h) do { _Pragma("unroll") for (int n = 0; n < 2; ++n) _Pragma("unroll") for (int k = 0; k < 2; ++k) dst[n][k] = *(const PG8_LAS bf16x8*)(lds + PG8_SB(b, h) + boff + n * 2048 + k * 1024); } while (0)
; #define PG8_MMA(ai, bj, At, Bt) do { __builtin_amdgcn_s_setprio(1); _Pragma("unroll") for (int m = 0; m < 4; ++m) _Pragma("unroll") for (int n = 0; n < 2; ++n) _Pragma("unroll") for (int k = 0; k < 2; ++k) \
;         acc[ai][bj][m][n] = __builtin_amdgcn_mfma_f32_16x16x32_bf16(Bt[n][k], At[m][k], acc[ai][bj][m][n], 0, 0, 0); __builtin_amdgcn_s_setprio(0); } while (0)
; #define PG8_BAR __builtin_amdgcn_s_barrier()
; template <class Epi, class Sched, bool ALIGN_EPI = false, bool SP2 = false>
; __device__ __forceinline__ void gemm_phase(PG8_LAS unsigned char* lds, const Gemm g, const Sched& S, const Epi& E) {
;     ...
;             if constexpr (SP2) {
;             PG8_LDB(B0, 0, 0); PG8_LDB(B1, 0, 1); PG8_SCHED; PG8_LDA(At, 0, 0); PG8_STAGE(PG8_SA(1, 1), a1 + hstep, voffA);
;             PG8_WAIT_V(8); PG8_WAIT_L(0); PG8_BAR; PG8_MMA(0, 0, At, B0); PG8_MMA(0, 1, At, B1); PG8_BAR; PG8_SCHED;
;             PG8_LDA(At, 0, 1); PG8_STAGE(PG8_SB(0, 0), b2, voffB); PG8_STAGE(PG8_SB(0, 1), b2 + hstep, voffB); PG8_STAGE(PG8_SA(0, 0), a2, voffA);
;             PG8_WAIT_V(8); PG8_WAIT_L(0); PG8_BAR; PG8_MMA(1, 0, At, B0); PG8_MMA(1, 1, At, B1); PG8_BAR; PG8_SCHED;
;             PG8_LDB(B0, 1, 0); PG8_LDB(B1, 1, 1); PG8_SCHED; PG8_LDA(At, 1, 0); PG8_STAGE(PG8_SA(0, 1), a2 + hstep, voffA);
;             PG8_WAIT_V(8); PG8_WAIT_L(0); PG8_BAR; PG8_MMA(0, 0, At, B0); PG8_MMA(0, 1, At, B1); PG8_BAR; PG8_SCHED;
;             PG8_LDA(At, 1, 1); PG8_STAGE(PG8_SB(1, 0), b3, voffB); PG8_STAGE(PG8_SB(1, 1), b3 + hstep, voffB); PG8_STAGE(PG8_SA(1, 0), a3, voffA);
;             PG8_WAIT_V(8); PG8_WAIT_L(0); PG8_BAR; PG8_MMA(1, 0, At, B0); PG8_MMA(1, 1, At, B1); PG8_BAR; PG8_SCHED;
	s_sleep 2
	s_add_i32 s93, s93, s3
	s_add_i32 s90, s93, 0x2000
	v_lshl_add_u64 v[140:141], v[140:141], 0, s[36:37]
	s_mov_b32 m0, s93
	s_add_u32 s96, s60, 0x10180
	ds_read_b128 v[190:193], v149 offset:49152
	ds_read_b128 v[194:197], v149 offset:50176
	ds_read_b128 v[198:201], v149 offset:51200
	ds_read_b128 v[202:205], v149 offset:52224
	ds_read_b128 v[206:209], v149 offset:53248
	ds_read_b128 v[210:213], v149 offset:54272
	ds_read_b128 v[214:217], v149 offset:55296
	ds_read_b128 v[218:221], v149 offset:56320
	global_load_lds_dwordx4 v[140:141], off
	v_lshl_add_u64 v[140:141], v[180:181], 0, s[36:37]
	s_mov_b32 m0, s90
	s_addc_u32 s97, s61, 0
	s_add_i32 s60, s94, s3
	global_load_lds_dwordx4 v[140:141], off
	v_lshl_add_u64 v[140:141], s[96:97], 0, v[130:131]
	s_mov_b32 m0, s60
	s_add_i32 s61, s60, 0x2000
	global_load_lds_dwordx4 v[140:141], off
	v_lshl_add_u64 v[140:141], s[96:97], 0, v[128:129]
	s_mov_b32 m0, s61
	s_nop 0
	global_load_lds_dwordx4 v[140:141], off
	v_lshl_add_u64 v[140:141], v[188:189], 0, s[36:37]
	s_mov_b32 m0, s66
	s_nop 0
	global_load_lds_dwordx4 v[140:141], off
	v_lshl_add_u64 v[140:141], v[222:223], 0, s[36:37]
	s_mov_b32 m0, s67
	s_nop 0
	global_load_lds_dwordx4 v[140:141], off
	s_waitcnt vmcnt(8)
	s_waitcnt lgkmcnt(0)
	s_barrier
	s_setprio 1
	s_waitcnt lgkmcnt(0)
	v_mfma_f32_16x16x32_bf16 v[0:3], v[24:27], v[214:217], v[0:3]
	v_mfma_f32_16x16x32_bf16 v[4:7], v[112:115], v[214:217], v[4:7]
	v_mfma_f32_16x16x32_bf16 v[136:139], v[24:27], v[190:193], v[136:139]
	v_mfma_f32_16x16x32_bf16 v[152:155], v[112:115], v[190:193], v[152:155]
	v_mfma_f32_16x16x32_bf16 v[156:159], v[24:27], v[198:201], v[156:159]
	v_mfma_f32_16x16x32_bf16 v[160:163], v[112:115], v[198:201], v[160:163]
	v_mfma_f32_16x16x32_bf16 v[164:167], v[24:27], v[206:209], v[164:167]
	v_mfma_f32_16x16x32_bf16 v[168:171], v[112:115], v[206:209], v[168:171]
	v_mfma_f32_16x16x32_bf16 v[0:3], v[28:31], v[218:221], v[0:3]
	v_mfma_f32_16x16x32_bf16 v[4:7], v[116:119], v[218:221], v[4:7]
	v_mfma_f32_16x16x32_bf16 v[136:139], v[28:31], v[194:197], v[136:139]
	v_mfma_f32_16x16x32_bf16 v[152:155], v[116:119], v[194:197], v[152:155]
	v_mfma_f32_16x16x32_bf16 v[156:159], v[28:31], v[202:205], v[156:159]
	v_mfma_f32_16x16x32_bf16 v[160:163], v[116:119], v[202:205], v[160:163]
	v_mfma_f32_16x16x32_bf16 v[164:167], v[28:31], v[210:213], v[164:167]
	v_mfma_f32_16x16x32_bf16 v[168:171], v[116:119], v[210:213], v[168:171]
	s_setprio 0
	s_setprio 1
	v_mfma_f32_16x16x32_bf16 v[8:11], v[120:123], v[190:193], v[8:11]
	v_mfma_f32_16x16x32_bf16 v[12:15], v[172:175], v[190:193], v[12:15]
	v_mfma_f32_16x16x32_bf16 v[24:27], v[120:123], v[198:201], v[60:63]
	v_mfma_f32_16x16x32_bf16 v[28:31], v[172:175], v[198:201], v[100:103]
	v_mfma_f32_16x16x32_bf16 v[60:63], v[120:123], v[206:209], v[104:107]
	v_mfma_f32_16x16x32_bf16 v[100:103], v[172:175], v[206:209], v[108:111]
	v_mfma_f32_16x16x32_bf16 v[16:19], v[120:123], v[214:217], v[16:19]
	v_mfma_f32_16x16x32_bf16 v[20:23], v[172:175], v[214:217], v[20:23]
	v_mfma_f32_16x16x32_bf16 v[8:11], v[124:127], v[194:197], v[8:11]
	v_mfma_f32_16x16x32_bf16 v[12:15], v[176:179], v[194:197], v[12:15]
	v_mfma_f32_16x16x32_bf16 v[24:27], v[124:127], v[202:205], v[24:27]
	v_mfma_f32_16x16x32_bf16 v[28:31], v[176:179], v[202:205], v[28:31]
	v_mfma_f32_16x16x32_bf16 v[60:63], v[124:127], v[210:213], v[60:63]
	v_mfma_f32_16x16x32_bf16 v[100:103], v[176:179], v[210:213], v[100:103]
	v_mfma_f32_16x16x32_bf16 v[16:19], v[124:127], v[218:221], v[16:19]
	v_mfma_f32_16x16x32_bf16 v[20:23], v[176:179], v[218:221], v[20:23]
	s_setprio 0
	s_barrier
	s_sleep 2
	ds_read_b128 v[104:107], v147
	ds_read_b128 v[108:111], v147 offset:1024
	ds_read_b128 v[112:115], v147 offset:2048
	ds_read_b128 v[116:119], v147 offset:3072
	ds_read_b128 v[120:123], v148
	ds_read_b128 v[124:127], v148 offset:1024
	ds_read_b128 v[172:175], v148 offset:2048
	ds_read_b128 v[176:179], v148 offset:3072
	s_add_u32 s48, s48, 0x10180
	s_addc_u32 s49, s49, 0
	s_mov_b32 m0, s92
	v_lshl_add_u64 v[140:141], s[48:49], 0, v[130:131]
	ds_read_b128 v[190:193], v149
	ds_read_b128 v[194:197], v149 offset:1024
	ds_read_b128 v[198:201], v149 offset:2048
	ds_read_b128 v[202:205], v149 offset:3072
	ds_read_b128 v[206:209], v149 offset:4096
	ds_read_b128 v[210:213], v149 offset:5120
	ds_read_b128 v[214:217], v149 offset:6144
	ds_read_b128 v[218:221], v149 offset:7168
	global_load_lds_dwordx4 v[140:141], off
	v_lshl_add_u64 v[140:141], s[48:49], 0, v[128:129]
	s_mov_b32 m0, s39
	s_nop 0
	global_load_lds_dwordx4 v[140:141], off
	s_waitcnt vmcnt(8)
	s_waitcnt lgkmcnt(0)
	s_barrier
; #define PG8_STAGE(bufoff, gbase, voff) do { _Pragma("unroll") for (int _i = 0; _i < 2; ++_i) \
;         __builtin_amdgcn_global_load_lds((const unsigned*)((const char*)(gbase) + (voff)[_i]), (PG8_LAS unsigned*)(lds + (bufoff) + ldsw + _i * 8192), 16, 0, 0); } while (0)
; #define PG8_LDA(dst, b, h) do { _Pragma("unroll") for (int m = 0; m < 4; ++m) _Pragma("unroll") for (int k = 0; k < 2; ++k) dst[m][k] = *(const PG8_LAS bf16x8*)(lds + PG8_SA(b, h) + aoff + m * 2048 + k * 1024); } while (0)
; #define PG8_LDB(dst, b, h) do { _Pragma("unroll") for (int n = 0; n < 2; ++n) _Pragma("unroll") for (int k = 0; k < 2; ++k) dst[n][k] = *(const PG8_LAS bf16x8*)(lds + PG8_SB(b, h) + boff + n * 2048 + k * 1024); } while (0)
; #define PG8_MMA(ai, bj, At, Bt) do { __builtin_amdgcn_s_setprio(1); _Pragma("unroll") for (int m = 0; m < 4; ++m) _Pragma("unroll") for (int n = 0; n < 2; ++n) _Pragma("unroll") for (int k = 0; k < 2; ++k) \
;         acc[ai][bj][m][n] = __builtin_amdgcn_mfma_f32_16x16x32_bf16(Bt[n][k], At[m][k], acc[ai][bj][m][n], 0, 0, 0); __builtin_amdgcn_s_setprio(0); } while (0)
; #define PG8_BAR __builtin_amdgcn_s_barrier()
; template <class Epi, class Sched, bool ALIGN_EPI = false, bool SP2 = false>
; __device__ __forceinline__ void gemm_phase(PG8_LAS unsigned char* lds, const Gemm g, const Sched& S, const Epi& E) {
;     ...
;             if constexpr (SP2) {
;             PG8_LDB(B0, 0, 0); PG8_LDB(B1, 0, 1); PG8_SCHED; PG8_LDA(At, 0, 0); PG8_STAGE(PG8_SA(1, 1), a1 + hstep, voffA);
;             PG8_WAIT_V(8); PG8_WAIT_L(0); PG8_BAR; PG8_MMA(0, 0, At, B0); PG8_MMA(0, 1, At, B1); PG8_BAR; PG8_SCHED;
;             PG8_LDA(At, 0, 1); PG8_STAGE(PG8_SB(0, 0), b2, voffB); PG8_STAGE(PG8_SB(0, 1), b2 + hstep, voffB); PG8_STAGE(PG8_SA(0, 0), a2, voffA);
;             PG8_WAIT_V(8); PG8_WAIT_L(0); PG8_BAR; PG8_MMA(1, 0, At, B0); PG8_MMA(1, 1, At, B1); PG8_BAR; PG8_SCHED;
;             PG8_LDB(B0, 1, 0); PG8_LDB(B1, 1, 1); PG8_SCHED; PG8_LDA(At, 1, 0); PG8_STAGE(PG8_SA(0, 1), a2 + hstep, voffA);
;             PG8_WAIT_V(8); PG8_WAIT_L(0); PG8_BAR; PG8_MMA(0, 0, At, B0); PG8_MMA(0, 1, At, B1); PG8_BAR; PG8_SCHED;
;             PG8_LDA(At, 1, 1); PG8_STAGE(PG8_SB(1, 0), b3, voffB); PG8_STAGE(PG8_SB(1, 1), b3 + hstep, voffB); PG8_STAGE(PG8_SA(1, 0), a3, voffA);
;             PG8_WAIT_V(8); PG8_WAIT_L(0); PG8_BAR; PG8_MMA(1, 0, At, B0); PG8_MMA(1, 1, At, B1); PG8_BAR; PG8_SCHED;
	s_setprio 1
	s_waitcnt lgkmcnt(0)
	v_mfma_f32_16x16x32_bf16 v[64:67], v[104:107], v[190:193], v[64:67]
	v_mfma_f32_16x16x32_bf16 v[68:71], v[112:115], v[190:193], v[68:71]
	v_mfma_f32_16x16x32_bf16 v[72:75], v[104:107], v[198:201], v[72:75]
	v_mfma_f32_16x16x32_bf16 v[76:79], v[112:115], v[198:201], v[76:79]
	v_mfma_f32_16x16x32_bf16 v[80:83], v[104:107], v[206:209], v[80:83]
	v_mfma_f32_16x16x32_bf16 v[84:87], v[112:115], v[206:209], v[84:87]
	v_mfma_f32_16x16x32_bf16 v[88:91], v[104:107], v[214:217], v[88:91]
	v_mfma_f32_16x16x32_bf16 v[92:95], v[112:115], v[214:217], v[92:95]
	v_mfma_f32_16x16x32_bf16 v[64:67], v[108:111], v[194:197], v[64:67]
	v_mfma_f32_16x16x32_bf16 v[68:71], v[116:119], v[194:197], v[68:71]
	v_mfma_f32_16x16x32_bf16 v[72:75], v[108:111], v[202:205], v[72:75]
	v_mfma_f32_16x16x32_bf16 v[76:79], v[116:119], v[202:205], v[76:79]
	v_mfma_f32_16x16x32_bf16 v[80:83], v[108:111], v[210:213], v[80:83]
	v_mfma_f32_16x16x32_bf16 v[84:87], v[116:119], v[210:213], v[84:87]
	v_mfma_f32_16x16x32_bf16 v[88:91], v[108:111], v[218:221], v[88:91]
	v_mfma_f32_16x16x32_bf16 v[92:95], v[116:119], v[218:221], v[92:95]
	s_setprio 0
	s_setprio 1
	v_mfma_f32_16x16x32_bf16 v[32:35], v[172:175], v[190:193], v[32:35]
	v_mfma_f32_16x16x32_bf16 v[36:39], v[120:123], v[198:201], v[36:39]
	v_mfma_f32_16x16x32_bf16 v[40:43], v[172:175], v[198:201], v[40:43]
	v_mfma_f32_16x16x32_bf16 v[44:47], v[120:123], v[206:209], v[44:47]
	v_mfma_f32_16x16x32_bf16 v[48:51], v[172:175], v[206:209], v[48:51]
	v_mfma_f32_16x16x32_bf16 v[52:55], v[120:123], v[214:217], v[52:55]
	v_mfma_f32_16x16x32_bf16 v[56:59], v[172:175], v[214:217], v[56:59]
	v_mfma_f32_16x16x32_bf16 v[96:99], v[120:123], v[190:193], v[96:99]
	v_mfma_f32_16x16x32_bf16 v[32:35], v[176:179], v[194:197], v[32:35]
	v_mfma_f32_16x16x32_bf16 v[36:39], v[124:127], v[202:205], v[36:39]
	v_mfma_f32_16x16x32_bf16 v[40:43], v[176:179], v[202:205], v[40:43]
	v_mfma_f32_16x16x32_bf16 v[44:47], v[124:127], v[210:213], v[44:47]
	v_mfma_f32_16x16x32_bf16 v[48:51], v[176:179], v[210:213], v[48:51]
	v_mfma_f32_16x16x32_bf16 v[52:55], v[124:127], v[218:221], v[52:55]
	v_mfma_f32_16x16x32_bf16 v[56:59], v[176:179], v[218:221], v[56:59]
	v_mfma_f32_16x16x32_bf16 v[222:225], v[124:127], v[194:197], v[96:99]
	s_setprio 0
	s_barrier
	s_sleep 2
	s_mov_b32 m0, s89
	v_lshl_add_u64 v[140:141], s[58:59], 0, v[130:131]
	s_add_u32 s48, s58, 0x10000
	ds_read_b128 v[96:99], v149 offset:16384
	ds_read_b128 v[190:193], v149 offset:17408
	ds_read_b128 v[194:197], v149 offset:18432
	ds_read_b128 v[198:201], v149 offset:19456
	ds_read_b128 v[202:205], v149 offset:20480
	ds_read_b128 v[206:209], v149 offset:21504
	ds_read_b128 v[210:213], v149 offset:22528
	ds_read_b128 v[214:217], v149 offset:23552
	global_load_lds_dwordx4 v[140:141], off
	v_lshl_add_u64 v[180:181], s[58:59], 0, v[128:129]
	s_mov_b32 m0, s41
	s_addc_u32 s49, s59, 0
	global_load_lds_dwordx4 v[180:181], off
	v_lshl_add_u64 v[188:189], s[48:49], 0, v[130:131]
	s_mov_b32 m0, s86
	v_lshl_add_u64 v[250:251], s[62:63], 0, v[128:129]
	global_load_lds_dwordx4 v[188:189], off
	v_lshl_add_u64 v[188:189], s[48:49], 0, v[128:129]
	s_mov_b32 m0, s87
	s_nop 0
	global_load_lds_dwordx4 v[188:189], off
	v_lshl_add_u64 v[188:189], s[62:63], 0, v[130:131]
	s_mov_b32 m0, s35
	s_nop 0
	global_load_lds_dwordx4 v[188:189], off
	s_mov_b32 m0, s47
	s_nop 0
	global_load_lds_dwordx4 v[250:251], off
	s_waitcnt vmcnt(8)
	s_waitcnt lgkmcnt(0)
	s_barrier
	s_setprio 1
	s_waitcnt lgkmcnt(0)
	v_mfma_f32_16x16x32_bf16 v[0:3], v[104:107], v[210:213], v[0:3]
	v_mfma_f32_16x16x32_bf16 v[4:7], v[112:115], v[210:213], v[4:7]
	v_mfma_f32_16x16x32_bf16 v[136:139], v[104:107], v[96:99], v[136:139]
	v_mfma_f32_16x16x32_bf16 v[152:155], v[112:115], v[96:99], v[152:155]
	v_mfma_f32_16x16x32_bf16 v[156:159], v[104:107], v[194:197], v[156:159]
	v_mfma_f32_16x16x32_bf16 v[160:163], v[112:115], v[194:197], v[160:163]
	v_mfma_f32_16x16x32_bf16 v[164:167], v[104:107], v[202:205], v[164:167]
	v_mfma_f32_16x16x32_bf16 v[168:171], v[112:115], v[202:205], v[168:171]
	v_mfma_f32_16x16x32_bf16 v[0:3], v[108:111], v[214:217], v[0:3]
	v_mfma_f32_16x16x32_bf16 v[4:7], v[116:119], v[214:217], v[4:7]
	v_mfma_f32_16x16x32_bf16 v[136:139], v[108:111], v[190:193], v[136:139]
	v_mfma_f32_16x16x32_bf16 v[152:155], v[116:119], v[190:193], v[152:155]
	v_mfma_f32_16x16x32_bf16 v[156:159], v[108:111], v[198:201], v[156:159]
	v_mfma_f32_16x16x32_bf16 v[160:163], v[116:119], v[198:201], v[160:163]
	v_mfma_f32_16x16x32_bf16 v[164:167], v[108:111], v[206:209], v[164:167]
	v_mfma_f32_16x16x32_bf16 v[168:171], v[116:119], v[206:209], v[168:171]
	s_setprio 0
	s_setprio 1
	v_mfma_f32_16x16x32_bf16 v[8:11], v[120:123], v[96:99], v[8:11]
	v_mfma_f32_16x16x32_bf16 v[12:15], v[172:175], v[96:99], v[12:15]
	v_mfma_f32_16x16x32_bf16 v[24:27], v[120:123], v[194:197], v[24:27]
	v_mfma_f32_16x16x32_bf16 v[28:31], v[172:175], v[194:197], v[28:31]
	v_mfma_f32_16x16x32_bf16 v[60:63], v[120:123], v[202:205], v[60:63]
	v_mfma_f32_16x16x32_bf16 v[16:19], v[120:123], v[210:213], v[16:19]
	v_mfma_f32_16x16x32_bf16 v[8:11], v[124:127], v[190:193], v[8:11]
	v_mfma_f32_16x16x32_bf16 v[12:15], v[176:179], v[190:193], v[12:15]
	v_mfma_f32_16x16x32_bf16 v[24:27], v[124:127], v[198:201], v[24:27]
	v_mfma_f32_16x16x32_bf16 v[28:31], v[176:179], v[198:201], v[28:31]
	v_mfma_f32_16x16x32_bf16 v[190:193], v[124:127], v[206:209], v[60:63]
	v_mfma_f32_16x16x32_bf16 v[60:63], v[172:175], v[202:205], v[100:103]
	v_mfma_f32_16x16x32_bf16 v[198:201], v[124:127], v[214:217], v[16:19]
	v_mfma_f32_16x16x32_bf16 v[16:19], v[172:175], v[210:213], v[20:23]
	v_mfma_f32_16x16x32_bf16 v[194:197], v[176:179], v[206:209], v[60:63]
	v_mfma_f32_16x16x32_bf16 v[172:175], v[176:179], v[214:217], v[16:19]
	s_setprio 0
	s_barrier
; #define PG8_STAGE(bufoff, gbase, voff) do { _Pragma("unroll") for (int _i = 0; _i < 2; ++_i) \
;         __builtin_amdgcn_global_load_lds((const unsigned*)((const char*)(gbase) + (voff)[_i]), (PG8_LAS unsigned*)(lds + (bufoff) + ldsw + _i * 8192), 16, 0, 0); } while (0)
; #define PG8_LDA(dst, b, h) do { _Pragma("unroll") for (int m = 0; m < 4; ++m) _Pragma("unroll") for (int k = 0; k < 2; ++k) dst[m][k] = *(const PG8_LAS bf16x8*)(lds + PG8_SA(b, h) + aoff + m * 2048 + k * 1024); } while (0)
; #define PG8_LDB(dst, b, h) do { _Pragma("unroll") for (int n = 0; n < 2; ++n) _Pragma("unroll") for (int k = 0; k < 2; ++k) dst[n][k] = *(const PG8_LAS bf16x8*)(lds + PG8_SB(b, h) + boff + n * 2048 + k * 1024); } while (0)
; #define PG8_WAIT_V(n) asm volatile("s_waitcnt vmcnt(" #n ")" ::: "memory")
; #define PG8_WAIT_L(n) asm volatile("s_waitcnt lgkmcnt(" #n ")" ::: "memory")
; #define PG8_BAR __builtin_amdgcn_s_barrier()
; #define PG8_SCHED __builtin_amdgcn_sched_barrier(0)
; template <class Epi, class Sched, bool ALIGN_EPI = false, bool SP2 = false>
; __device__ __forceinline__ void gemm_phase(PG8_LAS unsigned char* lds, const Gemm g, const Sched& S, const Epi& E) {
;     ...
;             if constexpr (SP2) {
;             PG8_LDB(B0, 0, 0); PG8_LDB(B1, 0, 1); PG8_SCHED; PG8_LDA(At, 0, 0); PG8_STAGE(PG8_SA(1, 1), a1 + hstep, voffA);
;             PG8_WAIT_V(8); PG8_WAIT_L(0); PG8_BAR; PG8_MMA(0, 0, At, B0); PG8_MMA(0, 1, At, B1); PG8_BAR; PG8_SCHED;
;             PG8_LDA(At, 0, 1); PG8_STAGE(PG8_SB(0, 0), b2, voffB); PG8_STAGE(PG8_SB(0, 1), b2 + hstep, voffB); PG8_STAGE(PG8_SA(0, 0), a2, voffA);
;             PG8_WAIT_V(8); PG8_WAIT_L(0); PG8_BAR; PG8_MMA(1, 0, At, B0); PG8_MMA(1, 1, At, B1); PG8_BAR; PG8_SCHED;
;             PG8_LDB(B0, 1, 0); PG8_LDB(B1, 1, 1); PG8_SCHED; PG8_LDA(At, 1, 0); PG8_STAGE(PG8_SA(0, 1), a2 + hstep, voffA);
;             PG8_WAIT_V(8); PG8_WAIT_L(0); PG8_BAR; PG8_MMA(0, 0, At, B0); PG8_MMA(0, 1, At, B1); PG8_BAR; PG8_SCHED;
;             PG8_LDA(At, 1, 1); PG8_STAGE(PG8_SB(1, 0), b3, voffB); PG8_STAGE(PG8_SB(1, 1), b3 + hstep, voffB); PG8_STAGE(PG8_SA(1, 0), a3, voffA);
;             PG8_WAIT_V(8); PG8_WAIT_L(0); PG8_BAR; PG8_MMA(1, 0, At, B0); PG8_MMA(1, 1, At, B1); PG8_BAR; PG8_SCHED;
;     ...
;         if constexpr (ALIGN_EPI) { if (wr == 0) PG8_BAR; }
	s_sleep 2
	s_nop 1
	ds_read_b128 v[60:63], v226
	ds_read_b128 v[176:179], v226 offset:1024
	ds_read_b128 v[202:205], v226 offset:2048
	ds_read_b128 v[206:209], v226 offset:3072
	ds_read_b128 v[210:213], v227
	ds_read_b128 v[214:217], v227 offset:1024
	ds_read_b128 v[218:221], v227 offset:2048
	ds_read_b128 v[226:229], v227 offset:3072
	s_add_u32 s48, s62, 0x10000
	s_addc_u32 s49, s63, 0
	s_mov_b32 m0, s64
	v_lshl_add_u64 v[96:97], s[48:49], 0, v[130:131]
	ds_read_b128 v[16:19], v149 offset:32768
	ds_read_b128 v[20:23], v149 offset:33792
	ds_read_b128 v[104:107], v149 offset:34816
	ds_read_b128 v[230:233], v149 offset:35840
	ds_read_b128 v[234:237], v149 offset:36864
	ds_read_b128 v[238:241], v149 offset:37888
	ds_read_b128 v[242:245], v149 offset:38912
	ds_read_b128 v[246:249], v149 offset:39936
	global_load_lds_dwordx4 v[96:97], off
	v_lshl_add_u64 v[96:97], s[48:49], 0, v[128:129]
	s_mov_b32 m0, s65
	s_nop 0
	global_load_lds_dwordx4 v[96:97], off
	s_waitcnt vmcnt(8)
	s_waitcnt lgkmcnt(0)
	s_barrier
	s_setprio 1
	s_waitcnt lgkmcnt(0)
	v_mfma_f32_16x16x32_bf16 v[64:67], v[60:63], v[16:19], v[64:67]
	v_mfma_f32_16x16x32_bf16 v[112:115], v[176:179], v[20:23], v[64:67]
	v_mfma_f32_16x16x32_bf16 v[64:67], v[202:205], v[16:19], v[68:71]
	v_mfma_f32_16x16x32_bf16 v[116:119], v[206:209], v[20:23], v[64:67]
	v_mfma_f32_16x16x32_bf16 v[64:67], v[60:63], v[104:107], v[72:75]
	v_mfma_f32_16x16x32_bf16 v[96:99], v[176:179], v[230:233], v[64:67]
	v_mfma_f32_16x16x32_bf16 v[64:67], v[202:205], v[104:107], v[76:79]
	v_mfma_f32_16x16x32_bf16 v[100:103], v[206:209], v[230:233], v[64:67]
	v_mfma_f32_16x16x32_bf16 v[64:67], v[60:63], v[234:237], v[80:83]
	v_mfma_f32_16x16x32_bf16 v[80:83], v[176:179], v[238:241], v[64:67]
	v_mfma_f32_16x16x32_bf16 v[64:67], v[202:205], v[234:237], v[84:87]
	v_mfma_f32_16x16x32_bf16 v[84:87], v[206:209], v[238:241], v[64:67]
	v_mfma_f32_16x16x32_bf16 v[64:67], v[60:63], v[242:245], v[88:91]
	v_mfma_f32_16x16x32_bf16 v[68:71], v[202:205], v[242:245], v[92:95]
	v_mfma_f32_16x16x32_bf16 v[64:67], v[176:179], v[246:249], v[64:67]
	v_mfma_f32_16x16x32_bf16 v[68:71], v[206:209], v[246:249], v[68:71]
	s_setprio 0
	s_setprio 1
	v_mfma_f32_16x16x32_bf16 v[72:75], v[210:213], v[16:19], v[222:225]
	v_mfma_f32_16x16x32_bf16 v[16:19], v[218:221], v[16:19], v[32:35]
	v_mfma_f32_16x16x32_bf16 v[120:123], v[226:229], v[20:23], v[16:19]
	v_mfma_f32_16x16x32_bf16 v[16:19], v[210:213], v[104:107], v[36:39]
	v_mfma_f32_16x16x32_bf16 v[108:111], v[214:217], v[230:233], v[16:19]
	v_mfma_f32_16x16x32_bf16 v[16:19], v[218:221], v[104:107], v[40:43]
	v_mfma_f32_16x16x32_bf16 v[104:107], v[226:229], v[230:233], v[16:19]
	v_mfma_f32_16x16x32_bf16 v[16:19], v[210:213], v[234:237], v[44:47]
	v_mfma_f32_16x16x32_bf16 v[92:95], v[214:217], v[238:241], v[16:19]
	v_mfma_f32_16x16x32_bf16 v[16:19], v[218:221], v[234:237], v[48:51]
	v_mfma_f32_16x16x32_bf16 v[88:91], v[226:229], v[238:241], v[16:19]
	v_mfma_f32_16x16x32_bf16 v[16:19], v[210:213], v[242:245], v[52:55]
	v_mfma_f32_16x16x32_bf16 v[76:79], v[214:217], v[246:249], v[16:19]
	v_mfma_f32_16x16x32_bf16 v[16:19], v[218:221], v[242:245], v[56:59]
	v_mfma_f32_16x16x32_bf16 v[124:127], v[214:217], v[20:23], v[72:75]
	v_mfma_f32_16x16x32_bf16 v[72:75], v[226:229], v[246:249], v[16:19]
	s_setprio 0
	s_barrier
	s_sleep 2
	s_mov_b32 m0, s93
	s_nop 2
	v_lshl_add_u64 v[16:17], v[140:141], 0, s[6:7]
	s_add_u32 s48, s58, 0x10080
	ds_read_b128 v[40:43], v149 offset:49152
	ds_read_b128 v[44:47], v149 offset:50176
	ds_read_b128 v[222:225], v149 offset:51200
	ds_read_b128 v[230:233], v149 offset:52224
	ds_read_b128 v[234:237], v149 offset:53248
	ds_read_b128 v[238:241], v149 offset:54272
	ds_read_b128 v[242:245], v149 offset:55296
	ds_read_b128 v[246:249], v149 offset:56320
	global_load_lds_dwordx4 v[16:17], off
	v_lshl_add_u64 v[16:17], v[180:181], 0, s[6:7]
	s_mov_b32 m0, s90
	s_addc_u32 s49, s59, 0
	global_load_lds_dwordx4 v[16:17], off
	v_lshl_add_u64 v[16:17], s[48:49], 0, v[130:131]
	s_mov_b32 m0, s60
	s_nop 0
	global_load_lds_dwordx4 v[16:17], off
	v_lshl_add_u64 v[16:17], s[48:49], 0, v[128:129]
	s_mov_b32 m0, s61
	s_nop 0
	global_load_lds_dwordx4 v[16:17], off
	v_lshl_add_u64 v[16:17], v[188:189], 0, s[6:7]
	s_mov_b32 m0, s66
	s_nop 0
	global_load_lds_dwordx4 v[16:17], off
	v_lshl_add_u64 v[16:17], v[250:251], 0, s[6:7]
	s_mov_b32 m0, s67
	s_nop 0
	global_load_lds_dwordx4 v[16:17], off
	s_waitcnt vmcnt(8)
	s_waitcnt lgkmcnt(0)
	s_barrier
	s_setprio 1
	s_waitcnt lgkmcnt(0)
	v_mfma_f32_16x16x32_bf16 v[16:19], v[60:63], v[40:43], v[136:139]
	v_mfma_f32_16x16x32_bf16 v[48:51], v[176:179], v[44:47], v[16:19]
	v_mfma_f32_16x16x32_bf16 v[16:19], v[202:205], v[40:43], v[152:155]
	v_mfma_f32_16x16x32_bf16 v[52:55], v[206:209], v[44:47], v[16:19]
	v_mfma_f32_16x16x32_bf16 v[16:19], v[60:63], v[222:225], v[156:159]
	v_mfma_f32_16x16x32_bf16 v[32:35], v[176:179], v[230:233], v[16:19]
	v_mfma_f32_16x16x32_bf16 v[16:19], v[202:205], v[222:225], v[160:163]
	v_mfma_f32_16x16x32_bf16 v[36:39], v[206:209], v[230:233], v[16:19]
	v_mfma_f32_16x16x32_bf16 v[16:19], v[60:63], v[234:237], v[164:167]
	v_mfma_f32_16x16x32_bf16 v[20:23], v[202:205], v[234:237], v[168:171]
	v_mfma_f32_16x16x32_bf16 v[0:3], v[60:63], v[242:245], v[0:3]
	v_mfma_f32_16x16x32_bf16 v[4:7], v[202:205], v[242:245], v[4:7]
	v_mfma_f32_16x16x32_bf16 v[16:19], v[176:179], v[238:241], v[16:19]
	v_mfma_f32_16x16x32_bf16 v[20:23], v[206:209], v[238:241], v[20:23]
	v_mfma_f32_16x16x32_bf16 v[0:3], v[176:179], v[246:249], v[0:3]
	v_mfma_f32_16x16x32_bf16 v[4:7], v[206:209], v[246:249], v[4:7]
	s_setprio 0
	s_setprio 1
	v_mfma_f32_16x16x32_bf16 v[8:11], v[210:213], v[40:43], v[8:11]
	v_mfma_f32_16x16x32_bf16 v[60:63], v[214:217], v[44:47], v[8:11]
	v_mfma_f32_16x16x32_bf16 v[8:11], v[218:221], v[40:43], v[12:15]
	v_mfma_f32_16x16x32_bf16 v[56:59], v[226:229], v[44:47], v[8:11]
	v_mfma_f32_16x16x32_bf16 v[8:11], v[210:213], v[222:225], v[24:27]
	v_mfma_f32_16x16x32_bf16 v[44:47], v[214:217], v[230:233], v[8:11]
	v_mfma_f32_16x16x32_bf16 v[8:11], v[218:221], v[222:225], v[28:31]
	v_mfma_f32_16x16x32_bf16 v[40:43], v[226:229], v[230:233], v[8:11]
	v_mfma_f32_16x16x32_bf16 v[8:11], v[210:213], v[234:237], v[190:193]
	v_mfma_f32_16x16x32_bf16 v[28:31], v[214:217], v[238:241], v[8:11]
	v_mfma_f32_16x16x32_bf16 v[8:11], v[218:221], v[234:237], v[194:197]
	v_mfma_f32_16x16x32_bf16 v[24:27], v[226:229], v[238:241], v[8:11]
	v_mfma_f32_16x16x32_bf16 v[8:11], v[210:213], v[242:245], v[198:201]
	v_mfma_f32_16x16x32_bf16 v[12:15], v[218:221], v[242:245], v[172:175]
	v_mfma_f32_16x16x32_bf16 v[8:11], v[214:217], v[246:249], v[8:11]
	v_mfma_f32_16x16x32_bf16 v[12:15], v[226:229], v[246:249], v[12:15]
	s_setprio 0
	s_barrier
	s_sleep 2
	s_andn2_b64 vcc, exec, s[8:9]
	s_cbranch_vccnz .LBB0_183
	s_barrier

; #define PG8_STAGE(bufoff, gbase, voff) do { _Pragma("unroll") for (int _i = 0; _i < 2; ++_i) \
;         __builtin_amdgcn_global_load_lds((const unsigned*)((const char*)(gbase) + (voff)[_i]), (PG8_LAS unsigned*)(lds + (bufoff) + ldsw + _i * 8192), 16, 0, 0); } while (0)
; #define PG8_LDA(dst, b, h) do { _Pragma("unroll") for (int m = 0; m < 4; ++m) _Pragma("unroll") for (int k = 0; k < 2; ++k) dst[m][k] = *(const PG8_LAS bf16x8*)(lds + PG8_SA(b, h) + aoff + m * 2048 + k * 1024); } while (0)
; #define PG8_LDB(dst, b, h) do { _Pragma("unroll") for (int n = 0; n < 2; ++n) _Pragma("unroll") for (int k = 0; k < 2; ++k) dst[n][k] = *(const PG8_LAS bf16x8*)(lds + PG8_SB(b, h) + boff + n * 2048 + k * 1024); } while (0)
; template <class Epi, class Sched, bool ALIGN_EPI = false, bool SP2 = false>
; __device__ __forceinline__ void gemm_phase(PG8_LAS unsigned char* lds, const Gemm g, const Sched& S, const Epi& E) {
;     ...
;         for (int t = 0; t < nt; t += 2) {
;             const bool last = (t == nt - 2);
;             const char* a1 = cA + (size_t)(t + 1) * kstep;
;             const char* a2 = last ? nA : cA + (size_t)(t + 2) * kstep; const char* b2 = last ? nB : cB + (size_t)(t + 2) * kstep;
;             const char* a3 = a2 + kstep; const char* b3 = b2 + kstep;
;             if (last && has_next) S.a_ready(nxt);
;             if constexpr (SP2) {
;             PG8_LDB(B0, 0, 0); PG8_LDB(B1, 0, 1); PG8_SCHED; PG8_LDA(At, 0, 0); PG8_STAGE(PG8_SA(1, 1), a1 + hstep, voffA);
;             PG8_WAIT_V(8); PG8_WAIT_L(0); PG8_BAR; PG8_MMA(0, 0, At, B0); PG8_MMA(0, 1, At, B1); PG8_BAR; PG8_SCHED;
;             PG8_LDA(At, 0, 1); PG8_STAGE(PG8_SB(0, 0), b2, voffB); PG8_STAGE(PG8_SB(0, 1), b2 + hstep, voffB); PG8_STAGE(PG8_SA(0, 0), a2, voffA);
;             PG8_WAIT_V(8); PG8_WAIT_L(0); PG8_BAR; PG8_MMA(1, 0, At, B0); PG8_MMA(1, 1, At, B1); PG8_BAR; PG8_SCHED;
;             PG8_LDB(B0, 1, 0); PG8_LDB(B1, 1, 1); PG8_SCHED; PG8_LDA(At, 1, 0); PG8_STAGE(PG8_SA(0, 1), a2 + hstep, voffA);
;             PG8_WAIT_V(8); PG8_WAIT_L(0); PG8_BAR; PG8_MMA(0, 0, At, B0); PG8_MMA(0, 1, At, B1); PG8_BAR; PG8_SCHED;
;             PG8_LDA(At, 1, 1); PG8_STAGE(PG8_SB(1, 0), b3, voffB); PG8_STAGE(PG8_SB(1, 1), b3 + hstep, voffB); PG8_STAGE(PG8_SA(1, 0), a3, voffA);
;             PG8_WAIT_V(8); PG8_WAIT_L(0); PG8_BAR; PG8_MMA(1, 0, At, B0); PG8_MMA(1, 1, At, B1); PG8_BAR; PG8_SCHED;
.LBB0_199:
	ds_read_b128 v[146:149], v162
	ds_read_b128 v[172:175], v162 offset:1024
	ds_read_b128 v[176:179], v162 offset:2048
	ds_read_b128 v[190:193], v162 offset:3072
	ds_read_b128 v[194:197], v163
	ds_read_b128 v[198:201], v163 offset:1024
	ds_read_b128 v[202:205], v163 offset:2048
	ds_read_b128 v[206:209], v163 offset:3072
	s_add_u32 s60, s58, 0xfff80080
	s_addc_u32 s61, s59, -1
	s_cmp_eq_u32 s94, 28
	s_cselect_b32 s63, s9, s61
	s_cselect_b32 s62, s43, s60
	s_cselect_b32 s61, s41, s93
	s_cselect_b32 s60, s90, s92
	v_lshl_add_u64 v[150:151], s[58:59], 0, v[136:137]
	s_add_i32 m0, s28, 0xc000
	ds_read_b128 v[210:213], v164
	ds_read_b128 v[214:217], v164 offset:1024
	ds_read_b128 v[218:221], v164 offset:2048
	ds_read_b128 v[222:225], v164 offset:3072
	ds_read_b128 v[226:229], v164 offset:4096
	ds_read_b128 v[230:233], v164 offset:5120
	ds_read_b128 v[234:237], v164 offset:6144
	ds_read_b128 v[238:241], v164 offset:7168
	global_load_lds_dwordx4 v[150:151], off
	v_lshl_add_u64 v[150:151], s[58:59], 0, v[138:139]
	s_add_i32 m0, s28, 0xe000
	s_nop 0
	global_load_lds_dwordx4 v[150:151], off
	s_waitcnt vmcnt(8)
	s_waitcnt lgkmcnt(0)
	s_barrier
	s_setprio 1
	s_waitcnt lgkmcnt(0)
	v_mfma_f32_16x16x32_bf16 v[124:127], v[146:149], v[210:213], v[124:127]
	v_mfma_f32_16x16x32_bf16 v[120:123], v[176:179], v[210:213], v[120:123]
	v_mfma_f32_16x16x32_bf16 v[108:111], v[146:149], v[218:221], v[108:111]
	v_mfma_f32_16x16x32_bf16 v[104:107], v[176:179], v[218:221], v[104:107]
	v_mfma_f32_16x16x32_bf16 v[92:95], v[146:149], v[226:229], v[92:95]
	v_mfma_f32_16x16x32_bf16 v[88:91], v[176:179], v[226:229], v[88:91]
	v_mfma_f32_16x16x32_bf16 v[76:79], v[146:149], v[234:237], v[76:79]
	v_mfma_f32_16x16x32_bf16 v[72:75], v[176:179], v[234:237], v[72:75]
	v_mfma_f32_16x16x32_bf16 v[124:127], v[172:175], v[214:217], v[124:127]
	v_mfma_f32_16x16x32_bf16 v[120:123], v[190:193], v[214:217], v[120:123]
	v_mfma_f32_16x16x32_bf16 v[108:111], v[172:175], v[222:225], v[108:111]
	v_mfma_f32_16x16x32_bf16 v[104:107], v[190:193], v[222:225], v[104:107]
	v_mfma_f32_16x16x32_bf16 v[92:95], v[172:175], v[230:233], v[92:95]
	v_mfma_f32_16x16x32_bf16 v[88:91], v[190:193], v[230:233], v[88:91]
	v_mfma_f32_16x16x32_bf16 v[76:79], v[172:175], v[238:241], v[76:79]
	v_mfma_f32_16x16x32_bf16 v[72:75], v[190:193], v[238:241], v[72:75]
	s_setprio 0
	s_setprio 1
	v_mfma_f32_16x16x32_bf16 v[116:119], v[194:197], v[210:213], v[116:119]
	v_mfma_f32_16x16x32_bf16 v[112:115], v[202:205], v[210:213], v[112:115]
	v_mfma_f32_16x16x32_bf16 v[100:103], v[194:197], v[218:221], v[100:103]
	v_mfma_f32_16x16x32_bf16 v[96:99], v[202:205], v[218:221], v[96:99]
	v_mfma_f32_16x16x32_bf16 v[84:87], v[194:197], v[226:229], v[84:87]
	v_mfma_f32_16x16x32_bf16 v[80:83], v[202:205], v[226:229], v[80:83]
	v_mfma_f32_16x16x32_bf16 v[68:71], v[194:197], v[234:237], v[68:71]
	v_mfma_f32_16x16x32_bf16 v[64:67], v[202:205], v[234:237], v[64:67]
	v_mfma_f32_16x16x32_bf16 v[116:119], v[198:201], v[214:217], v[116:119]
	v_mfma_f32_16x16x32_bf16 v[112:115], v[206:209], v[214:217], v[112:115]
	v_mfma_f32_16x16x32_bf16 v[100:103], v[198:201], v[222:225], v[100:103]
	v_mfma_f32_16x16x32_bf16 v[96:99], v[206:209], v[222:225], v[96:99]
	v_mfma_f32_16x16x32_bf16 v[84:87], v[198:201], v[230:233], v[84:87]
	v_mfma_f32_16x16x32_bf16 v[80:83], v[206:209], v[230:233], v[80:83]
	v_mfma_f32_16x16x32_bf16 v[68:71], v[198:201], v[238:241], v[68:71]
	v_mfma_f32_16x16x32_bf16 v[64:67], v[206:209], v[238:241], v[64:67]
	s_setprio 0
	s_barrier
	s_sleep 2
	s_add_i32 s95, s84, s3
	v_lshl_add_u64 v[150:151], s[60:61], 0, v[130:131]
	s_mov_b32 m0, s95
	ds_read_b128 v[210:213], v164 offset:16384
	ds_read_b128 v[214:217], v164 offset:17408
	ds_read_b128 v[218:221], v164 offset:18432
	ds_read_b128 v[222:225], v164 offset:19456
	ds_read_b128 v[226:229], v164 offset:20480
	ds_read_b128 v[230:233], v164 offset:21504
	ds_read_b128 v[234:237], v164 offset:22528
	ds_read_b128 v[238:241], v164 offset:23552
	global_load_lds_dwordx4 v[150:151], off
	s_add_i32 m0, s95, 0x2000
	s_add_u32 s96, s60, 0x80000
	v_lshl_add_u64 v[180:181], s[60:61], 0, v[134:135]
	s_addc_u32 s97, s61, 0
	s_add_i32 s95, s85, s3
	global_load_lds_dwordx4 v[180:181], off
	v_lshl_add_u64 v[188:189], s[96:97], 0, v[130:131]
	s_mov_b32 m0, s95
	v_lshl_add_u64 v[242:243], s[62:63], 0, v[132:133]
	global_load_lds_dwordx4 v[188:189], off
	v_lshl_add_u64 v[188:189], s[96:97], 0, v[134:135]
	s_add_i32 m0, s95, 0x2000
	s_nop 0
	global_load_lds_dwordx4 v[188:189], off
	v_lshl_add_u64 v[188:189], s[62:63], 0, v[128:129]
	s_mov_b32 m0, s28
	s_nop 0
	global_load_lds_dwordx4 v[188:189], off
	s_mov_b32 m0, s29
	s_nop 0
	global_load_lds_dwordx4 v[242:243], off
	s_waitcnt vmcnt(8)
	s_waitcnt lgkmcnt(0)
	s_barrier
; #define PG8_STAGE(bufoff, gbase, voff) do { _Pragma("unroll") for (int _i = 0; _i < 2; ++_i) \
;         __builtin_amdgcn_global_load_lds((const unsigned*)((const char*)(gbase) + (voff)[_i]), (PG8_LAS unsigned*)(lds + (bufoff) + ldsw + _i * 8192), 16, 0, 0); } while (0)
; #define PG8_LDA(dst, b, h) do { _Pragma("unroll") for (int m = 0; m < 4; ++m) _Pragma("unroll") for (int k = 0; k < 2; ++k) dst[m][k] = *(const PG8_LAS bf16x8*)(lds + PG8_SA(b, h) + aoff + m * 2048 + k * 1024); } while (0)
; #define PG8_LDB(dst, b, h) do { _Pragma("unroll") for (int n = 0; n < 2; ++n) _Pragma("unroll") for (int k = 0; k < 2; ++k) dst[n][k] = *(const PG8_LAS bf16x8*)(lds + PG8_SB(b, h) + boff + n * 2048 + k * 1024); } while (0)
; #define PG8_MMA(ai, bj, At, Bt) do { __builtin_amdgcn_s_setprio(1); _Pragma("unroll") for (int m = 0; m < 4; ++m) _Pragma("unroll") for (int n = 0; n < 2; ++n) _Pragma("unroll") for (int k = 0; k < 2; ++k) \
;         acc[ai][bj][m][n] = __builtin_amdgcn_mfma_f32_16x16x32_bf16(Bt[n][k], At[m][k], acc[ai][bj][m][n], 0, 0, 0); __builtin_amdgcn_s_setprio(0); } while (0)
; #define PG8_BAR __builtin_amdgcn_s_barrier()
; template <class Epi, class Sched, bool ALIGN_EPI = false, bool SP2 = false>
; __device__ __forceinline__ void gemm_phase(PG8_LAS unsigned char* lds, const Gemm g, const Sched& S, const Epi& E) {
;     ...
;             if constexpr (SP2) {
;             PG8_LDB(B0, 0, 0); PG8_LDB(B1, 0, 1); PG8_SCHED; PG8_LDA(At, 0, 0); PG8_STAGE(PG8_SA(1, 1), a1 + hstep, voffA);
;             PG8_WAIT_V(8); PG8_WAIT_L(0); PG8_BAR; PG8_MMA(0, 0, At, B0); PG8_MMA(0, 1, At, B1); PG8_BAR; PG8_SCHED;
;             PG8_LDA(At, 0, 1); PG8_STAGE(PG8_SB(0, 0), b2, voffB); PG8_STAGE(PG8_SB(0, 1), b2 + hstep, voffB); PG8_STAGE(PG8_SA(0, 0), a2, voffA);
;             PG8_WAIT_V(8); PG8_WAIT_L(0); PG8_BAR; PG8_MMA(1, 0, At, B0); PG8_MMA(1, 1, At, B1); PG8_BAR; PG8_SCHED;
;             PG8_LDB(B0, 1, 0); PG8_LDB(B1, 1, 1); PG8_SCHED; PG8_LDA(At, 1, 0); PG8_STAGE(PG8_SA(0, 1), a2 + hstep, voffA);
;             PG8_WAIT_V(8); PG8_WAIT_L(0); PG8_BAR; PG8_MMA(0, 0, At, B0); PG8_MMA(0, 1, At, B1); PG8_BAR; PG8_SCHED;
;             PG8_LDA(At, 1, 1); PG8_STAGE(PG8_SB(1, 0), b3, voffB); PG8_STAGE(PG8_SB(1, 1), b3 + hstep, voffB); PG8_STAGE(PG8_SA(1, 0), a3, voffA);
;             PG8_WAIT_V(8); PG8_WAIT_L(0); PG8_BAR; PG8_MMA(1, 0, At, B0); PG8_MMA(1, 1, At, B1); PG8_BAR; PG8_SCHED;
	s_setprio 1
	s_waitcnt lgkmcnt(0)
	v_mfma_f32_16x16x32_bf16 v[60:63], v[146:149], v[210:213], v[60:63]
	v_mfma_f32_16x16x32_bf16 v[56:59], v[176:179], v[210:213], v[56:59]
	v_mfma_f32_16x16x32_bf16 v[44:47], v[146:149], v[218:221], v[44:47]
	v_mfma_f32_16x16x32_bf16 v[40:43], v[176:179], v[218:221], v[40:43]
	v_mfma_f32_16x16x32_bf16 v[28:31], v[146:149], v[226:229], v[28:31]
	v_mfma_f32_16x16x32_bf16 v[24:27], v[176:179], v[226:229], v[24:27]
	v_mfma_f32_16x16x32_bf16 v[12:15], v[146:149], v[234:237], v[12:15]
	v_mfma_f32_16x16x32_bf16 v[8:11], v[176:179], v[234:237], v[8:11]
	v_mfma_f32_16x16x32_bf16 v[60:63], v[172:175], v[214:217], v[60:63]
	v_mfma_f32_16x16x32_bf16 v[56:59], v[190:193], v[214:217], v[56:59]
	v_mfma_f32_16x16x32_bf16 v[44:47], v[172:175], v[222:225], v[44:47]
	v_mfma_f32_16x16x32_bf16 v[40:43], v[190:193], v[222:225], v[40:43]
	v_mfma_f32_16x16x32_bf16 v[28:31], v[172:175], v[230:233], v[28:31]
	v_mfma_f32_16x16x32_bf16 v[24:27], v[190:193], v[230:233], v[24:27]
	v_mfma_f32_16x16x32_bf16 v[12:15], v[172:175], v[238:241], v[12:15]
	v_mfma_f32_16x16x32_bf16 v[8:11], v[190:193], v[238:241], v[8:11]
	s_setprio 0
	s_setprio 1
	v_mfma_f32_16x16x32_bf16 v[52:55], v[194:197], v[210:213], v[52:55]
	v_mfma_f32_16x16x32_bf16 v[48:51], v[202:205], v[210:213], v[48:51]
	v_mfma_f32_16x16x32_bf16 v[36:39], v[194:197], v[218:221], v[36:39]
	v_mfma_f32_16x16x32_bf16 v[32:35], v[202:205], v[218:221], v[32:35]
	v_mfma_f32_16x16x32_bf16 v[20:23], v[194:197], v[226:229], v[20:23]
	v_mfma_f32_16x16x32_bf16 v[16:19], v[202:205], v[226:229], v[16:19]
	v_mfma_f32_16x16x32_bf16 v[4:7], v[194:197], v[234:237], v[4:7]
	v_mfma_f32_16x16x32_bf16 v[0:3], v[202:205], v[234:237], v[0:3]
	v_mfma_f32_16x16x32_bf16 v[52:55], v[198:201], v[214:217], v[52:55]
	v_mfma_f32_16x16x32_bf16 v[48:51], v[206:209], v[214:217], v[48:51]
	v_mfma_f32_16x16x32_bf16 v[36:39], v[198:201], v[222:225], v[36:39]
	v_mfma_f32_16x16x32_bf16 v[32:35], v[206:209], v[222:225], v[32:35]
	v_mfma_f32_16x16x32_bf16 v[20:23], v[198:201], v[230:233], v[20:23]
	v_mfma_f32_16x16x32_bf16 v[16:19], v[206:209], v[230:233], v[16:19]
	v_mfma_f32_16x16x32_bf16 v[4:7], v[198:201], v[238:241], v[4:7]
	v_mfma_f32_16x16x32_bf16 v[0:3], v[206:209], v[238:241], v[0:3]
	s_setprio 0
	s_barrier
	s_sleep 2
	s_add_i32 s95, 0, 0x18000
	v_add_u32_e32 v171, s95, v160
	s_add_i32 s96, 0, 0x1c000
	ds_read_b128 v[146:149], v171
	ds_read_b128 v[172:175], v171 offset:1024
	ds_read_b128 v[176:179], v171 offset:2048
	ds_read_b128 v[190:193], v171 offset:3072
	v_add_u32_e32 v171, s96, v160
	ds_read_b128 v[194:197], v171
	ds_read_b128 v[198:201], v171 offset:1024
	ds_read_b128 v[202:205], v171 offset:2048
	ds_read_b128 v[206:209], v171 offset:3072
	s_add_u32 s62, s62, 0x80000
	s_addc_u32 s63, s63, 0
	s_mov_b32 m0, s34
	v_lshl_add_u64 v[244:245], s[62:63], 0, v[128:129]
	ds_read_b128 v[210:213], v164 offset:32768
	ds_read_b128 v[214:217], v164 offset:33792
	ds_read_b128 v[218:221], v164 offset:34816
	ds_read_b128 v[222:225], v164 offset:35840
	ds_read_b128 v[226:229], v164 offset:36864
	ds_read_b128 v[230:233], v164 offset:37888
	ds_read_b128 v[234:237], v164 offset:38912
	ds_read_b128 v[238:241], v164 offset:39936
	global_load_lds_dwordx4 v[244:245], off
	v_lshl_add_u64 v[244:245], s[62:63], 0, v[132:133]
	s_mov_b32 m0, s35
	s_nop 0
	global_load_lds_dwordx4 v[244:245], off
	s_waitcnt vmcnt(8)
	s_waitcnt lgkmcnt(0)
	s_barrier
	s_setprio 1
	s_waitcnt lgkmcnt(0)
	v_mfma_f32_16x16x32_bf16 v[124:127], v[146:149], v[210:213], v[124:127]
	v_mfma_f32_16x16x32_bf16 v[120:123], v[176:179], v[210:213], v[120:123]
	v_mfma_f32_16x16x32_bf16 v[108:111], v[146:149], v[218:221], v[108:111]
	v_mfma_f32_16x16x32_bf16 v[104:107], v[176:179], v[218:221], v[104:107]
	v_mfma_f32_16x16x32_bf16 v[92:95], v[146:149], v[226:229], v[92:95]
	v_mfma_f32_16x16x32_bf16 v[88:91], v[176:179], v[226:229], v[88:91]
	v_mfma_f32_16x16x32_bf16 v[76:79], v[146:149], v[234:237], v[76:79]
	v_mfma_f32_16x16x32_bf16 v[72:75], v[176:179], v[234:237], v[72:75]
	v_mfma_f32_16x16x32_bf16 v[124:127], v[172:175], v[214:217], v[124:127]
	v_mfma_f32_16x16x32_bf16 v[120:123], v[190:193], v[214:217], v[120:123]
	v_mfma_f32_16x16x32_bf16 v[108:111], v[172:175], v[222:225], v[108:111]
	v_mfma_f32_16x16x32_bf16 v[104:107], v[190:193], v[222:225], v[104:107]
	v_mfma_f32_16x16x32_bf16 v[92:95], v[172:175], v[230:233], v[92:95]
	v_mfma_f32_16x16x32_bf16 v[88:91], v[190:193], v[230:233], v[88:91]
	v_mfma_f32_16x16x32_bf16 v[76:79], v[172:175], v[238:241], v[76:79]
	v_mfma_f32_16x16x32_bf16 v[72:75], v[190:193], v[238:241], v[72:75]
	s_setprio 0
	s_setprio 1
	v_mfma_f32_16x16x32_bf16 v[116:119], v[194:197], v[210:213], v[116:119]
	v_mfma_f32_16x16x32_bf16 v[112:115], v[202:205], v[210:213], v[112:115]
	v_mfma_f32_16x16x32_bf16 v[100:103], v[194:197], v[218:221], v[100:103]
	v_mfma_f32_16x16x32_bf16 v[96:99], v[202:205], v[218:221], v[96:99]
	v_mfma_f32_16x16x32_bf16 v[84:87], v[194:197], v[226:229], v[84:87]
	v_mfma_f32_16x16x32_bf16 v[80:83], v[202:205], v[226:229], v[80:83]
	v_mfma_f32_16x16x32_bf16 v[68:71], v[194:197], v[234:237], v[68:71]
	v_mfma_f32_16x16x32_bf16 v[64:67], v[202:205], v[234:237], v[64:67]
	v_mfma_f32_16x16x32_bf16 v[116:119], v[198:201], v[214:217], v[116:119]
	v_mfma_f32_16x16x32_bf16 v[112:115], v[206:209], v[214:217], v[112:115]
	v_mfma_f32_16x16x32_bf16 v[100:103], v[198:201], v[222:225], v[100:103]
	v_mfma_f32_16x16x32_bf16 v[96:99], v[206:209], v[222:225], v[96:99]
	v_mfma_f32_16x16x32_bf16 v[84:87], v[198:201], v[230:233], v[84:87]
	v_mfma_f32_16x16x32_bf16 v[80:83], v[206:209], v[230:233], v[80:83]
	v_mfma_f32_16x16x32_bf16 v[68:71], v[198:201], v[238:241], v[68:71]
	v_mfma_f32_16x16x32_bf16 v[64:67], v[206:209], v[238:241], v[64:67]
	s_setprio 0
	s_barrier
; #define PG8_STAGE(bufoff, gbase, voff) do { _Pragma("unroll") for (int _i = 0; _i < 2; ++_i) \
;         __builtin_amdgcn_global_load_lds((const unsigned*)((const char*)(gbase) + (voff)[_i]), (PG8_LAS unsigned*)(lds + (bufoff) + ldsw + _i * 8192), 16, 0, 0); } while (0)
; #define PG8_LDA(dst, b, h) do { _Pragma("unroll") for (int m = 0; m < 4; ++m) _Pragma("unroll") for (int k = 0; k < 2; ++k) dst[m][k] = *(const PG8_LAS bf16x8*)(lds + PG8_SA(b, h) + aoff + m * 2048 + k * 1024); } while (0)
; #define PG8_LDB(dst, b, h) do { _Pragma("unroll") for (int n = 0; n < 2; ++n) _Pragma("unroll") for (int k = 0; k < 2; ++k) dst[n][k] = *(const PG8_LAS bf16x8*)(lds + PG8_SB(b, h) + boff + n * 2048 + k * 1024); } while (0)
; #define PG8_MMA(ai, bj, At, Bt) do { __builtin_amdgcn_s_setprio(1); _Pragma("unroll") for (int m = 0; m < 4; ++m) _Pragma("unroll") for (int n = 0; n < 2; ++n) _Pragma("unroll") for (int k = 0; k < 2; ++k) \
;         acc[ai][bj][m][n] = __builtin_amdgcn_mfma_f32_16x16x32_bf16(Bt[n][k], At[m][k], acc[ai][bj][m][n], 0, 0, 0); __builtin_amdgcn_s_setprio(0); } while (0)
; template <class Epi, class Sched, bool ALIGN_EPI = false, bool SP2 = false>
; __device__ __forceinline__ void gemm_phase(PG8_LAS unsigned char* lds, const Gemm g, const Sched& S, const Epi& E) {
;     ...
;         for (int t = 0; t < nt; t += 2) {
;     ...
;             if constexpr (SP2) {
;             PG8_LDB(B0, 0, 0); PG8_LDB(B1, 0, 1); PG8_SCHED; PG8_LDA(At, 0, 0); PG8_STAGE(PG8_SA(1, 1), a1 + hstep, voffA);
;             PG8_WAIT_V(8); PG8_WAIT_L(0); PG8_BAR; PG8_MMA(0, 0, At, B0); PG8_MMA(0, 1, At, B1); PG8_BAR; PG8_SCHED;
;             PG8_LDA(At, 0, 1); PG8_STAGE(PG8_SB(0, 0), b2, voffB); PG8_STAGE(PG8_SB(0, 1), b2 + hstep, voffB); PG8_STAGE(PG8_SA(0, 0), a2, voffA);
;             PG8_WAIT_V(8); PG8_WAIT_L(0); PG8_BAR; PG8_MMA(1, 0, At, B0); PG8_MMA(1, 1, At, B1); PG8_BAR; PG8_SCHED;
;             PG8_LDB(B0, 1, 0); PG8_LDB(B1, 1, 1); PG8_SCHED; PG8_LDA(At, 1, 0); PG8_STAGE(PG8_SA(0, 1), a2 + hstep, voffA);
;             PG8_WAIT_V(8); PG8_WAIT_L(0); PG8_BAR; PG8_MMA(0, 0, At, B0); PG8_MMA(0, 1, At, B1); PG8_BAR; PG8_SCHED;
;             PG8_LDA(At, 1, 1); PG8_STAGE(PG8_SB(1, 0), b3, voffB); PG8_STAGE(PG8_SB(1, 1), b3 + hstep, voffB); PG8_STAGE(PG8_SA(1, 0), a3, voffA);
;             PG8_WAIT_V(8); PG8_WAIT_L(0); PG8_BAR; PG8_MMA(1, 0, At, B0); PG8_MMA(1, 1, At, B1); PG8_BAR; PG8_SCHED;
	s_sleep 2
	s_add_i32 s62, s95, s3
	v_lshl_add_u64 v[150:151], v[150:151], 0, s[36:37]
	s_mov_b32 m0, s62
	ds_read_b128 v[210:213], v164 offset:49152
	ds_read_b128 v[214:217], v164 offset:50176
	ds_read_b128 v[218:221], v164 offset:51200
	ds_read_b128 v[222:225], v164 offset:52224
	ds_read_b128 v[226:229], v164 offset:53248
	ds_read_b128 v[230:233], v164 offset:54272
	ds_read_b128 v[234:237], v164 offset:55296
	ds_read_b128 v[238:241], v164 offset:56320
	global_load_lds_dwordx4 v[150:151], off
	s_add_i32 m0, s62, 0x2000
	s_add_u32 s60, s60, 0x80080
	v_lshl_add_u64 v[150:151], v[180:181], 0, s[36:37]
	s_addc_u32 s61, s61, 0
	s_add_i32 s62, s96, s3
	global_load_lds_dwordx4 v[150:151], off
	v_lshl_add_u64 v[150:151], s[60:61], 0, v[130:131]
	s_mov_b32 m0, s62
	s_nop 0
	global_load_lds_dwordx4 v[150:151], off
	v_lshl_add_u64 v[150:151], s[60:61], 0, v[134:135]
	s_add_i32 m0, s62, 0x2000
	s_nop 0
	global_load_lds_dwordx4 v[150:151], off
	v_lshl_add_u64 v[150:151], v[188:189], 0, s[36:37]
	s_mov_b32 m0, s65
	s_nop 0
	global_load_lds_dwordx4 v[150:151], off
	v_lshl_add_u64 v[150:151], v[242:243], 0, s[36:37]
	s_mov_b32 m0, s66
	s_nop 0
	global_load_lds_dwordx4 v[150:151], off
	s_waitcnt vmcnt(8)
	s_waitcnt lgkmcnt(0)
	s_barrier
	s_setprio 1
	s_waitcnt lgkmcnt(0)
	v_mfma_f32_16x16x32_bf16 v[60:63], v[146:149], v[210:213], v[60:63]
	v_mfma_f32_16x16x32_bf16 v[56:59], v[176:179], v[210:213], v[56:59]
	v_mfma_f32_16x16x32_bf16 v[44:47], v[146:149], v[218:221], v[44:47]
	v_mfma_f32_16x16x32_bf16 v[40:43], v[176:179], v[218:221], v[40:43]
	v_mfma_f32_16x16x32_bf16 v[28:31], v[146:149], v[226:229], v[28:31]
	v_mfma_f32_16x16x32_bf16 v[24:27], v[176:179], v[226:229], v[24:27]
	v_mfma_f32_16x16x32_bf16 v[12:15], v[146:149], v[234:237], v[12:15]
	v_mfma_f32_16x16x32_bf16 v[8:11], v[176:179], v[234:237], v[8:11]
	v_mfma_f32_16x16x32_bf16 v[60:63], v[172:175], v[214:217], v[60:63]
	v_mfma_f32_16x16x32_bf16 v[56:59], v[190:193], v[214:217], v[56:59]
	v_mfma_f32_16x16x32_bf16 v[44:47], v[172:175], v[222:225], v[44:47]
	v_mfma_f32_16x16x32_bf16 v[40:43], v[190:193], v[222:225], v[40:43]
	v_mfma_f32_16x16x32_bf16 v[28:31], v[172:175], v[230:233], v[28:31]
	v_mfma_f32_16x16x32_bf16 v[24:27], v[190:193], v[230:233], v[24:27]
	v_mfma_f32_16x16x32_bf16 v[12:15], v[172:175], v[238:241], v[12:15]
	v_mfma_f32_16x16x32_bf16 v[8:11], v[190:193], v[238:241], v[8:11]
	s_setprio 0
	s_setprio 1
	v_mfma_f32_16x16x32_bf16 v[52:55], v[194:197], v[210:213], v[52:55]
	v_mfma_f32_16x16x32_bf16 v[48:51], v[202:205], v[210:213], v[48:51]
	v_mfma_f32_16x16x32_bf16 v[36:39], v[194:197], v[218:221], v[36:39]
	v_mfma_f32_16x16x32_bf16 v[32:35], v[202:205], v[218:221], v[32:35]
	v_mfma_f32_16x16x32_bf16 v[20:23], v[194:197], v[226:229], v[20:23]
	v_mfma_f32_16x16x32_bf16 v[16:19], v[202:205], v[226:229], v[16:19]
	v_mfma_f32_16x16x32_bf16 v[4:7], v[194:197], v[234:237], v[4:7]
	v_mfma_f32_16x16x32_bf16 v[0:3], v[202:205], v[234:237], v[0:3]
	v_mfma_f32_16x16x32_bf16 v[52:55], v[198:201], v[214:217], v[52:55]
	v_mfma_f32_16x16x32_bf16 v[48:51], v[206:209], v[214:217], v[48:51]
	v_mfma_f32_16x16x32_bf16 v[36:39], v[198:201], v[222:225], v[36:39]
	v_mfma_f32_16x16x32_bf16 v[32:35], v[206:209], v[222:225], v[32:35]
	v_mfma_f32_16x16x32_bf16 v[20:23], v[198:201], v[230:233], v[20:23]
	v_mfma_f32_16x16x32_bf16 v[16:19], v[206:209], v[230:233], v[16:19]
	v_mfma_f32_16x16x32_bf16 v[4:7], v[198:201], v[238:241], v[4:7]
	v_mfma_f32_16x16x32_bf16 v[0:3], v[206:209], v[238:241], v[0:3]
	s_setprio 0
	s_barrier
	s_sleep 2
	s_add_i32 s94, s94, 2
	s_add_u32 s58, s58, 0x100
	s_addc_u32 s59, s59, 0
	s_add_u32 s92, s92, 0x100
	s_addc_u32 s93, s93, 0
	s_cmp_gt_u32 s94, 29
	s_cbranch_scc0 .LBB0_199
	s_and_b64 vcc, exec, s[38:39]
	s_cbranch_vccz .LBB0_202
	s_barrier

; #define PG8_STAGE(bufoff, gbase, voff) do { _Pragma("unroll") for (int _i = 0; _i < 2; ++_i) \
;         __builtin_amdgcn_global_load_lds((const unsigned*)((const char*)(gbase) + (voff)[_i]), (PG8_LAS unsigned*)(lds + (bufoff) + ldsw + _i * 8192), 16, 0, 0); } while (0)
; #define PG8_LDA(dst, b, h) do { _Pragma("unroll") for (int m = 0; m < 4; ++m) _Pragma("unroll") for (int k = 0; k < 2; ++k) dst[m][k] = *(const PG8_LAS bf16x8*)(lds + PG8_SA(b, h) + aoff + m * 2048 + k * 1024); } while (0)
; #define PG8_LDB(dst, b, h) do { _Pragma("unroll") for (int n = 0; n < 2; ++n) _Pragma("unroll") for (int k = 0; k < 2; ++k) dst[n][k] = *(const PG8_LAS bf16x8*)(lds + PG8_SB(b, h) + boff + n * 2048 + k * 1024); } while (0)
; template <class Epi, class Sched, bool ALIGN_EPI = false, bool SP2 = false>
; __device__ __forceinline__ void gemm_phase(PG8_LAS unsigned char* lds, const Gemm g, const Sched& S, const Epi& E) {
;     ...
;         for (int t = 0; t < nt; t += 2) {
;             const bool last = (t == nt - 2);
;             const char* a1 = cA + (size_t)(t + 1) * kstep;
;             const char* a2 = last ? nA : cA + (size_t)(t + 2) * kstep; const char* b2 = last ? nB : cB + (size_t)(t + 2) * kstep;
;             const char* a3 = a2 + kstep; const char* b3 = b2 + kstep;
;             if (last && has_next) S.a_ready(nxt);
;             if constexpr (SP2) {
;             PG8_LDB(B0, 0, 0); PG8_LDB(B1, 0, 1); PG8_SCHED; PG8_LDA(At, 0, 0); PG8_STAGE(PG8_SA(1, 1), a1 + hstep, voffA);
;             PG8_WAIT_V(8); PG8_WAIT_L(0); PG8_BAR; PG8_MMA(0, 0, At, B0); PG8_MMA(0, 1, At, B1); PG8_BAR; PG8_SCHED;
;             PG8_LDA(At, 0, 1); PG8_STAGE(PG8_SB(0, 0), b2, voffB); PG8_STAGE(PG8_SB(0, 1), b2 + hstep, voffB); PG8_STAGE(PG8_SA(0, 0), a2, voffA);
;             PG8_WAIT_V(8); PG8_WAIT_L(0); PG8_BAR; PG8_MMA(1, 0, At, B0); PG8_MMA(1, 1, At, B1); PG8_BAR; PG8_SCHED;
;             PG8_LDB(B0, 1, 0); PG8_LDB(B1, 1, 1); PG8_SCHED; PG8_LDA(At, 1, 0); PG8_STAGE(PG8_SA(0, 1), a2 + hstep, voffA);
;             PG8_WAIT_V(8); PG8_WAIT_L(0); PG8_BAR; PG8_MMA(0, 0, At, B0); PG8_MMA(0, 1, At, B1); PG8_BAR; PG8_SCHED;
;             PG8_LDA(At, 1, 1); PG8_STAGE(PG8_SB(1, 0), b3, voffB); PG8_STAGE(PG8_SB(1, 1), b3 + hstep, voffB); PG8_STAGE(PG8_SA(1, 0), a3, voffA);
;             PG8_WAIT_V(8); PG8_WAIT_L(0); PG8_BAR; PG8_MMA(1, 0, At, B0); PG8_MMA(1, 1, At, B1); PG8_BAR; PG8_SCHED;
.LBB0_251:
	ds_read_b128 v[146:149], v152
	ds_read_b128 v[156:159], v152 offset:1024
	ds_read_b128 v[160:163], v152 offset:2048
	ds_read_b128 v[164:167], v152 offset:3072
	ds_read_b128 v[168:171], v154
	ds_read_b128 v[172:175], v154 offset:1024
	ds_read_b128 v[176:179], v154 offset:2048
	ds_read_b128 v[190:193], v154 offset:3072
	s_add_u32 s46, s44, 0xfff80080
	s_addc_u32 s47, s45, -1
	s_cmp_eq_u32 s82, 28
	s_cselect_b32 s49, s37, s47
	s_cselect_b32 s48, s77, s46
	s_cselect_b32 s47, s13, s81
	s_cselect_b32 s46, s79, s80
	v_lshl_add_u64 v[180:181], s[44:45], 0, v[136:137]
	s_add_i32 m0, s35, 0xc000
	ds_read_b128 v[194:197], v155
	ds_read_b128 v[198:201], v155 offset:1024
	ds_read_b128 v[202:205], v155 offset:2048
	ds_read_b128 v[206:209], v155 offset:3072
	ds_read_b128 v[210:213], v155 offset:4096
	ds_read_b128 v[214:217], v155 offset:5120
	ds_read_b128 v[218:221], v155 offset:6144
	ds_read_b128 v[222:225], v155 offset:7168
	global_load_lds_dwordx4 v[180:181], off
	v_lshl_add_u64 v[180:181], s[44:45], 0, v[138:139]
	s_add_i32 m0, s35, 0xe000
	s_nop 0
	global_load_lds_dwordx4 v[180:181], off
	s_waitcnt vmcnt(8)
	s_waitcnt lgkmcnt(0)
	s_barrier
	s_setprio 1
	s_waitcnt lgkmcnt(0)
	v_mfma_f32_16x16x32_bf16 v[124:127], v[146:149], v[194:197], v[124:127]
	v_mfma_f32_16x16x32_bf16 v[120:123], v[160:163], v[194:197], v[120:123]
	v_mfma_f32_16x16x32_bf16 v[116:119], v[146:149], v[202:205], v[116:119]
	v_mfma_f32_16x16x32_bf16 v[108:111], v[160:163], v[202:205], v[108:111]
	v_mfma_f32_16x16x32_bf16 v[100:103], v[146:149], v[210:213], v[100:103]
	v_mfma_f32_16x16x32_bf16 v[92:95], v[160:163], v[210:213], v[92:95]
	v_mfma_f32_16x16x32_bf16 v[84:87], v[146:149], v[218:221], v[84:87]
	v_mfma_f32_16x16x32_bf16 v[76:79], v[160:163], v[218:221], v[76:79]
	v_mfma_f32_16x16x32_bf16 v[124:127], v[156:159], v[198:201], v[124:127]
	v_mfma_f32_16x16x32_bf16 v[120:123], v[164:167], v[198:201], v[120:123]
	v_mfma_f32_16x16x32_bf16 v[116:119], v[156:159], v[206:209], v[116:119]
	v_mfma_f32_16x16x32_bf16 v[108:111], v[164:167], v[206:209], v[108:111]
	v_mfma_f32_16x16x32_bf16 v[100:103], v[156:159], v[214:217], v[100:103]
	v_mfma_f32_16x16x32_bf16 v[92:95], v[164:167], v[214:217], v[92:95]
	v_mfma_f32_16x16x32_bf16 v[84:87], v[156:159], v[222:225], v[84:87]
	v_mfma_f32_16x16x32_bf16 v[76:79], v[164:167], v[222:225], v[76:79]
	s_setprio 0
	s_setprio 1
	v_mfma_f32_16x16x32_bf16 v[112:115], v[168:171], v[194:197], v[112:115]
	v_mfma_f32_16x16x32_bf16 v[104:107], v[176:179], v[194:197], v[104:107]
	v_mfma_f32_16x16x32_bf16 v[96:99], v[168:171], v[202:205], v[96:99]
	v_mfma_f32_16x16x32_bf16 v[88:91], v[176:179], v[202:205], v[88:91]
	v_mfma_f32_16x16x32_bf16 v[80:83], v[168:171], v[210:213], v[80:83]
	v_mfma_f32_16x16x32_bf16 v[72:75], v[176:179], v[210:213], v[72:75]
	v_mfma_f32_16x16x32_bf16 v[68:71], v[168:171], v[218:221], v[68:71]
	v_mfma_f32_16x16x32_bf16 v[64:67], v[176:179], v[218:221], v[64:67]
	v_mfma_f32_16x16x32_bf16 v[112:115], v[172:175], v[198:201], v[112:115]
	v_mfma_f32_16x16x32_bf16 v[104:107], v[190:193], v[198:201], v[104:107]
	v_mfma_f32_16x16x32_bf16 v[96:99], v[172:175], v[206:209], v[96:99]
	v_mfma_f32_16x16x32_bf16 v[88:91], v[190:193], v[206:209], v[88:91]
	v_mfma_f32_16x16x32_bf16 v[80:83], v[172:175], v[214:217], v[80:83]
	v_mfma_f32_16x16x32_bf16 v[72:75], v[190:193], v[214:217], v[72:75]
	v_mfma_f32_16x16x32_bf16 v[68:71], v[172:175], v[222:225], v[68:71]
	v_mfma_f32_16x16x32_bf16 v[64:67], v[190:193], v[222:225], v[64:67]
	s_setprio 0
	s_barrier
	s_sleep 2
	s_add_i32 s83, s65, s29
	v_lshl_add_u64 v[180:181], s[46:47], 0, v[130:131]
	s_mov_b32 m0, s83
	ds_read_b128 v[194:197], v155 offset:16384
	ds_read_b128 v[198:201], v155 offset:17408
	ds_read_b128 v[202:205], v155 offset:18432
	ds_read_b128 v[206:209], v155 offset:19456
	ds_read_b128 v[210:213], v155 offset:20480
	ds_read_b128 v[214:217], v155 offset:21504
	ds_read_b128 v[218:221], v155 offset:22528
	ds_read_b128 v[222:225], v155 offset:23552
	global_load_lds_dwordx4 v[180:181], off
	s_add_i32 m0, s83, 0x2000
	s_add_u32 s84, s46, 0x80000
	v_lshl_add_u64 v[188:189], s[46:47], 0, v[134:135]
	s_addc_u32 s85, s47, 0
	s_add_i32 s83, s66, s29
	global_load_lds_dwordx4 v[188:189], off
	v_lshl_add_u64 v[226:227], s[84:85], 0, v[130:131]
	s_mov_b32 m0, s83
	v_lshl_add_u64 v[228:229], s[48:49], 0, v[132:133]
	global_load_lds_dwordx4 v[226:227], off
	v_lshl_add_u64 v[226:227], s[84:85], 0, v[134:135]
	s_add_i32 m0, s83, 0x2000
	s_nop 0
	global_load_lds_dwordx4 v[226:227], off
	v_lshl_add_u64 v[226:227], s[48:49], 0, v[128:129]
	s_mov_b32 m0, s35
	s_nop 0
	global_load_lds_dwordx4 v[226:227], off
	s_mov_b32 m0, s43
	s_nop 0
	global_load_lds_dwordx4 v[228:229], off
	s_waitcnt vmcnt(8)
	s_waitcnt lgkmcnt(0)
	s_barrier
; #define PG8_STAGE(bufoff, gbase, voff) do { _Pragma("unroll") for (int _i = 0; _i < 2; ++_i) \
;         __builtin_amdgcn_global_load_lds((const unsigned*)((const char*)(gbase) + (voff)[_i]), (PG8_LAS unsigned*)(lds + (bufoff) + ldsw + _i * 8192), 16, 0, 0); } while (0)
; #define PG8_LDA(dst, b, h) do { _Pragma("unroll") for (int m = 0; m < 4; ++m) _Pragma("unroll") for (int k = 0; k < 2; ++k) dst[m][k] = *(const PG8_LAS bf16x8*)(lds + PG8_SA(b, h) + aoff + m * 2048 + k * 1024); } while (0)
; #define PG8_LDB(dst, b, h) do { _Pragma("unroll") for (int n = 0; n < 2; ++n) _Pragma("unroll") for (int k = 0; k < 2; ++k) dst[n][k] = *(const PG8_LAS bf16x8*)(lds + PG8_SB(b, h) + boff + n * 2048 + k * 1024); } while (0)
; #define PG8_MMA(ai, bj, At, Bt) do { __builtin_amdgcn_s_setprio(1); _Pragma("unroll") for (int m = 0; m < 4; ++m) _Pragma("unroll") for (int n = 0; n < 2; ++n) _Pragma("unroll") for (int k = 0; k < 2; ++k) \
;         acc[ai][bj][m][n] = __builtin_amdgcn_mfma_f32_16x16x32_bf16(Bt[n][k], At[m][k], acc[ai][bj][m][n], 0, 0, 0); __builtin_amdgcn_s_setprio(0); } while (0)
; #define PG8_BAR __builtin_amdgcn_s_barrier()
; template <class Epi, class Sched, bool ALIGN_EPI = false, bool SP2 = false>
; __device__ __forceinline__ void gemm_phase(PG8_LAS unsigned char* lds, const Gemm g, const Sched& S, const Epi& E) {
;     ...
;             if constexpr (SP2) {
;             PG8_LDB(B0, 0, 0); PG8_LDB(B1, 0, 1); PG8_SCHED; PG8_LDA(At, 0, 0); PG8_STAGE(PG8_SA(1, 1), a1 + hstep, voffA);
;             PG8_WAIT_V(8); PG8_WAIT_L(0); PG8_BAR; PG8_MMA(0, 0, At, B0); PG8_MMA(0, 1, At, B1); PG8_BAR; PG8_SCHED;
;             PG8_LDA(At, 0, 1); PG8_STAGE(PG8_SB(0, 0), b2, voffB); PG8_STAGE(PG8_SB(0, 1), b2 + hstep, voffB); PG8_STAGE(PG8_SA(0, 0), a2, voffA);
;             PG8_WAIT_V(8); PG8_WAIT_L(0); PG8_BAR; PG8_MMA(1, 0, At, B0); PG8_MMA(1, 1, At, B1); PG8_BAR; PG8_SCHED;
;             PG8_LDB(B0, 1, 0); PG8_LDB(B1, 1, 1); PG8_SCHED; PG8_LDA(At, 1, 0); PG8_STAGE(PG8_SA(0, 1), a2 + hstep, voffA);
;             PG8_WAIT_V(8); PG8_WAIT_L(0); PG8_BAR; PG8_MMA(0, 0, At, B0); PG8_MMA(0, 1, At, B1); PG8_BAR; PG8_SCHED;
;             PG8_LDA(At, 1, 1); PG8_STAGE(PG8_SB(1, 0), b3, voffB); PG8_STAGE(PG8_SB(1, 1), b3 + hstep, voffB); PG8_STAGE(PG8_SA(1, 0), a3, voffA);
;             PG8_WAIT_V(8); PG8_WAIT_L(0); PG8_BAR; PG8_MMA(1, 0, At, B0); PG8_MMA(1, 1, At, B1); PG8_BAR; PG8_SCHED;
	s_setprio 1
	s_waitcnt lgkmcnt(0)
	v_mfma_f32_16x16x32_bf16 v[60:63], v[146:149], v[194:197], v[60:63]
	v_mfma_f32_16x16x32_bf16 v[56:59], v[160:163], v[194:197], v[56:59]
	v_mfma_f32_16x16x32_bf16 v[52:55], v[146:149], v[202:205], v[52:55]
	v_mfma_f32_16x16x32_bf16 v[44:47], v[160:163], v[202:205], v[44:47]
	v_mfma_f32_16x16x32_bf16 v[36:39], v[146:149], v[210:213], v[36:39]
	v_mfma_f32_16x16x32_bf16 v[28:31], v[160:163], v[210:213], v[28:31]
	v_mfma_f32_16x16x32_bf16 v[20:23], v[146:149], v[218:221], v[20:23]
	v_mfma_f32_16x16x32_bf16 v[12:15], v[160:163], v[218:221], v[12:15]
	v_mfma_f32_16x16x32_bf16 v[60:63], v[156:159], v[198:201], v[60:63]
	v_mfma_f32_16x16x32_bf16 v[56:59], v[164:167], v[198:201], v[56:59]
	v_mfma_f32_16x16x32_bf16 v[52:55], v[156:159], v[206:209], v[52:55]
	v_mfma_f32_16x16x32_bf16 v[44:47], v[164:167], v[206:209], v[44:47]
	v_mfma_f32_16x16x32_bf16 v[36:39], v[156:159], v[214:217], v[36:39]
	v_mfma_f32_16x16x32_bf16 v[28:31], v[164:167], v[214:217], v[28:31]
	v_mfma_f32_16x16x32_bf16 v[20:23], v[156:159], v[222:225], v[20:23]
	v_mfma_f32_16x16x32_bf16 v[12:15], v[164:167], v[222:225], v[12:15]
	s_setprio 0
	s_setprio 1
	v_mfma_f32_16x16x32_bf16 v[48:51], v[168:171], v[194:197], v[48:51]
	v_mfma_f32_16x16x32_bf16 v[40:43], v[176:179], v[194:197], v[40:43]
	v_mfma_f32_16x16x32_bf16 v[32:35], v[168:171], v[202:205], v[32:35]
	v_mfma_f32_16x16x32_bf16 v[24:27], v[176:179], v[202:205], v[24:27]
	v_mfma_f32_16x16x32_bf16 v[16:19], v[168:171], v[210:213], v[16:19]
	v_mfma_f32_16x16x32_bf16 v[8:11], v[176:179], v[210:213], v[8:11]
	v_mfma_f32_16x16x32_bf16 v[4:7], v[168:171], v[218:221], v[4:7]
	v_mfma_f32_16x16x32_bf16 v[0:3], v[176:179], v[218:221], v[0:3]
	v_mfma_f32_16x16x32_bf16 v[48:51], v[172:175], v[198:201], v[48:51]
	v_mfma_f32_16x16x32_bf16 v[40:43], v[190:193], v[198:201], v[40:43]
	v_mfma_f32_16x16x32_bf16 v[32:35], v[172:175], v[206:209], v[32:35]
	v_mfma_f32_16x16x32_bf16 v[24:27], v[190:193], v[206:209], v[24:27]
	v_mfma_f32_16x16x32_bf16 v[16:19], v[172:175], v[214:217], v[16:19]
	v_mfma_f32_16x16x32_bf16 v[8:11], v[190:193], v[214:217], v[8:11]
	v_mfma_f32_16x16x32_bf16 v[4:7], v[172:175], v[222:225], v[4:7]
	v_mfma_f32_16x16x32_bf16 v[0:3], v[190:193], v[222:225], v[0:3]
	s_setprio 0
	s_barrier
	s_sleep 2
	s_add_i32 s83, 0, 0x18000
	s_add_i32 s84, 0, 0x1c000
	v_add_u32_e32 v164, s83, v151
	v_add_u32_e32 v190, s84, v151
	ds_read_b128 v[146:149], v164
	ds_read_b128 v[156:159], v164 offset:1024
	ds_read_b128 v[160:163], v164 offset:2048
	ds_read_b128 v[164:167], v164 offset:3072
	ds_read_b128 v[168:171], v190
	ds_read_b128 v[172:175], v190 offset:1024
	ds_read_b128 v[176:179], v190 offset:2048
	ds_read_b128 v[190:193], v190 offset:3072
	s_add_u32 s48, s48, 0x80000
	s_addc_u32 s49, s49, 0
	s_mov_b32 m0, s58
	v_lshl_add_u64 v[230:231], s[48:49], 0, v[128:129]
	ds_read_b128 v[194:197], v155 offset:32768
	ds_read_b128 v[198:201], v155 offset:33792
	ds_read_b128 v[202:205], v155 offset:34816
	ds_read_b128 v[206:209], v155 offset:35840
	ds_read_b128 v[210:213], v155 offset:36864
	ds_read_b128 v[214:217], v155 offset:37888
	ds_read_b128 v[218:221], v155 offset:38912
	ds_read_b128 v[222:225], v155 offset:39936
	global_load_lds_dwordx4 v[230:231], off
	v_lshl_add_u64 v[230:231], s[48:49], 0, v[132:133]
	s_mov_b32 m0, s59
	s_nop 0
	global_load_lds_dwordx4 v[230:231], off
	s_waitcnt vmcnt(8)
	s_waitcnt lgkmcnt(0)
	s_barrier
	s_setprio 1
	s_waitcnt lgkmcnt(0)
	v_mfma_f32_16x16x32_bf16 v[124:127], v[146:149], v[194:197], v[124:127]
	v_mfma_f32_16x16x32_bf16 v[120:123], v[160:163], v[194:197], v[120:123]
	v_mfma_f32_16x16x32_bf16 v[116:119], v[146:149], v[202:205], v[116:119]
	v_mfma_f32_16x16x32_bf16 v[108:111], v[160:163], v[202:205], v[108:111]
	v_mfma_f32_16x16x32_bf16 v[100:103], v[146:149], v[210:213], v[100:103]
	v_mfma_f32_16x16x32_bf16 v[92:95], v[160:163], v[210:213], v[92:95]
	v_mfma_f32_16x16x32_bf16 v[84:87], v[146:149], v[218:221], v[84:87]
	v_mfma_f32_16x16x32_bf16 v[76:79], v[160:163], v[218:221], v[76:79]
	v_mfma_f32_16x16x32_bf16 v[124:127], v[156:159], v[198:201], v[124:127]
	v_mfma_f32_16x16x32_bf16 v[120:123], v[164:167], v[198:201], v[120:123]
	v_mfma_f32_16x16x32_bf16 v[116:119], v[156:159], v[206:209], v[116:119]
	v_mfma_f32_16x16x32_bf16 v[108:111], v[164:167], v[206:209], v[108:111]
	v_mfma_f32_16x16x32_bf16 v[100:103], v[156:159], v[214:217], v[100:103]
	v_mfma_f32_16x16x32_bf16 v[92:95], v[164:167], v[214:217], v[92:95]
	v_mfma_f32_16x16x32_bf16 v[84:87], v[156:159], v[222:225], v[84:87]
	v_mfma_f32_16x16x32_bf16 v[76:79], v[164:167], v[222:225], v[76:79]
	s_setprio 0
	s_setprio 1
	v_mfma_f32_16x16x32_bf16 v[112:115], v[168:171], v[194:197], v[112:115]
	v_mfma_f32_16x16x32_bf16 v[104:107], v[176:179], v[194:197], v[104:107]
	v_mfma_f32_16x16x32_bf16 v[96:99], v[168:171], v[202:205], v[96:99]
	v_mfma_f32_16x16x32_bf16 v[88:91], v[176:179], v[202:205], v[88:91]
	v_mfma_f32_16x16x32_bf16 v[80:83], v[168:171], v[210:213], v[80:83]
	v_mfma_f32_16x16x32_bf16 v[72:75], v[176:179], v[210:213], v[72:75]
	v_mfma_f32_16x16x32_bf16 v[68:71], v[168:171], v[218:221], v[68:71]
	v_mfma_f32_16x16x32_bf16 v[64:67], v[176:179], v[218:221], v[64:67]
	v_mfma_f32_16x16x32_bf16 v[112:115], v[172:175], v[198:201], v[112:115]
	v_mfma_f32_16x16x32_bf16 v[104:107], v[190:193], v[198:201], v[104:107]
	v_mfma_f32_16x16x32_bf16 v[96:99], v[172:175], v[206:209], v[96:99]
	v_mfma_f32_16x16x32_bf16 v[88:91], v[190:193], v[206:209], v[88:91]
	v_mfma_f32_16x16x32_bf16 v[80:83], v[172:175], v[214:217], v[80:83]
	v_mfma_f32_16x16x32_bf16 v[72:75], v[190:193], v[214:217], v[72:75]
	v_mfma_f32_16x16x32_bf16 v[68:71], v[172:175], v[222:225], v[68:71]
	v_mfma_f32_16x16x32_bf16 v[64:67], v[190:193], v[222:225], v[64:67]
	s_setprio 0
	s_barrier
; #define PG8_STAGE(bufoff, gbase, voff) do { _Pragma("unroll") for (int _i = 0; _i < 2; ++_i) \
;         __builtin_amdgcn_global_load_lds((const unsigned*)((const char*)(gbase) + (voff)[_i]), (PG8_LAS unsigned*)(lds + (bufoff) + ldsw + _i * 8192), 16, 0, 0); } while (0)
; #define PG8_LDA(dst, b, h) do { _Pragma("unroll") for (int m = 0; m < 4; ++m) _Pragma("unroll") for (int k = 0; k < 2; ++k) dst[m][k] = *(const PG8_LAS bf16x8*)(lds + PG8_SA(b, h) + aoff + m * 2048 + k * 1024); } while (0)
; #define PG8_LDB(dst, b, h) do { _Pragma("unroll") for (int n = 0; n < 2; ++n) _Pragma("unroll") for (int k = 0; k < 2; ++k) dst[n][k] = *(const PG8_LAS bf16x8*)(lds + PG8_SB(b, h) + boff + n * 2048 + k * 1024); } while (0)
; #define PG8_MMA(ai, bj, At, Bt) do { __builtin_amdgcn_s_setprio(1); _Pragma("unroll") for (int m = 0; m < 4; ++m) _Pragma("unroll") for (int n = 0; n < 2; ++n) _Pragma("unroll") for (int k = 0; k < 2; ++k) \
;         acc[ai][bj][m][n] = __builtin_amdgcn_mfma_f32_16x16x32_bf16(Bt[n][k], At[m][k], acc[ai][bj][m][n], 0, 0, 0); __builtin_amdgcn_s_setprio(0); } while (0)
; template <class Epi, class Sched, bool ALIGN_EPI = false, bool SP2 = false>
; __device__ __forceinline__ void gemm_phase(PG8_LAS unsigned char* lds, const Gemm g, const Sched& S, const Epi& E) {
;     ...
;         for (int t = 0; t < nt; t += 2) {
;     ...
;             if constexpr (SP2) {
;             PG8_LDB(B0, 0, 0); PG8_LDB(B1, 0, 1); PG8_SCHED; PG8_LDA(At, 0, 0); PG8_STAGE(PG8_SA(1, 1), a1 + hstep, voffA);
;             PG8_WAIT_V(8); PG8_WAIT_L(0); PG8_BAR; PG8_MMA(0, 0, At, B0); PG8_MMA(0, 1, At, B1); PG8_BAR; PG8_SCHED;
;             PG8_LDA(At, 0, 1); PG8_STAGE(PG8_SB(0, 0), b2, voffB); PG8_STAGE(PG8_SB(0, 1), b2 + hstep, voffB); PG8_STAGE(PG8_SA(0, 0), a2, voffA);
;             PG8_WAIT_V(8); PG8_WAIT_L(0); PG8_BAR; PG8_MMA(1, 0, At, B0); PG8_MMA(1, 1, At, B1); PG8_BAR; PG8_SCHED;
;             PG8_LDB(B0, 1, 0); PG8_LDB(B1, 1, 1); PG8_SCHED; PG8_LDA(At, 1, 0); PG8_STAGE(PG8_SA(0, 1), a2 + hstep, voffA);
;             PG8_WAIT_V(8); PG8_WAIT_L(0); PG8_BAR; PG8_MMA(0, 0, At, B0); PG8_MMA(0, 1, At, B1); PG8_BAR; PG8_SCHED;
;             PG8_LDA(At, 1, 1); PG8_STAGE(PG8_SB(1, 0), b3, voffB); PG8_STAGE(PG8_SB(1, 1), b3 + hstep, voffB); PG8_STAGE(PG8_SA(1, 0), a3, voffA);
;             PG8_WAIT_V(8); PG8_WAIT_L(0); PG8_BAR; PG8_MMA(1, 0, At, B0); PG8_MMA(1, 1, At, B1); PG8_BAR; PG8_SCHED;
	s_sleep 2
	s_add_i32 s48, s83, s29
	v_lshl_add_u64 v[180:181], v[180:181], 0, s[6:7]
	s_mov_b32 m0, s48
	ds_read_b128 v[194:197], v155 offset:49152
	ds_read_b128 v[198:201], v155 offset:50176
	ds_read_b128 v[202:205], v155 offset:51200
	ds_read_b128 v[206:209], v155 offset:52224
	ds_read_b128 v[210:213], v155 offset:53248
	ds_read_b128 v[214:217], v155 offset:54272
	ds_read_b128 v[218:221], v155 offset:55296
	ds_read_b128 v[222:225], v155 offset:56320
	global_load_lds_dwordx4 v[180:181], off
	s_add_i32 m0, s48, 0x2000
	s_add_u32 s46, s46, 0x80080
	v_lshl_add_u64 v[180:181], v[188:189], 0, s[6:7]
	s_addc_u32 s47, s47, 0
	s_add_i32 s48, s84, s29
	global_load_lds_dwordx4 v[180:181], off
	v_lshl_add_u64 v[180:181], s[46:47], 0, v[130:131]
	s_mov_b32 m0, s48
	s_nop 0
	global_load_lds_dwordx4 v[180:181], off
	v_lshl_add_u64 v[180:181], s[46:47], 0, v[134:135]
	s_add_i32 m0, s48, 0x2000
	s_nop 0
	global_load_lds_dwordx4 v[180:181], off
	v_lshl_add_u64 v[180:181], v[226:227], 0, s[6:7]
	s_mov_b32 m0, s62
	s_nop 0
	global_load_lds_dwordx4 v[180:181], off
	v_lshl_add_u64 v[180:181], v[228:229], 0, s[6:7]
	s_mov_b32 m0, s63
	s_nop 0
	global_load_lds_dwordx4 v[180:181], off
	s_waitcnt vmcnt(8)
	s_waitcnt lgkmcnt(0)
	s_barrier
	s_setprio 1
	s_waitcnt lgkmcnt(0)
	v_mfma_f32_16x16x32_bf16 v[60:63], v[146:149], v[194:197], v[60:63]
	v_mfma_f32_16x16x32_bf16 v[56:59], v[160:163], v[194:197], v[56:59]
	v_mfma_f32_16x16x32_bf16 v[52:55], v[146:149], v[202:205], v[52:55]
	v_mfma_f32_16x16x32_bf16 v[44:47], v[160:163], v[202:205], v[44:47]
	v_mfma_f32_16x16x32_bf16 v[36:39], v[146:149], v[210:213], v[36:39]
	v_mfma_f32_16x16x32_bf16 v[28:31], v[160:163], v[210:213], v[28:31]
	v_mfma_f32_16x16x32_bf16 v[20:23], v[146:149], v[218:221], v[20:23]
	v_mfma_f32_16x16x32_bf16 v[12:15], v[160:163], v[218:221], v[12:15]
	v_mfma_f32_16x16x32_bf16 v[60:63], v[156:159], v[198:201], v[60:63]
	v_mfma_f32_16x16x32_bf16 v[56:59], v[164:167], v[198:201], v[56:59]
	v_mfma_f32_16x16x32_bf16 v[52:55], v[156:159], v[206:209], v[52:55]
	v_mfma_f32_16x16x32_bf16 v[44:47], v[164:167], v[206:209], v[44:47]
	v_mfma_f32_16x16x32_bf16 v[36:39], v[156:159], v[214:217], v[36:39]
	v_mfma_f32_16x16x32_bf16 v[28:31], v[164:167], v[214:217], v[28:31]
	v_mfma_f32_16x16x32_bf16 v[20:23], v[156:159], v[222:225], v[20:23]
	v_mfma_f32_16x16x32_bf16 v[12:15], v[164:167], v[222:225], v[12:15]
	s_setprio 0
	s_setprio 1
	v_mfma_f32_16x16x32_bf16 v[48:51], v[168:171], v[194:197], v[48:51]
	v_mfma_f32_16x16x32_bf16 v[40:43], v[176:179], v[194:197], v[40:43]
	v_mfma_f32_16x16x32_bf16 v[32:35], v[168:171], v[202:205], v[32:35]
	v_mfma_f32_16x16x32_bf16 v[24:27], v[176:179], v[202:205], v[24:27]
	v_mfma_f32_16x16x32_bf16 v[16:19], v[168:171], v[210:213], v[16:19]
	v_mfma_f32_16x16x32_bf16 v[8:11], v[176:179], v[210:213], v[8:11]
	v_mfma_f32_16x16x32_bf16 v[4:7], v[168:171], v[218:221], v[4:7]
	v_mfma_f32_16x16x32_bf16 v[0:3], v[176:179], v[218:221], v[0:3]
	v_mfma_f32_16x16x32_bf16 v[48:51], v[172:175], v[198:201], v[48:51]
	v_mfma_f32_16x16x32_bf16 v[40:43], v[190:193], v[198:201], v[40:43]
	v_mfma_f32_16x16x32_bf16 v[32:35], v[172:175], v[206:209], v[32:35]
	v_mfma_f32_16x16x32_bf16 v[24:27], v[190:193], v[206:209], v[24:27]
	v_mfma_f32_16x16x32_bf16 v[16:19], v[172:175], v[214:217], v[16:19]
	v_mfma_f32_16x16x32_bf16 v[8:11], v[190:193], v[214:217], v[8:11]
	v_mfma_f32_16x16x32_bf16 v[4:7], v[172:175], v[222:225], v[4:7]
	v_mfma_f32_16x16x32_bf16 v[0:3], v[190:193], v[222:225], v[0:3]
	s_setprio 0
	s_barrier
	s_sleep 2
	s_add_i32 s82, s82, 2
	s_add_u32 s44, s44, 0x100
	s_addc_u32 s45, s45, 0
	s_add_u32 s80, s80, 0x100
	s_addc_u32 s81, s81, 0
	s_cmp_gt_u32 s82, 29
	s_cbranch_scc0 .LBB0_251
	s_and_b64 vcc, exec, s[8:9]
	s_cbranch_vccz .LBB0_254
	s_barrier

; #define PG8_STAGE(bufoff, gbase, voff) do { _Pragma("unroll") for (int _i = 0; _i < 2; ++_i) \
;         __builtin_amdgcn_global_load_lds((const unsigned*)((const char*)(gbase) + (voff)[_i]), (PG8_LAS unsigned*)(lds + (bufoff) + ldsw + _i * 8192), 16, 0, 0); } while (0)
; #define PG8_LDA(dst, b, h) do { _Pragma("unroll") for (int m = 0; m < 4; ++m) _Pragma("unroll") for (int k = 0; k < 2; ++k) dst[m][k] = *(const PG8_LAS bf16x8*)(lds + PG8_SA(b, h) + aoff + m * 2048 + k * 1024); } while (0)
; #define PG8_LDB(dst, b, h) do { _Pragma("unroll") for (int n = 0; n < 2; ++n) _Pragma("unroll") for (int k = 0; k < 2; ++k) dst[n][k] = *(const PG8_LAS bf16x8*)(lds + PG8_SB(b, h) + boff + n * 2048 + k * 1024); } while (0)
; template <class Epi, class Sched, bool ALIGN_EPI = false, bool SP2 = false>
; __device__ __forceinline__ void gemm_phase(PG8_LAS unsigned char* lds, const Gemm g, const Sched& S, const Epi& E) {
;     ...
;         for (int t = 0; t < nt; t += 2) {
;             const bool last = (t == nt - 2);
;             const char* a1 = cA + (size_t)(t + 1) * kstep;
;             const char* a2 = last ? nA : cA + (size_t)(t + 2) * kstep; const char* b2 = last ? nB : cB + (size_t)(t + 2) * kstep;
;             const char* a3 = a2 + kstep; const char* b3 = b2 + kstep;
;             if (last && has_next) S.a_ready(nxt);
;             if constexpr (SP2) {
;             PG8_LDB(B0, 0, 0); PG8_LDB(B1, 0, 1); PG8_SCHED; PG8_LDA(At, 0, 0); PG8_STAGE(PG8_SA(1, 1), a1 + hstep, voffA);
;             PG8_WAIT_V(8); PG8_WAIT_L(0); PG8_BAR; PG8_MMA(0, 0, At, B0); PG8_MMA(0, 1, At, B1); PG8_BAR; PG8_SCHED;
;             PG8_LDA(At, 0, 1); PG8_STAGE(PG8_SB(0, 0), b2, voffB); PG8_STAGE(PG8_SB(0, 1), b2 + hstep, voffB); PG8_STAGE(PG8_SA(0, 0), a2, voffA);
;             PG8_WAIT_V(8); PG8_WAIT_L(0); PG8_BAR; PG8_MMA(1, 0, At, B0); PG8_MMA(1, 1, At, B1); PG8_BAR; PG8_SCHED;
;             PG8_LDB(B0, 1, 0); PG8_LDB(B1, 1, 1); PG8_SCHED; PG8_LDA(At, 1, 0); PG8_STAGE(PG8_SA(0, 1), a2 + hstep, voffA);
;             PG8_WAIT_V(8); PG8_WAIT_L(0); PG8_BAR; PG8_MMA(0, 0, At, B0); PG8_MMA(0, 1, At, B1); PG8_BAR; PG8_SCHED;
;             PG8_LDA(At, 1, 1); PG8_STAGE(PG8_SB(1, 0), b3, voffB); PG8_STAGE(PG8_SB(1, 1), b3 + hstep, voffB); PG8_STAGE(PG8_SA(1, 0), a3, voffA);
;             PG8_WAIT_V(8); PG8_WAIT_L(0); PG8_BAR; PG8_MMA(1, 0, At, B0); PG8_MMA(1, 1, At, B1); PG8_BAR; PG8_SCHED;
.LBB0_560:
	ds_read_b128 v[174:177], v167
	ds_read_b128 v[178:181], v167 offset:1024
	ds_read_b128 v[190:193], v167 offset:2048
	ds_read_b128 v[194:197], v167 offset:3072
	ds_read_b128 v[198:201], v168
	ds_read_b128 v[202:205], v168 offset:1024
	ds_read_b128 v[206:209], v168 offset:2048
	ds_read_b128 v[210:213], v168 offset:3072
	s_add_u32 s50, s10, 0x100
	s_addc_u32 s51, s11, 0
	s_add_u32 s52, s34, s10
	s_addc_u32 s53, s49, s11
	s_cmp_eq_u32 s67, 28
	s_cselect_b32 s54, s18, s52
	s_cselect_b32 s52, 0, s50
	s_cselect_b32 s55, s19, s53
	s_cselect_b32 s53, 0, s51
	s_add_u32 s52, s16, s52
	s_addc_u32 s53, s17, s53
	v_lshl_add_u64 v[246:247], v[142:143], 0, s[10:11]
	s_add_i32 m0, s15, 0xc000
	ds_read_b128 v[214:217], v169
	ds_read_b128 v[218:221], v169 offset:1024
	ds_read_b128 v[222:225], v169 offset:2048
	ds_read_b128 v[226:229], v169 offset:3072
	ds_read_b128 v[230:233], v169 offset:4096
	ds_read_b128 v[234:237], v169 offset:5120
	ds_read_b128 v[238:241], v169 offset:6144
	ds_read_b128 v[242:245], v169 offset:7168
	global_load_lds_dwordx4 v[246:247], off
	v_lshl_add_u64 v[246:247], v[146:147], 0, s[10:11]
	s_add_i32 m0, s15, 0xe000
	s_nop 0
	global_load_lds_dwordx4 v[246:247], off
	s_waitcnt vmcnt(8)
	s_waitcnt lgkmcnt(0)
	s_barrier
	s_setprio 1
	s_waitcnt lgkmcnt(0)
	v_mfma_f32_16x16x32_bf16 v[76:79], v[174:177], v[214:217], v[76:79]
	v_mfma_f32_16x16x32_bf16 v[72:75], v[190:193], v[214:217], v[72:75]
	v_mfma_f32_16x16x32_bf16 v[92:95], v[174:177], v[222:225], v[92:95]
	v_mfma_f32_16x16x32_bf16 v[88:91], v[190:193], v[222:225], v[88:91]
	v_mfma_f32_16x16x32_bf16 v[116:119], v[174:177], v[230:233], v[116:119]
	v_mfma_f32_16x16x32_bf16 v[112:115], v[190:193], v[230:233], v[112:115]
	v_mfma_f32_16x16x32_bf16 v[124:127], v[174:177], v[238:241], v[124:127]
	v_mfma_f32_16x16x32_bf16 v[120:123], v[190:193], v[238:241], v[120:123]
	v_mfma_f32_16x16x32_bf16 v[76:79], v[178:181], v[218:221], v[76:79]
	v_mfma_f32_16x16x32_bf16 v[72:75], v[194:197], v[218:221], v[72:75]
	v_mfma_f32_16x16x32_bf16 v[92:95], v[178:181], v[226:229], v[92:95]
	v_mfma_f32_16x16x32_bf16 v[88:91], v[194:197], v[226:229], v[88:91]
	v_mfma_f32_16x16x32_bf16 v[116:119], v[178:181], v[234:237], v[116:119]
	v_mfma_f32_16x16x32_bf16 v[112:115], v[194:197], v[234:237], v[112:115]
	v_mfma_f32_16x16x32_bf16 v[124:127], v[178:181], v[242:245], v[124:127]
	v_mfma_f32_16x16x32_bf16 v[120:123], v[194:197], v[242:245], v[120:123]
	s_setprio 0
	s_setprio 1
	v_mfma_f32_16x16x32_bf16 v[68:71], v[198:201], v[214:217], v[68:71]
	v_mfma_f32_16x16x32_bf16 v[64:67], v[206:209], v[214:217], v[64:67]
	v_mfma_f32_16x16x32_bf16 v[84:87], v[198:201], v[222:225], v[84:87]
	v_mfma_f32_16x16x32_bf16 v[80:83], v[206:209], v[222:225], v[80:83]
	v_mfma_f32_16x16x32_bf16 v[108:111], v[198:201], v[230:233], v[108:111]
	v_mfma_f32_16x16x32_bf16 v[96:99], v[206:209], v[230:233], v[96:99]
	v_mfma_f32_16x16x32_bf16 v[104:107], v[198:201], v[238:241], v[104:107]
	v_mfma_f32_16x16x32_bf16 v[100:103], v[206:209], v[238:241], v[100:103]
	v_mfma_f32_16x16x32_bf16 v[68:71], v[202:205], v[218:221], v[68:71]
	v_mfma_f32_16x16x32_bf16 v[64:67], v[210:213], v[218:221], v[64:67]
	v_mfma_f32_16x16x32_bf16 v[84:87], v[202:205], v[226:229], v[84:87]
	v_mfma_f32_16x16x32_bf16 v[80:83], v[210:213], v[226:229], v[80:83]
	v_mfma_f32_16x16x32_bf16 v[108:111], v[202:205], v[234:237], v[108:111]
	v_mfma_f32_16x16x32_bf16 v[96:99], v[210:213], v[234:237], v[96:99]
	v_mfma_f32_16x16x32_bf16 v[104:107], v[202:205], v[242:245], v[104:107]
	v_mfma_f32_16x16x32_bf16 v[100:103], v[210:213], v[242:245], v[100:103]
	s_setprio 0
	s_barrier
	s_sleep 2
	s_add_i32 s10, s61, s2
	v_lshl_add_u64 v[246:247], s[52:53], 0, v[128:129]
	s_mov_b32 m0, s10
	ds_read_b128 v[214:217], v169 offset:16384
	ds_read_b128 v[218:221], v169 offset:17408
	ds_read_b128 v[222:225], v169 offset:18432
	ds_read_b128 v[226:229], v169 offset:19456
	ds_read_b128 v[230:233], v169 offset:20480
	ds_read_b128 v[234:237], v169 offset:21504
	ds_read_b128 v[238:241], v169 offset:22528
	ds_read_b128 v[242:245], v169 offset:23552
	global_load_lds_dwordx4 v[246:247], off
	s_add_i32 m0, s10, 0x2000
	s_add_u32 s10, s52, 0x80000
	v_lshl_add_u64 v[248:249], s[52:53], 0, v[130:131]
	s_addc_u32 s11, s53, 0
	s_add_i32 s76, s62, s2
	global_load_lds_dwordx4 v[248:249], off
	v_lshl_add_u64 v[250:251], s[10:11], 0, v[128:129]
	s_mov_b32 m0, s76
	v_lshl_add_u64 v[252:253], s[54:55], 0, v[130:131]
	global_load_lds_dwordx4 v[250:251], off
	v_lshl_add_u64 v[250:251], s[10:11], 0, v[130:131]
	s_add_i32 m0, s76, 0x2000
	s_nop 0
	global_load_lds_dwordx4 v[250:251], off
	v_lshl_add_u64 v[250:251], s[54:55], 0, v[128:129]
	s_mov_b32 m0, s15
	s_nop 0
	global_load_lds_dwordx4 v[250:251], off
	s_mov_b32 m0, s28
	s_nop 0
	global_load_lds_dwordx4 v[252:253], off
	s_waitcnt vmcnt(8)
	s_waitcnt lgkmcnt(0)
	s_barrier
; #define PG8_STAGE(bufoff, gbase, voff) do { _Pragma("unroll") for (int _i = 0; _i < 2; ++_i) \
;         __builtin_amdgcn_global_load_lds((const unsigned*)((const char*)(gbase) + (voff)[_i]), (PG8_LAS unsigned*)(lds + (bufoff) + ldsw + _i * 8192), 16, 0, 0); } while (0)
; #define PG8_LDA(dst, b, h) do { _Pragma("unroll") for (int m = 0; m < 4; ++m) _Pragma("unroll") for (int k = 0; k < 2; ++k) dst[m][k] = *(const PG8_LAS bf16x8*)(lds + PG8_SA(b, h) + aoff + m * 2048 + k * 1024); } while (0)
; #define PG8_LDB(dst, b, h) do { _Pragma("unroll") for (int n = 0; n < 2; ++n) _Pragma("unroll") for (int k = 0; k < 2; ++k) dst[n][k] = *(const PG8_LAS bf16x8*)(lds + PG8_SB(b, h) + boff + n * 2048 + k * 1024); } while (0)
; #define PG8_MMA(ai, bj, At, Bt) do { __builtin_amdgcn_s_setprio(1); _Pragma("unroll") for (int m = 0; m < 4; ++m) _Pragma("unroll") for (int n = 0; n < 2; ++n) _Pragma("unroll") for (int k = 0; k < 2; ++k) \
;         acc[ai][bj][m][n] = __builtin_amdgcn_mfma_f32_16x16x32_bf16(Bt[n][k], At[m][k], acc[ai][bj][m][n], 0, 0, 0); __builtin_amdgcn_s_setprio(0); } while (0)
; #define PG8_BAR __builtin_amdgcn_s_barrier()
; template <class Epi, class Sched, bool ALIGN_EPI = false, bool SP2 = false>
; __device__ __forceinline__ void gemm_phase(PG8_LAS unsigned char* lds, const Gemm g, const Sched& S, const Epi& E) {
;     ...
;             if constexpr (SP2) {
;             PG8_LDB(B0, 0, 0); PG8_LDB(B1, 0, 1); PG8_SCHED; PG8_LDA(At, 0, 0); PG8_STAGE(PG8_SA(1, 1), a1 + hstep, voffA);
;             PG8_WAIT_V(8); PG8_WAIT_L(0); PG8_BAR; PG8_MMA(0, 0, At, B0); PG8_MMA(0, 1, At, B1); PG8_BAR; PG8_SCHED;
;             PG8_LDA(At, 0, 1); PG8_STAGE(PG8_SB(0, 0), b2, voffB); PG8_STAGE(PG8_SB(0, 1), b2 + hstep, voffB); PG8_STAGE(PG8_SA(0, 0), a2, voffA);
;             PG8_WAIT_V(8); PG8_WAIT_L(0); PG8_BAR; PG8_MMA(1, 0, At, B0); PG8_MMA(1, 1, At, B1); PG8_BAR; PG8_SCHED;
;             PG8_LDB(B0, 1, 0); PG8_LDB(B1, 1, 1); PG8_SCHED; PG8_LDA(At, 1, 0); PG8_STAGE(PG8_SA(0, 1), a2 + hstep, voffA);
;             PG8_WAIT_V(8); PG8_WAIT_L(0); PG8_BAR; PG8_MMA(0, 0, At, B0); PG8_MMA(0, 1, At, B1); PG8_BAR; PG8_SCHED;
;             PG8_LDA(At, 1, 1); PG8_STAGE(PG8_SB(1, 0), b3, voffB); PG8_STAGE(PG8_SB(1, 1), b3 + hstep, voffB); PG8_STAGE(PG8_SA(1, 0), a3, voffA);
;             PG8_WAIT_V(8); PG8_WAIT_L(0); PG8_BAR; PG8_MMA(1, 0, At, B0); PG8_MMA(1, 1, At, B1); PG8_BAR; PG8_SCHED;
	s_setprio 1
	s_waitcnt lgkmcnt(0)
	v_mfma_f32_16x16x32_bf16 v[60:63], v[174:177], v[214:217], v[60:63]
	v_mfma_f32_16x16x32_bf16 v[56:59], v[190:193], v[214:217], v[56:59]
	v_mfma_f32_16x16x32_bf16 v[44:47], v[174:177], v[222:225], v[44:47]
	v_mfma_f32_16x16x32_bf16 v[40:43], v[190:193], v[222:225], v[40:43]
	v_mfma_f32_16x16x32_bf16 v[28:31], v[174:177], v[230:233], v[28:31]
	v_mfma_f32_16x16x32_bf16 v[24:27], v[190:193], v[230:233], v[24:27]
	v_mfma_f32_16x16x32_bf16 v[12:15], v[174:177], v[238:241], v[12:15]
	v_mfma_f32_16x16x32_bf16 v[8:11], v[190:193], v[238:241], v[8:11]
	v_mfma_f32_16x16x32_bf16 v[60:63], v[178:181], v[218:221], v[60:63]
	v_mfma_f32_16x16x32_bf16 v[56:59], v[194:197], v[218:221], v[56:59]
	v_mfma_f32_16x16x32_bf16 v[44:47], v[178:181], v[226:229], v[44:47]
	v_mfma_f32_16x16x32_bf16 v[40:43], v[194:197], v[226:229], v[40:43]
	v_mfma_f32_16x16x32_bf16 v[28:31], v[178:181], v[234:237], v[28:31]
	v_mfma_f32_16x16x32_bf16 v[24:27], v[194:197], v[234:237], v[24:27]
	v_mfma_f32_16x16x32_bf16 v[12:15], v[178:181], v[242:245], v[12:15]
	v_mfma_f32_16x16x32_bf16 v[8:11], v[194:197], v[242:245], v[8:11]
	s_setprio 0
	s_setprio 1
	v_mfma_f32_16x16x32_bf16 v[52:55], v[198:201], v[214:217], v[52:55]
	v_mfma_f32_16x16x32_bf16 v[48:51], v[206:209], v[214:217], v[48:51]
	v_mfma_f32_16x16x32_bf16 v[36:39], v[198:201], v[222:225], v[36:39]
	v_mfma_f32_16x16x32_bf16 v[32:35], v[206:209], v[222:225], v[32:35]
	v_mfma_f32_16x16x32_bf16 v[20:23], v[198:201], v[230:233], v[20:23]
	v_mfma_f32_16x16x32_bf16 v[16:19], v[206:209], v[230:233], v[16:19]
	v_mfma_f32_16x16x32_bf16 v[4:7], v[198:201], v[238:241], v[4:7]
	v_mfma_f32_16x16x32_bf16 v[0:3], v[206:209], v[238:241], v[0:3]
	v_mfma_f32_16x16x32_bf16 v[52:55], v[202:205], v[218:221], v[52:55]
	v_mfma_f32_16x16x32_bf16 v[48:51], v[210:213], v[218:221], v[48:51]
	v_mfma_f32_16x16x32_bf16 v[36:39], v[202:205], v[226:229], v[36:39]
	v_mfma_f32_16x16x32_bf16 v[32:35], v[210:213], v[226:229], v[32:35]
	v_mfma_f32_16x16x32_bf16 v[20:23], v[202:205], v[234:237], v[20:23]
	v_mfma_f32_16x16x32_bf16 v[16:19], v[210:213], v[234:237], v[16:19]
	v_mfma_f32_16x16x32_bf16 v[4:7], v[202:205], v[242:245], v[4:7]
	v_mfma_f32_16x16x32_bf16 v[0:3], v[210:213], v[242:245], v[0:3]
	s_setprio 0
	s_barrier
	s_sleep 2
	s_add_i32 s76, 0, 0x18000
	v_add_u32_e32 v188, s76, v149
	s_add_i32 s77, 0, 0x1c000
	ds_read_b128 v[174:177], v188
	ds_read_b128 v[178:181], v188 offset:1024
	ds_read_b128 v[190:193], v188 offset:2048
	ds_read_b128 v[194:197], v188 offset:3072
	v_add_u32_e32 v188, s77, v149
	ds_read_b128 v[198:201], v188
	ds_read_b128 v[202:205], v188 offset:1024
	ds_read_b128 v[206:209], v188 offset:2048
	ds_read_b128 v[210:213], v188 offset:3072
	s_add_u32 s10, s54, 0x80000
	s_addc_u32 s11, s55, 0
	s_mov_b32 m0, s29
	v_lshl_add_u64 v[188:189], s[10:11], 0, v[128:129]
	ds_read_b128 v[214:217], v169 offset:32768
	ds_read_b128 v[218:221], v169 offset:33792
	ds_read_b128 v[222:225], v169 offset:34816
	ds_read_b128 v[226:229], v169 offset:35840
	ds_read_b128 v[230:233], v169 offset:36864
	ds_read_b128 v[234:237], v169 offset:37888
	ds_read_b128 v[238:241], v169 offset:38912
	ds_read_b128 v[242:245], v169 offset:39936
	global_load_lds_dwordx4 v[188:189], off
	v_lshl_add_u64 v[188:189], s[10:11], 0, v[130:131]
	s_mov_b32 m0, s56
	s_nop 0
	global_load_lds_dwordx4 v[188:189], off
	s_waitcnt vmcnt(8)
	s_waitcnt lgkmcnt(0)
	s_barrier
	s_setprio 1
	s_waitcnt lgkmcnt(0)
	v_mfma_f32_16x16x32_bf16 v[76:79], v[174:177], v[214:217], v[76:79]
	v_mfma_f32_16x16x32_bf16 v[72:75], v[190:193], v[214:217], v[72:75]
	v_mfma_f32_16x16x32_bf16 v[92:95], v[174:177], v[222:225], v[92:95]
	v_mfma_f32_16x16x32_bf16 v[88:91], v[190:193], v[222:225], v[88:91]
	v_mfma_f32_16x16x32_bf16 v[116:119], v[174:177], v[230:233], v[116:119]
	v_mfma_f32_16x16x32_bf16 v[112:115], v[190:193], v[230:233], v[112:115]
	v_mfma_f32_16x16x32_bf16 v[124:127], v[174:177], v[238:241], v[124:127]
	v_mfma_f32_16x16x32_bf16 v[120:123], v[190:193], v[238:241], v[120:123]
	v_mfma_f32_16x16x32_bf16 v[76:79], v[178:181], v[218:221], v[76:79]
	v_mfma_f32_16x16x32_bf16 v[72:75], v[194:197], v[218:221], v[72:75]
	v_mfma_f32_16x16x32_bf16 v[92:95], v[178:181], v[226:229], v[92:95]
	v_mfma_f32_16x16x32_bf16 v[88:91], v[194:197], v[226:229], v[88:91]
	v_mfma_f32_16x16x32_bf16 v[116:119], v[178:181], v[234:237], v[116:119]
	v_mfma_f32_16x16x32_bf16 v[112:115], v[194:197], v[234:237], v[112:115]
	v_mfma_f32_16x16x32_bf16 v[124:127], v[178:181], v[242:245], v[124:127]
	v_mfma_f32_16x16x32_bf16 v[120:123], v[194:197], v[242:245], v[120:123]
	s_setprio 0
	s_setprio 1
	v_mfma_f32_16x16x32_bf16 v[68:71], v[198:201], v[214:217], v[68:71]
	v_mfma_f32_16x16x32_bf16 v[64:67], v[206:209], v[214:217], v[64:67]
	v_mfma_f32_16x16x32_bf16 v[84:87], v[198:201], v[222:225], v[84:87]
	v_mfma_f32_16x16x32_bf16 v[80:83], v[206:209], v[222:225], v[80:83]
	v_mfma_f32_16x16x32_bf16 v[108:111], v[198:201], v[230:233], v[108:111]
	v_mfma_f32_16x16x32_bf16 v[96:99], v[206:209], v[230:233], v[96:99]
	v_mfma_f32_16x16x32_bf16 v[104:107], v[198:201], v[238:241], v[104:107]
	v_mfma_f32_16x16x32_bf16 v[100:103], v[206:209], v[238:241], v[100:103]
	v_mfma_f32_16x16x32_bf16 v[68:71], v[202:205], v[218:221], v[68:71]
	v_mfma_f32_16x16x32_bf16 v[64:67], v[210:213], v[218:221], v[64:67]
	v_mfma_f32_16x16x32_bf16 v[84:87], v[202:205], v[226:229], v[84:87]
	v_mfma_f32_16x16x32_bf16 v[80:83], v[210:213], v[226:229], v[80:83]
	v_mfma_f32_16x16x32_bf16 v[108:111], v[202:205], v[234:237], v[108:111]
	v_mfma_f32_16x16x32_bf16 v[96:99], v[210:213], v[234:237], v[96:99]
	v_mfma_f32_16x16x32_bf16 v[104:107], v[202:205], v[242:245], v[104:107]
	v_mfma_f32_16x16x32_bf16 v[100:103], v[210:213], v[242:245], v[100:103]
	s_setprio 0
	s_barrier
; #define PG8_STAGE(bufoff, gbase, voff) do { _Pragma("unroll") for (int _i = 0; _i < 2; ++_i) \
;         __builtin_amdgcn_global_load_lds((const unsigned*)((const char*)(gbase) + (voff)[_i]), (PG8_LAS unsigned*)(lds + (bufoff) + ldsw + _i * 8192), 16, 0, 0); } while (0)
; #define PG8_LDA(dst, b, h) do { _Pragma("unroll") for (int m = 0; m < 4; ++m) _Pragma("unroll") for (int k = 0; k < 2; ++k) dst[m][k] = *(const PG8_LAS bf16x8*)(lds + PG8_SA(b, h) + aoff + m * 2048 + k * 1024); } while (0)
; #define PG8_LDB(dst, b, h) do { _Pragma("unroll") for (int n = 0; n < 2; ++n) _Pragma("unroll") for (int k = 0; k < 2; ++k) dst[n][k] = *(const PG8_LAS bf16x8*)(lds + PG8_SB(b, h) + boff + n * 2048 + k * 1024); } while (0)
; #define PG8_MMA(ai, bj, At, Bt) do { __builtin_amdgcn_s_setprio(1); _Pragma("unroll") for (int m = 0; m < 4; ++m) _Pragma("unroll") for (int n = 0; n < 2; ++n) _Pragma("unroll") for (int k = 0; k < 2; ++k) \
;         acc[ai][bj][m][n] = __builtin_amdgcn_mfma_f32_16x16x32_bf16(Bt[n][k], At[m][k], acc[ai][bj][m][n], 0, 0, 0); __builtin_amdgcn_s_setprio(0); } while (0)
; template <class Epi, class Sched, bool ALIGN_EPI = false, bool SP2 = false>
; __device__ __forceinline__ void gemm_phase(PG8_LAS unsigned char* lds, const Gemm g, const Sched& S, const Epi& E) {
;     ...
;         for (int t = 0; t < nt; t += 2) {
;     ...
;             if constexpr (SP2) {
;             PG8_LDB(B0, 0, 0); PG8_LDB(B1, 0, 1); PG8_SCHED; PG8_LDA(At, 0, 0); PG8_STAGE(PG8_SA(1, 1), a1 + hstep, voffA);
;             PG8_WAIT_V(8); PG8_WAIT_L(0); PG8_BAR; PG8_MMA(0, 0, At, B0); PG8_MMA(0, 1, At, B1); PG8_BAR; PG8_SCHED;
;             PG8_LDA(At, 0, 1); PG8_STAGE(PG8_SB(0, 0), b2, voffB); PG8_STAGE(PG8_SB(0, 1), b2 + hstep, voffB); PG8_STAGE(PG8_SA(0, 0), a2, voffA);
;             PG8_WAIT_V(8); PG8_WAIT_L(0); PG8_BAR; PG8_MMA(1, 0, At, B0); PG8_MMA(1, 1, At, B1); PG8_BAR; PG8_SCHED;
;             PG8_LDB(B0, 1, 0); PG8_LDB(B1, 1, 1); PG8_SCHED; PG8_LDA(At, 1, 0); PG8_STAGE(PG8_SA(0, 1), a2 + hstep, voffA);
;             PG8_WAIT_V(8); PG8_WAIT_L(0); PG8_BAR; PG8_MMA(0, 0, At, B0); PG8_MMA(0, 1, At, B1); PG8_BAR; PG8_SCHED;
;             PG8_LDA(At, 1, 1); PG8_STAGE(PG8_SB(1, 0), b3, voffB); PG8_STAGE(PG8_SB(1, 1), b3 + hstep, voffB); PG8_STAGE(PG8_SA(1, 0), a3, voffA);
;             PG8_WAIT_V(8); PG8_WAIT_L(0); PG8_BAR; PG8_MMA(1, 0, At, B0); PG8_MMA(1, 1, At, B1); PG8_BAR; PG8_SCHED;
	s_sleep 2
	s_add_i32 s10, s76, s2
	v_lshl_add_u64 v[188:189], v[246:247], 0, s[38:39]
	s_mov_b32 m0, s10
	ds_read_b128 v[214:217], v169 offset:49152
	ds_read_b128 v[218:221], v169 offset:50176
	ds_read_b128 v[222:225], v169 offset:51200
	ds_read_b128 v[226:229], v169 offset:52224
	ds_read_b128 v[230:233], v169 offset:53248
	ds_read_b128 v[234:237], v169 offset:54272
	ds_read_b128 v[238:241], v169 offset:55296
	ds_read_b128 v[242:245], v169 offset:56320
	global_load_lds_dwordx4 v[188:189], off
	s_add_i32 m0, s10, 0x2000
	s_add_u32 s10, s52, 0x80080
	v_lshl_add_u64 v[188:189], v[248:249], 0, s[38:39]
	s_addc_u32 s11, s53, 0
	s_add_i32 s52, s77, s2
	global_load_lds_dwordx4 v[188:189], off
	v_lshl_add_u64 v[188:189], s[10:11], 0, v[128:129]
	s_mov_b32 m0, s52
	s_nop 0
	global_load_lds_dwordx4 v[188:189], off
	v_lshl_add_u64 v[188:189], s[10:11], 0, v[130:131]
	s_add_i32 m0, s52, 0x2000
	s_nop 0
	global_load_lds_dwordx4 v[188:189], off
	v_lshl_add_u64 v[188:189], v[250:251], 0, s[38:39]
	s_mov_b32 m0, s59
	s_nop 0
	global_load_lds_dwordx4 v[188:189], off
	v_lshl_add_u64 v[188:189], v[252:253], 0, s[38:39]
	s_mov_b32 m0, s60
	s_nop 0
	global_load_lds_dwordx4 v[188:189], off
	s_waitcnt vmcnt(8)
	s_waitcnt lgkmcnt(0)
	s_barrier
	s_setprio 1
	s_waitcnt lgkmcnt(0)
	v_mfma_f32_16x16x32_bf16 v[60:63], v[174:177], v[214:217], v[60:63]
	v_mfma_f32_16x16x32_bf16 v[56:59], v[190:193], v[214:217], v[56:59]
	v_mfma_f32_16x16x32_bf16 v[44:47], v[174:177], v[222:225], v[44:47]
	v_mfma_f32_16x16x32_bf16 v[40:43], v[190:193], v[222:225], v[40:43]
	v_mfma_f32_16x16x32_bf16 v[28:31], v[174:177], v[230:233], v[28:31]
	v_mfma_f32_16x16x32_bf16 v[24:27], v[190:193], v[230:233], v[24:27]
	v_mfma_f32_16x16x32_bf16 v[12:15], v[174:177], v[238:241], v[12:15]
	v_mfma_f32_16x16x32_bf16 v[8:11], v[190:193], v[238:241], v[8:11]
	v_mfma_f32_16x16x32_bf16 v[60:63], v[178:181], v[218:221], v[60:63]
	v_mfma_f32_16x16x32_bf16 v[56:59], v[194:197], v[218:221], v[56:59]
	v_mfma_f32_16x16x32_bf16 v[44:47], v[178:181], v[226:229], v[44:47]
	v_mfma_f32_16x16x32_bf16 v[40:43], v[194:197], v[226:229], v[40:43]
	v_mfma_f32_16x16x32_bf16 v[28:31], v[178:181], v[234:237], v[28:31]
	v_mfma_f32_16x16x32_bf16 v[24:27], v[194:197], v[234:237], v[24:27]
	v_mfma_f32_16x16x32_bf16 v[12:15], v[178:181], v[242:245], v[12:15]
	v_mfma_f32_16x16x32_bf16 v[8:11], v[194:197], v[242:245], v[8:11]
	s_setprio 0
	s_setprio 1
	v_mfma_f32_16x16x32_bf16 v[52:55], v[198:201], v[214:217], v[52:55]
	v_mfma_f32_16x16x32_bf16 v[48:51], v[206:209], v[214:217], v[48:51]
	v_mfma_f32_16x16x32_bf16 v[36:39], v[198:201], v[222:225], v[36:39]
	v_mfma_f32_16x16x32_bf16 v[32:35], v[206:209], v[222:225], v[32:35]
	v_mfma_f32_16x16x32_bf16 v[20:23], v[198:201], v[230:233], v[20:23]
	v_mfma_f32_16x16x32_bf16 v[16:19], v[206:209], v[230:233], v[16:19]
	v_mfma_f32_16x16x32_bf16 v[4:7], v[198:201], v[238:241], v[4:7]
	v_mfma_f32_16x16x32_bf16 v[0:3], v[206:209], v[238:241], v[0:3]
	v_mfma_f32_16x16x32_bf16 v[52:55], v[202:205], v[218:221], v[52:55]
	v_mfma_f32_16x16x32_bf16 v[48:51], v[210:213], v[218:221], v[48:51]
	v_mfma_f32_16x16x32_bf16 v[36:39], v[202:205], v[226:229], v[36:39]
	v_mfma_f32_16x16x32_bf16 v[32:35], v[210:213], v[226:229], v[32:35]
	v_mfma_f32_16x16x32_bf16 v[20:23], v[202:205], v[234:237], v[20:23]
	v_mfma_f32_16x16x32_bf16 v[16:19], v[210:213], v[234:237], v[16:19]
	v_mfma_f32_16x16x32_bf16 v[4:7], v[202:205], v[242:245], v[4:7]
	v_mfma_f32_16x16x32_bf16 v[0:3], v[210:213], v[242:245], v[0:3]
	s_setprio 0
	s_barrier
	s_sleep 2
	s_add_i32 s67, s67, 2
	s_cmp_gt_u32 s67, 29
	s_mov_b64 s[10:11], s[50:51]
	s_cbranch_scc0 .LBB0_560
	s_and_b64 vcc, exec, s[40:41]
	s_cbranch_vccz .LBB0_563
	s_barrier

; #define PG8_STAGE(bufoff, gbase, voff) do { _Pragma("unroll") for (int _i = 0; _i < 2; ++_i) \
;         __builtin_amdgcn_global_load_lds((const unsigned*)((const char*)(gbase) + (voff)[_i]), (PG8_LAS unsigned*)(lds + (bufoff) + ldsw + _i * 8192), 16, 0, 0); } while (0)
; #define PG8_LDA(dst, b, h) do { _Pragma("unroll") for (int m = 0; m < 4; ++m) _Pragma("unroll") for (int k = 0; k < 2; ++k) dst[m][k] = *(const PG8_LAS bf16x8*)(lds + PG8_SA(b, h) + aoff + m * 2048 + k * 1024); } while (0)
; #define PG8_LDB(dst, b, h) do { _Pragma("unroll") for (int n = 0; n < 2; ++n) _Pragma("unroll") for (int k = 0; k < 2; ++k) dst[n][k] = *(const PG8_LAS bf16x8*)(lds + PG8_SB(b, h) + boff + n * 2048 + k * 1024); } while (0)
; template <class Epi, class Sched, bool ALIGN_EPI = false, bool SP2 = false>
; __device__ __forceinline__ void gemm_phase(PG8_LAS unsigned char* lds, const Gemm g, const Sched& S, const Epi& E) {
;     ...
;         for (int t = 0; t < nt; t += 2) {
;             const bool last = (t == nt - 2);
;             const char* a1 = cA + (size_t)(t + 1) * kstep;
;             const char* a2 = last ? nA : cA + (size_t)(t + 2) * kstep; const char* b2 = last ? nB : cB + (size_t)(t + 2) * kstep;
;             const char* a3 = a2 + kstep; const char* b3 = b2 + kstep;
;             if (last && has_next) S.a_ready(nxt);
;             if constexpr (SP2) {
;             PG8_LDB(B0, 0, 0); PG8_LDB(B1, 0, 1); PG8_SCHED; PG8_LDA(At, 0, 0); PG8_STAGE(PG8_SA(1, 1), a1 + hstep, voffA);
;             PG8_WAIT_V(8); PG8_WAIT_L(0); PG8_BAR; PG8_MMA(0, 0, At, B0); PG8_MMA(0, 1, At, B1); PG8_BAR; PG8_SCHED;
;             PG8_LDA(At, 0, 1); PG8_STAGE(PG8_SB(0, 0), b2, voffB); PG8_STAGE(PG8_SB(0, 1), b2 + hstep, voffB); PG8_STAGE(PG8_SA(0, 0), a2, voffA);
;             PG8_WAIT_V(8); PG8_WAIT_L(0); PG8_BAR; PG8_MMA(1, 0, At, B0); PG8_MMA(1, 1, At, B1); PG8_BAR; PG8_SCHED;
;             PG8_LDB(B0, 1, 0); PG8_LDB(B1, 1, 1); PG8_SCHED; PG8_LDA(At, 1, 0); PG8_STAGE(PG8_SA(0, 1), a2 + hstep, voffA);
;             PG8_WAIT_V(8); PG8_WAIT_L(0); PG8_BAR; PG8_MMA(0, 0, At, B0); PG8_MMA(0, 1, At, B1); PG8_BAR; PG8_SCHED;
;             PG8_LDA(At, 1, 1); PG8_STAGE(PG8_SB(1, 0), b3, voffB); PG8_STAGE(PG8_SB(1, 1), b3 + hstep, voffB); PG8_STAGE(PG8_SA(1, 0), a3, voffA);
;             PG8_WAIT_V(8); PG8_WAIT_L(0); PG8_BAR; PG8_MMA(1, 0, At, B0); PG8_MMA(1, 1, At, B1); PG8_BAR; PG8_SCHED;
.LBB0_621:
	ds_read_b128 v[146:149], v153
	ds_read_b128 v[156:159], v153 offset:1024
	ds_read_b128 v[160:163], v153 offset:2048
	ds_read_b128 v[164:167], v153 offset:3072
	ds_read_b128 v[168:171], v154
	ds_read_b128 v[172:175], v154 offset:1024
	ds_read_b128 v[176:179], v154 offset:2048
	ds_read_b128 v[190:193], v154 offset:3072
	s_add_u32 s34, s30, 0xfff80080
	s_addc_u32 s35, s31, -1
	s_cmp_eq_u32 s50, 28
	s_cselect_b32 s37, s15, s35
	s_cselect_b32 s36, s46, s34
	s_cselect_b32 s35, s13, s49
	s_cselect_b32 s34, s47, s48
	v_lshl_add_u64 v[180:181], s[30:31], 0, v[136:137]
	s_add_i32 m0, s23, 0xc000
	ds_read_b128 v[194:197], v155
	ds_read_b128 v[198:201], v155 offset:1024
	ds_read_b128 v[202:205], v155 offset:2048
	ds_read_b128 v[206:209], v155 offset:3072
	ds_read_b128 v[210:213], v155 offset:4096
	ds_read_b128 v[214:217], v155 offset:5120
	ds_read_b128 v[218:221], v155 offset:6144
	ds_read_b128 v[222:225], v155 offset:7168
	global_load_lds_dwordx4 v[180:181], off
	v_lshl_add_u64 v[180:181], s[30:31], 0, v[138:139]
	s_add_i32 m0, s23, 0xe000
	s_nop 0
	global_load_lds_dwordx4 v[180:181], off
	s_waitcnt vmcnt(8)
	s_waitcnt lgkmcnt(0)
	s_barrier
	s_setprio 1
	s_waitcnt lgkmcnt(0)
	v_mfma_f32_16x16x32_bf16 v[124:127], v[146:149], v[194:197], v[124:127]
	v_mfma_f32_16x16x32_bf16 v[120:123], v[160:163], v[194:197], v[120:123]
	v_mfma_f32_16x16x32_bf16 v[108:111], v[146:149], v[202:205], v[108:111]
	v_mfma_f32_16x16x32_bf16 v[104:107], v[160:163], v[202:205], v[104:107]
	v_mfma_f32_16x16x32_bf16 v[92:95], v[146:149], v[210:213], v[92:95]
	v_mfma_f32_16x16x32_bf16 v[88:91], v[160:163], v[210:213], v[88:91]
	v_mfma_f32_16x16x32_bf16 v[76:79], v[146:149], v[218:221], v[76:79]
	v_mfma_f32_16x16x32_bf16 v[72:75], v[160:163], v[218:221], v[72:75]
	v_mfma_f32_16x16x32_bf16 v[124:127], v[156:159], v[198:201], v[124:127]
	v_mfma_f32_16x16x32_bf16 v[120:123], v[164:167], v[198:201], v[120:123]
	v_mfma_f32_16x16x32_bf16 v[108:111], v[156:159], v[206:209], v[108:111]
	v_mfma_f32_16x16x32_bf16 v[104:107], v[164:167], v[206:209], v[104:107]
	v_mfma_f32_16x16x32_bf16 v[92:95], v[156:159], v[214:217], v[92:95]
	v_mfma_f32_16x16x32_bf16 v[88:91], v[164:167], v[214:217], v[88:91]
	v_mfma_f32_16x16x32_bf16 v[76:79], v[156:159], v[222:225], v[76:79]
	v_mfma_f32_16x16x32_bf16 v[72:75], v[164:167], v[222:225], v[72:75]
	s_setprio 0
	s_setprio 1
	v_mfma_f32_16x16x32_bf16 v[116:119], v[168:171], v[194:197], v[116:119]
	v_mfma_f32_16x16x32_bf16 v[112:115], v[176:179], v[194:197], v[112:115]
	v_mfma_f32_16x16x32_bf16 v[100:103], v[168:171], v[202:205], v[100:103]
	v_mfma_f32_16x16x32_bf16 v[96:99], v[176:179], v[202:205], v[96:99]
	v_mfma_f32_16x16x32_bf16 v[84:87], v[168:171], v[210:213], v[84:87]
	v_mfma_f32_16x16x32_bf16 v[80:83], v[176:179], v[210:213], v[80:83]
	v_mfma_f32_16x16x32_bf16 v[68:71], v[168:171], v[218:221], v[68:71]
	v_mfma_f32_16x16x32_bf16 v[64:67], v[176:179], v[218:221], v[64:67]
	v_mfma_f32_16x16x32_bf16 v[116:119], v[172:175], v[198:201], v[116:119]
	v_mfma_f32_16x16x32_bf16 v[112:115], v[190:193], v[198:201], v[112:115]
	v_mfma_f32_16x16x32_bf16 v[100:103], v[172:175], v[206:209], v[100:103]
	v_mfma_f32_16x16x32_bf16 v[96:99], v[190:193], v[206:209], v[96:99]
	v_mfma_f32_16x16x32_bf16 v[84:87], v[172:175], v[214:217], v[84:87]
	v_mfma_f32_16x16x32_bf16 v[80:83], v[190:193], v[214:217], v[80:83]
	v_mfma_f32_16x16x32_bf16 v[68:71], v[172:175], v[222:225], v[68:71]
	v_mfma_f32_16x16x32_bf16 v[64:67], v[190:193], v[222:225], v[64:67]
	s_setprio 0
	s_barrier
	s_sleep 2
	s_add_i32 s51, s42, s2
	v_lshl_add_u64 v[180:181], s[34:35], 0, v[132:133]
	s_mov_b32 m0, s51
	ds_read_b128 v[194:197], v155 offset:16384
	ds_read_b128 v[198:201], v155 offset:17408
	ds_read_b128 v[202:205], v155 offset:18432
	ds_read_b128 v[206:209], v155 offset:19456
	ds_read_b128 v[210:213], v155 offset:20480
	ds_read_b128 v[214:217], v155 offset:21504
	ds_read_b128 v[218:221], v155 offset:22528
	ds_read_b128 v[222:225], v155 offset:23552
	global_load_lds_dwordx4 v[180:181], off
	s_add_i32 m0, s51, 0x2000
	s_add_u32 s52, s34, 0x80000
	v_lshl_add_u64 v[188:189], s[34:35], 0, v[128:129]
	s_addc_u32 s53, s35, 0
	s_add_i32 s51, s43, s2
	global_load_lds_dwordx4 v[188:189], off
	v_lshl_add_u64 v[226:227], s[52:53], 0, v[132:133]
	s_mov_b32 m0, s51
	v_lshl_add_u64 v[228:229], s[36:37], 0, v[130:131]
	global_load_lds_dwordx4 v[226:227], off
	v_lshl_add_u64 v[226:227], s[52:53], 0, v[128:129]
	s_add_i32 m0, s51, 0x2000
	s_nop 0
	global_load_lds_dwordx4 v[226:227], off
	v_lshl_add_u64 v[226:227], s[36:37], 0, v[134:135]
	s_mov_b32 m0, s23
	s_nop 0
	global_load_lds_dwordx4 v[226:227], off
	s_mov_b32 m0, s28
	s_nop 0
	global_load_lds_dwordx4 v[228:229], off
	s_waitcnt vmcnt(8)
	s_waitcnt lgkmcnt(0)
	s_barrier
; #define PG8_STAGE(bufoff, gbase, voff) do { _Pragma("unroll") for (int _i = 0; _i < 2; ++_i) \
;         __builtin_amdgcn_global_load_lds((const unsigned*)((const char*)(gbase) + (voff)[_i]), (PG8_LAS unsigned*)(lds + (bufoff) + ldsw + _i * 8192), 16, 0, 0); } while (0)
; #define PG8_LDA(dst, b, h) do { _Pragma("unroll") for (int m = 0; m < 4; ++m) _Pragma("unroll") for (int k = 0; k < 2; ++k) dst[m][k] = *(const PG8_LAS bf16x8*)(lds + PG8_SA(b, h) + aoff + m * 2048 + k * 1024); } while (0)
; #define PG8_LDB(dst, b, h) do { _Pragma("unroll") for (int n = 0; n < 2; ++n) _Pragma("unroll") for (int k = 0; k < 2; ++k) dst[n][k] = *(const PG8_LAS bf16x8*)(lds + PG8_SB(b, h) + boff + n * 2048 + k * 1024); } while (0)
; #define PG8_MMA(ai, bj, At, Bt) do { __builtin_amdgcn_s_setprio(1); _Pragma("unroll") for (int m = 0; m < 4; ++m) _Pragma("unroll") for (int n = 0; n < 2; ++n) _Pragma("unroll") for (int k = 0; k < 2; ++k) \
;         acc[ai][bj][m][n] = __builtin_amdgcn_mfma_f32_16x16x32_bf16(Bt[n][k], At[m][k], acc[ai][bj][m][n], 0, 0, 0); __builtin_amdgcn_s_setprio(0); } while (0)
; #define PG8_BAR __builtin_amdgcn_s_barrier()
; template <class Epi, class Sched, bool ALIGN_EPI = false, bool SP2 = false>
; __device__ __forceinline__ void gemm_phase(PG8_LAS unsigned char* lds, const Gemm g, const Sched& S, const Epi& E) {
;     ...
;             if constexpr (SP2) {
;             PG8_LDB(B0, 0, 0); PG8_LDB(B1, 0, 1); PG8_SCHED; PG8_LDA(At, 0, 0); PG8_STAGE(PG8_SA(1, 1), a1 + hstep, voffA);
;             PG8_WAIT_V(8); PG8_WAIT_L(0); PG8_BAR; PG8_MMA(0, 0, At, B0); PG8_MMA(0, 1, At, B1); PG8_BAR; PG8_SCHED;
;             PG8_LDA(At, 0, 1); PG8_STAGE(PG8_SB(0, 0), b2, voffB); PG8_STAGE(PG8_SB(0, 1), b2 + hstep, voffB); PG8_STAGE(PG8_SA(0, 0), a2, voffA);
;             PG8_WAIT_V(8); PG8_WAIT_L(0); PG8_BAR; PG8_MMA(1, 0, At, B0); PG8_MMA(1, 1, At, B1); PG8_BAR; PG8_SCHED;
;             PG8_LDB(B0, 1, 0); PG8_LDB(B1, 1, 1); PG8_SCHED; PG8_LDA(At, 1, 0); PG8_STAGE(PG8_SA(0, 1), a2 + hstep, voffA);
;             PG8_WAIT_V(8); PG8_WAIT_L(0); PG8_BAR; PG8_MMA(0, 0, At, B0); PG8_MMA(0, 1, At, B1); PG8_BAR; PG8_SCHED;
;             PG8_LDA(At, 1, 1); PG8_STAGE(PG8_SB(1, 0), b3, voffB); PG8_STAGE(PG8_SB(1, 1), b3 + hstep, voffB); PG8_STAGE(PG8_SA(1, 0), a3, voffA);
;             PG8_WAIT_V(8); PG8_WAIT_L(0); PG8_BAR; PG8_MMA(1, 0, At, B0); PG8_MMA(1, 1, At, B1); PG8_BAR; PG8_SCHED;
	s_setprio 1
	s_waitcnt lgkmcnt(0)
	v_mfma_f32_16x16x32_bf16 v[60:63], v[146:149], v[194:197], v[60:63]
	v_mfma_f32_16x16x32_bf16 v[56:59], v[160:163], v[194:197], v[56:59]
	v_mfma_f32_16x16x32_bf16 v[44:47], v[146:149], v[202:205], v[44:47]
	v_mfma_f32_16x16x32_bf16 v[40:43], v[160:163], v[202:205], v[40:43]
	v_mfma_f32_16x16x32_bf16 v[28:31], v[146:149], v[210:213], v[28:31]
	v_mfma_f32_16x16x32_bf16 v[24:27], v[160:163], v[210:213], v[24:27]
	v_mfma_f32_16x16x32_bf16 v[12:15], v[146:149], v[218:221], v[12:15]
	v_mfma_f32_16x16x32_bf16 v[8:11], v[160:163], v[218:221], v[8:11]
	v_mfma_f32_16x16x32_bf16 v[60:63], v[156:159], v[198:201], v[60:63]
	v_mfma_f32_16x16x32_bf16 v[56:59], v[164:167], v[198:201], v[56:59]
	v_mfma_f32_16x16x32_bf16 v[44:47], v[156:159], v[206:209], v[44:47]
	v_mfma_f32_16x16x32_bf16 v[40:43], v[164:167], v[206:209], v[40:43]
	v_mfma_f32_16x16x32_bf16 v[28:31], v[156:159], v[214:217], v[28:31]
	v_mfma_f32_16x16x32_bf16 v[24:27], v[164:167], v[214:217], v[24:27]
	v_mfma_f32_16x16x32_bf16 v[12:15], v[156:159], v[222:225], v[12:15]
	v_mfma_f32_16x16x32_bf16 v[8:11], v[164:167], v[222:225], v[8:11]
	s_setprio 0
	s_setprio 1
	v_mfma_f32_16x16x32_bf16 v[52:55], v[168:171], v[194:197], v[52:55]
	v_mfma_f32_16x16x32_bf16 v[48:51], v[176:179], v[194:197], v[48:51]
	v_mfma_f32_16x16x32_bf16 v[36:39], v[168:171], v[202:205], v[36:39]
	v_mfma_f32_16x16x32_bf16 v[32:35], v[176:179], v[202:205], v[32:35]
	v_mfma_f32_16x16x32_bf16 v[20:23], v[168:171], v[210:213], v[20:23]
	v_mfma_f32_16x16x32_bf16 v[16:19], v[176:179], v[210:213], v[16:19]
	v_mfma_f32_16x16x32_bf16 v[4:7], v[168:171], v[218:221], v[4:7]
	v_mfma_f32_16x16x32_bf16 v[0:3], v[176:179], v[218:221], v[0:3]
	v_mfma_f32_16x16x32_bf16 v[52:55], v[172:175], v[198:201], v[52:55]
	v_mfma_f32_16x16x32_bf16 v[48:51], v[190:193], v[198:201], v[48:51]
	v_mfma_f32_16x16x32_bf16 v[36:39], v[172:175], v[206:209], v[36:39]
	v_mfma_f32_16x16x32_bf16 v[32:35], v[190:193], v[206:209], v[32:35]
	v_mfma_f32_16x16x32_bf16 v[20:23], v[172:175], v[214:217], v[20:23]
	v_mfma_f32_16x16x32_bf16 v[16:19], v[190:193], v[214:217], v[16:19]
	v_mfma_f32_16x16x32_bf16 v[4:7], v[172:175], v[222:225], v[4:7]
	v_mfma_f32_16x16x32_bf16 v[0:3], v[190:193], v[222:225], v[0:3]
	s_setprio 0
	s_barrier
	s_sleep 2
	s_add_i32 s51, 0, 0x18000
	s_add_i32 s52, 0, 0x1c000
	v_add_u32_e32 v164, s51, v151
	v_add_u32_e32 v190, s52, v151
	ds_read_b128 v[146:149], v164
	ds_read_b128 v[156:159], v164 offset:1024
	ds_read_b128 v[160:163], v164 offset:2048
	ds_read_b128 v[164:167], v164 offset:3072
	ds_read_b128 v[168:171], v190
	ds_read_b128 v[172:175], v190 offset:1024
	ds_read_b128 v[176:179], v190 offset:2048
	ds_read_b128 v[190:193], v190 offset:3072
	s_add_u32 s36, s36, 0x80000
	s_addc_u32 s37, s37, 0
	s_mov_b32 m0, s29
	v_lshl_add_u64 v[230:231], s[36:37], 0, v[134:135]
	ds_read_b128 v[194:197], v155 offset:32768
	ds_read_b128 v[198:201], v155 offset:33792
	ds_read_b128 v[202:205], v155 offset:34816
	ds_read_b128 v[206:209], v155 offset:35840
	ds_read_b128 v[210:213], v155 offset:36864
	ds_read_b128 v[214:217], v155 offset:37888
	ds_read_b128 v[218:221], v155 offset:38912
	ds_read_b128 v[222:225], v155 offset:39936
	global_load_lds_dwordx4 v[230:231], off
	v_lshl_add_u64 v[230:231], s[36:37], 0, v[130:131]
	s_mov_b32 m0, s38
	s_nop 0
	global_load_lds_dwordx4 v[230:231], off
	s_waitcnt vmcnt(8)
	s_waitcnt lgkmcnt(0)
	s_barrier
	s_setprio 1
	s_waitcnt lgkmcnt(0)
	v_mfma_f32_16x16x32_bf16 v[124:127], v[146:149], v[194:197], v[124:127]
	v_mfma_f32_16x16x32_bf16 v[120:123], v[160:163], v[194:197], v[120:123]
	v_mfma_f32_16x16x32_bf16 v[108:111], v[146:149], v[202:205], v[108:111]
	v_mfma_f32_16x16x32_bf16 v[104:107], v[160:163], v[202:205], v[104:107]
	v_mfma_f32_16x16x32_bf16 v[92:95], v[146:149], v[210:213], v[92:95]
	v_mfma_f32_16x16x32_bf16 v[88:91], v[160:163], v[210:213], v[88:91]
	v_mfma_f32_16x16x32_bf16 v[76:79], v[146:149], v[218:221], v[76:79]
	v_mfma_f32_16x16x32_bf16 v[72:75], v[160:163], v[218:221], v[72:75]
	v_mfma_f32_16x16x32_bf16 v[124:127], v[156:159], v[198:201], v[124:127]
	v_mfma_f32_16x16x32_bf16 v[120:123], v[164:167], v[198:201], v[120:123]
	v_mfma_f32_16x16x32_bf16 v[108:111], v[156:159], v[206:209], v[108:111]
	v_mfma_f32_16x16x32_bf16 v[104:107], v[164:167], v[206:209], v[104:107]
	v_mfma_f32_16x16x32_bf16 v[92:95], v[156:159], v[214:217], v[92:95]
	v_mfma_f32_16x16x32_bf16 v[88:91], v[164:167], v[214:217], v[88:91]
	v_mfma_f32_16x16x32_bf16 v[76:79], v[156:159], v[222:225], v[76:79]
	v_mfma_f32_16x16x32_bf16 v[72:75], v[164:167], v[222:225], v[72:75]
	s_setprio 0
	s_setprio 1
	v_mfma_f32_16x16x32_bf16 v[116:119], v[168:171], v[194:197], v[116:119]
	v_mfma_f32_16x16x32_bf16 v[112:115], v[176:179], v[194:197], v[112:115]
	v_mfma_f32_16x16x32_bf16 v[100:103], v[168:171], v[202:205], v[100:103]
	v_mfma_f32_16x16x32_bf16 v[96:99], v[176:179], v[202:205], v[96:99]
	v_mfma_f32_16x16x32_bf16 v[84:87], v[168:171], v[210:213], v[84:87]
	v_mfma_f32_16x16x32_bf16 v[80:83], v[176:179], v[210:213], v[80:83]
	v_mfma_f32_16x16x32_bf16 v[68:71], v[168:171], v[218:221], v[68:71]
	v_mfma_f32_16x16x32_bf16 v[64:67], v[176:179], v[218:221], v[64:67]
	v_mfma_f32_16x16x32_bf16 v[116:119], v[172:175], v[198:201], v[116:119]
	v_mfma_f32_16x16x32_bf16 v[112:115], v[190:193], v[198:201], v[112:115]
	v_mfma_f32_16x16x32_bf16 v[100:103], v[172:175], v[206:209], v[100:103]
	v_mfma_f32_16x16x32_bf16 v[96:99], v[190:193], v[206:209], v[96:99]
	v_mfma_f32_16x16x32_bf16 v[84:87], v[172:175], v[214:217], v[84:87]
	v_mfma_f32_16x16x32_bf16 v[80:83], v[190:193], v[214:217], v[80:83]
	v_mfma_f32_16x16x32_bf16 v[68:71], v[172:175], v[222:225], v[68:71]
	v_mfma_f32_16x16x32_bf16 v[64:67], v[190:193], v[222:225], v[64:67]
	s_setprio 0
	s_barrier
; #define PG8_STAGE(bufoff, gbase, voff) do { _Pragma("unroll") for (int _i = 0; _i < 2; ++_i) \
;         __builtin_amdgcn_global_load_lds((const unsigned*)((const char*)(gbase) + (voff)[_i]), (PG8_LAS unsigned*)(lds + (bufoff) + ldsw + _i * 8192), 16, 0, 0); } while (0)
; #define PG8_LDA(dst, b, h) do { _Pragma("unroll") for (int m = 0; m < 4; ++m) _Pragma("unroll") for (int k = 0; k < 2; ++k) dst[m][k] = *(const PG8_LAS bf16x8*)(lds + PG8_SA(b, h) + aoff + m * 2048 + k * 1024); } while (0)
; #define PG8_LDB(dst, b, h) do { _Pragma("unroll") for (int n = 0; n < 2; ++n) _Pragma("unroll") for (int k = 0; k < 2; ++k) dst[n][k] = *(const PG8_LAS bf16x8*)(lds + PG8_SB(b, h) + boff + n * 2048 + k * 1024); } while (0)
; #define PG8_MMA(ai, bj, At, Bt) do { __builtin_amdgcn_s_setprio(1); _Pragma("unroll") for (int m = 0; m < 4; ++m) _Pragma("unroll") for (int n = 0; n < 2; ++n) _Pragma("unroll") for (int k = 0; k < 2; ++k) \
;         acc[ai][bj][m][n] = __builtin_amdgcn_mfma_f32_16x16x32_bf16(Bt[n][k], At[m][k], acc[ai][bj][m][n], 0, 0, 0); __builtin_amdgcn_s_setprio(0); } while (0)
; template <class Epi, class Sched, bool ALIGN_EPI = false, bool SP2 = false>
; __device__ __forceinline__ void gemm_phase(PG8_LAS unsigned char* lds, const Gemm g, const Sched& S, const Epi& E) {
;     ...
;         for (int t = 0; t < nt; t += 2) {
;     ...
;             if constexpr (SP2) {
;             PG8_LDB(B0, 0, 0); PG8_LDB(B1, 0, 1); PG8_SCHED; PG8_LDA(At, 0, 0); PG8_STAGE(PG8_SA(1, 1), a1 + hstep, voffA);
;             PG8_WAIT_V(8); PG8_WAIT_L(0); PG8_BAR; PG8_MMA(0, 0, At, B0); PG8_MMA(0, 1, At, B1); PG8_BAR; PG8_SCHED;
;             PG8_LDA(At, 0, 1); PG8_STAGE(PG8_SB(0, 0), b2, voffB); PG8_STAGE(PG8_SB(0, 1), b2 + hstep, voffB); PG8_STAGE(PG8_SA(0, 0), a2, voffA);
;             PG8_WAIT_V(8); PG8_WAIT_L(0); PG8_BAR; PG8_MMA(1, 0, At, B0); PG8_MMA(1, 1, At, B1); PG8_BAR; PG8_SCHED;
;             PG8_LDB(B0, 1, 0); PG8_LDB(B1, 1, 1); PG8_SCHED; PG8_LDA(At, 1, 0); PG8_STAGE(PG8_SA(0, 1), a2 + hstep, voffA);
;             PG8_WAIT_V(8); PG8_WAIT_L(0); PG8_BAR; PG8_MMA(0, 0, At, B0); PG8_MMA(0, 1, At, B1); PG8_BAR; PG8_SCHED;
;             PG8_LDA(At, 1, 1); PG8_STAGE(PG8_SB(1, 0), b3, voffB); PG8_STAGE(PG8_SB(1, 1), b3 + hstep, voffB); PG8_STAGE(PG8_SA(1, 0), a3, voffA);
;             PG8_WAIT_V(8); PG8_WAIT_L(0); PG8_BAR; PG8_MMA(1, 0, At, B0); PG8_MMA(1, 1, At, B1); PG8_BAR; PG8_SCHED;
	s_sleep 2
	s_add_i32 s36, s51, s2
	v_lshl_add_u64 v[180:181], v[180:181], 0, s[8:9]
	s_mov_b32 m0, s36
	ds_read_b128 v[194:197], v155 offset:49152
	ds_read_b128 v[198:201], v155 offset:50176
	ds_read_b128 v[202:205], v155 offset:51200
	ds_read_b128 v[206:209], v155 offset:52224
	ds_read_b128 v[210:213], v155 offset:53248
	ds_read_b128 v[214:217], v155 offset:54272
	ds_read_b128 v[218:221], v155 offset:55296
	ds_read_b128 v[222:225], v155 offset:56320
	global_load_lds_dwordx4 v[180:181], off
	s_add_i32 m0, s36, 0x2000
	s_add_u32 s34, s34, 0x80080
	v_lshl_add_u64 v[180:181], v[188:189], 0, s[8:9]
	s_addc_u32 s35, s35, 0
	s_add_i32 s36, s52, s2
	global_load_lds_dwordx4 v[180:181], off
	v_lshl_add_u64 v[180:181], s[34:35], 0, v[132:133]
	s_mov_b32 m0, s36
	s_nop 0
	global_load_lds_dwordx4 v[180:181], off
	v_lshl_add_u64 v[180:181], s[34:35], 0, v[128:129]
	s_add_i32 m0, s36, 0x2000
	s_nop 0
	global_load_lds_dwordx4 v[180:181], off
	v_lshl_add_u64 v[180:181], v[226:227], 0, s[8:9]
	s_mov_b32 m0, s40
	s_nop 0
	global_load_lds_dwordx4 v[180:181], off
	v_lshl_add_u64 v[180:181], v[228:229], 0, s[8:9]
	s_mov_b32 m0, s41
	s_nop 0
	global_load_lds_dwordx4 v[180:181], off
	s_waitcnt vmcnt(8)
	s_waitcnt lgkmcnt(0)
	s_barrier
	s_setprio 1
	s_waitcnt lgkmcnt(0)
	v_mfma_f32_16x16x32_bf16 v[60:63], v[146:149], v[194:197], v[60:63]
	v_mfma_f32_16x16x32_bf16 v[56:59], v[160:163], v[194:197], v[56:59]
	v_mfma_f32_16x16x32_bf16 v[44:47], v[146:149], v[202:205], v[44:47]
	v_mfma_f32_16x16x32_bf16 v[40:43], v[160:163], v[202:205], v[40:43]
	v_mfma_f32_16x16x32_bf16 v[28:31], v[146:149], v[210:213], v[28:31]
	v_mfma_f32_16x16x32_bf16 v[24:27], v[160:163], v[210:213], v[24:27]
	v_mfma_f32_16x16x32_bf16 v[12:15], v[146:149], v[218:221], v[12:15]
	v_mfma_f32_16x16x32_bf16 v[8:11], v[160:163], v[218:221], v[8:11]
	v_mfma_f32_16x16x32_bf16 v[60:63], v[156:159], v[198:201], v[60:63]
	v_mfma_f32_16x16x32_bf16 v[56:59], v[164:167], v[198:201], v[56:59]
	v_mfma_f32_16x16x32_bf16 v[44:47], v[156:159], v[206:209], v[44:47]
	v_mfma_f32_16x16x32_bf16 v[40:43], v[164:167], v[206:209], v[40:43]
	v_mfma_f32_16x16x32_bf16 v[28:31], v[156:159], v[214:217], v[28:31]
	v_mfma_f32_16x16x32_bf16 v[24:27], v[164:167], v[214:217], v[24:27]
	v_mfma_f32_16x16x32_bf16 v[12:15], v[156:159], v[222:225], v[12:15]
	v_mfma_f32_16x16x32_bf16 v[8:11], v[164:167], v[222:225], v[8:11]
	s_setprio 0
	s_setprio 1
	v_mfma_f32_16x16x32_bf16 v[52:55], v[168:171], v[194:197], v[52:55]
	v_mfma_f32_16x16x32_bf16 v[48:51], v[176:179], v[194:197], v[48:51]
	v_mfma_f32_16x16x32_bf16 v[36:39], v[168:171], v[202:205], v[36:39]
	v_mfma_f32_16x16x32_bf16 v[32:35], v[176:179], v[202:205], v[32:35]
	v_mfma_f32_16x16x32_bf16 v[20:23], v[168:171], v[210:213], v[20:23]
	v_mfma_f32_16x16x32_bf16 v[16:19], v[176:179], v[210:213], v[16:19]
	v_mfma_f32_16x16x32_bf16 v[4:7], v[168:171], v[218:221], v[4:7]
	v_mfma_f32_16x16x32_bf16 v[0:3], v[176:179], v[218:221], v[0:3]
	v_mfma_f32_16x16x32_bf16 v[52:55], v[172:175], v[198:201], v[52:55]
	v_mfma_f32_16x16x32_bf16 v[48:51], v[190:193], v[198:201], v[48:51]
	v_mfma_f32_16x16x32_bf16 v[36:39], v[172:175], v[206:209], v[36:39]
	v_mfma_f32_16x16x32_bf16 v[32:35], v[190:193], v[206:209], v[32:35]
	v_mfma_f32_16x16x32_bf16 v[20:23], v[172:175], v[214:217], v[20:23]
	v_mfma_f32_16x16x32_bf16 v[16:19], v[190:193], v[214:217], v[16:19]
	v_mfma_f32_16x16x32_bf16 v[4:7], v[172:175], v[222:225], v[4:7]
	v_mfma_f32_16x16x32_bf16 v[0:3], v[190:193], v[222:225], v[0:3]
	s_setprio 0
	s_barrier
	s_sleep 2
	s_add_i32 s50, s50, 2
	s_add_u32 s30, s30, 0x100
	s_addc_u32 s31, s31, 0
	s_add_u32 s48, s48, 0x100
	s_addc_u32 s49, s49, 0
	s_cmp_gt_u32 s50, 29
	s_cbranch_scc0 .LBB0_621
	s_and_b64 vcc, exec, s[10:11]
	s_cbranch_vccz .LBB0_624
	s_barrier

; #define PG8_STAGE(bufoff, gbase, voff) do { _Pragma("unroll") for (int _i = 0; _i < 2; ++_i) \
;         __builtin_amdgcn_global_load_lds((const unsigned*)((const char*)(gbase) + (voff)[_i]), (PG8_LAS unsigned*)(lds + (bufoff) + ldsw + _i * 8192), 16, 0, 0); } while (0)
; #define PG8_LDA(dst, b, h) do { _Pragma("unroll") for (int m = 0; m < 4; ++m) _Pragma("unroll") for (int k = 0; k < 2; ++k) dst[m][k] = *(const PG8_LAS bf16x8*)(lds + PG8_SA(b, h) + aoff + m * 2048 + k * 1024); } while (0)
; #define PG8_LDB(dst, b, h) do { _Pragma("unroll") for (int n = 0; n < 2; ++n) _Pragma("unroll") for (int k = 0; k < 2; ++k) dst[n][k] = *(const PG8_LAS bf16x8*)(lds + PG8_SB(b, h) + boff + n * 2048 + k * 1024); } while (0)
; template <class Epi, class Sched, bool ALIGN_EPI = false, bool SP2 = false>
; __device__ __forceinline__ void gemm_phase(PG8_LAS unsigned char* lds, const Gemm g, const Sched& S, const Epi& E) {
;     ...
;         for (int t = 0; t < nt; t += 2) {
;             const bool last = (t == nt - 2);
;             const char* a1 = cA + (size_t)(t + 1) * kstep;
;             const char* a2 = last ? nA : cA + (size_t)(t + 2) * kstep; const char* b2 = last ? nB : cB + (size_t)(t + 2) * kstep;
;             const char* a3 = a2 + kstep; const char* b3 = b2 + kstep;
;             if (last && has_next) S.a_ready(nxt);
;             if constexpr (SP2) {
;             PG8_LDB(B0, 0, 0); PG8_LDB(B1, 0, 1); PG8_SCHED; PG8_LDA(At, 0, 0); PG8_STAGE(PG8_SA(1, 1), a1 + hstep, voffA);
;             PG8_WAIT_V(8); PG8_WAIT_L(0); PG8_BAR; PG8_MMA(0, 0, At, B0); PG8_MMA(0, 1, At, B1); PG8_BAR; PG8_SCHED;
;             PG8_LDA(At, 0, 1); PG8_STAGE(PG8_SB(0, 0), b2, voffB); PG8_STAGE(PG8_SB(0, 1), b2 + hstep, voffB); PG8_STAGE(PG8_SA(0, 0), a2, voffA);
;             PG8_WAIT_V(8); PG8_WAIT_L(0); PG8_BAR; PG8_MMA(1, 0, At, B0); PG8_MMA(1, 1, At, B1); PG8_BAR; PG8_SCHED;
;             PG8_LDB(B0, 1, 0); PG8_LDB(B1, 1, 1); PG8_SCHED; PG8_LDA(At, 1, 0); PG8_STAGE(PG8_SA(0, 1), a2 + hstep, voffA);
;             PG8_WAIT_V(8); PG8_WAIT_L(0); PG8_BAR; PG8_MMA(0, 0, At, B0); PG8_MMA(0, 1, At, B1); PG8_BAR; PG8_SCHED;
;             PG8_LDA(At, 1, 1); PG8_STAGE(PG8_SB(1, 0), b3, voffB); PG8_STAGE(PG8_SB(1, 1), b3 + hstep, voffB); PG8_STAGE(PG8_SA(1, 0), a3, voffA);
;             PG8_WAIT_V(8); PG8_WAIT_L(0); PG8_BAR; PG8_MMA(1, 0, At, B0); PG8_MMA(1, 1, At, B1); PG8_BAR; PG8_SCHED;
.LBB0_649:
	ds_read_b128 v[140:143], v165
	ds_read_b128 v[176:179], v165 offset:1024
	ds_read_b128 v[180:183], v165 offset:2048
	ds_read_b128 v[184:187], v165 offset:3072
	ds_read_b128 v[188:191], v166
	ds_read_b128 v[192:195], v166 offset:1024
	ds_read_b128 v[196:199], v166 offset:2048
	ds_read_b128 v[200:203], v166 offset:3072
	s_add_u32 s40, s8, 0xffea0080
	s_addc_u32 s41, s9, -1
	s_cmpk_eq_i32 s65, 0x54
	s_cselect_b32 s43, s37, s41
	s_cselect_b32 s42, s36, s40
	s_cselect_b32 s41, s11, s39
	s_cselect_b32 s40, s10, s38
	s_mov_b32 m0, s54
	v_lshl_add_u64 v[144:145], s[8:9], 0, v[136:137]
	ds_read_b128 v[204:207], v167
	ds_read_b128 v[208:211], v167 offset:1024
	ds_read_b128 v[212:215], v167 offset:2048
	ds_read_b128 v[216:219], v167 offset:3072
	ds_read_b128 v[220:223], v167 offset:4096
	ds_read_b128 v[224:227], v167 offset:5120
	ds_read_b128 v[228:231], v167 offset:6144
	ds_read_b128 v[232:235], v167 offset:7168
	global_load_lds_dwordx4 v[144:145], off
	v_lshl_add_u64 v[144:145], s[8:9], 0, v[138:139]
	s_mov_b32 m0, s55
	s_nop 0
	global_load_lds_dwordx4 v[144:145], off
	s_waitcnt vmcnt(8)
	s_waitcnt lgkmcnt(0)
	s_barrier
	s_setprio 1
	s_waitcnt lgkmcnt(0)
	v_mfma_f32_16x16x32_bf16 v[124:127], v[140:143], v[204:207], v[124:127]
	v_mfma_f32_16x16x32_bf16 v[120:123], v[180:183], v[204:207], v[120:123]
	v_mfma_f32_16x16x32_bf16 v[108:111], v[140:143], v[212:215], v[108:111]
	v_mfma_f32_16x16x32_bf16 v[104:107], v[180:183], v[212:215], v[104:107]
	v_mfma_f32_16x16x32_bf16 v[92:95], v[140:143], v[220:223], v[92:95]
	v_mfma_f32_16x16x32_bf16 v[88:91], v[180:183], v[220:223], v[88:91]
	v_mfma_f32_16x16x32_bf16 v[76:79], v[140:143], v[228:231], v[76:79]
	v_mfma_f32_16x16x32_bf16 v[72:75], v[180:183], v[228:231], v[72:75]
	v_mfma_f32_16x16x32_bf16 v[124:127], v[176:179], v[208:211], v[124:127]
	v_mfma_f32_16x16x32_bf16 v[120:123], v[184:187], v[208:211], v[120:123]
	v_mfma_f32_16x16x32_bf16 v[108:111], v[176:179], v[216:219], v[108:111]
	v_mfma_f32_16x16x32_bf16 v[104:107], v[184:187], v[216:219], v[104:107]
	v_mfma_f32_16x16x32_bf16 v[92:95], v[176:179], v[224:227], v[92:95]
	v_mfma_f32_16x16x32_bf16 v[88:91], v[184:187], v[224:227], v[88:91]
	v_mfma_f32_16x16x32_bf16 v[76:79], v[176:179], v[232:235], v[76:79]
	v_mfma_f32_16x16x32_bf16 v[72:75], v[184:187], v[232:235], v[72:75]
	s_setprio 0
	s_setprio 1
	v_mfma_f32_16x16x32_bf16 v[116:119], v[188:191], v[204:207], v[116:119]
	v_mfma_f32_16x16x32_bf16 v[112:115], v[196:199], v[204:207], v[112:115]
	v_mfma_f32_16x16x32_bf16 v[100:103], v[188:191], v[212:215], v[100:103]
	v_mfma_f32_16x16x32_bf16 v[96:99], v[196:199], v[212:215], v[96:99]
	v_mfma_f32_16x16x32_bf16 v[84:87], v[188:191], v[220:223], v[84:87]
	v_mfma_f32_16x16x32_bf16 v[80:83], v[196:199], v[220:223], v[80:83]
	v_mfma_f32_16x16x32_bf16 v[68:71], v[188:191], v[228:231], v[68:71]
	v_mfma_f32_16x16x32_bf16 v[64:67], v[196:199], v[228:231], v[64:67]
	v_mfma_f32_16x16x32_bf16 v[116:119], v[192:195], v[208:211], v[116:119]
	v_mfma_f32_16x16x32_bf16 v[112:115], v[200:203], v[208:211], v[112:115]
	v_mfma_f32_16x16x32_bf16 v[100:103], v[192:195], v[216:219], v[100:103]
	v_mfma_f32_16x16x32_bf16 v[96:99], v[200:203], v[216:219], v[96:99]
	v_mfma_f32_16x16x32_bf16 v[84:87], v[192:195], v[224:227], v[84:87]
	v_mfma_f32_16x16x32_bf16 v[80:83], v[200:203], v[224:227], v[80:83]
	v_mfma_f32_16x16x32_bf16 v[68:71], v[192:195], v[232:235], v[68:71]
	v_mfma_f32_16x16x32_bf16 v[64:67], v[200:203], v[232:235], v[64:67]
	s_setprio 0
	s_barrier
	s_sleep 2
	s_mov_b32 m0, s56
	v_lshl_add_u64 v[144:145], s[40:41], 0, v[128:129]
	s_add_u32 s66, s40, 0x160000
	ds_read_b128 v[204:207], v167 offset:16384
	ds_read_b128 v[208:211], v167 offset:17408
	ds_read_b128 v[212:215], v167 offset:18432
	ds_read_b128 v[216:219], v167 offset:19456
	ds_read_b128 v[220:223], v167 offset:20480
	ds_read_b128 v[224:227], v167 offset:21504
	ds_read_b128 v[228:231], v167 offset:22528
	ds_read_b128 v[232:235], v167 offset:23552
	global_load_lds_dwordx4 v[144:145], off
	v_lshl_add_u64 v[236:237], s[40:41], 0, v[130:131]
	s_mov_b32 m0, s57
	s_addc_u32 s67, s41, 0
	global_load_lds_dwordx4 v[236:237], off
	v_lshl_add_u64 v[238:239], s[66:67], 0, v[128:129]
	s_mov_b32 m0, s58
	v_lshl_add_u64 v[240:241], s[42:43], 0, v[130:131]
	global_load_lds_dwordx4 v[238:239], off
	v_lshl_add_u64 v[238:239], s[66:67], 0, v[130:131]
	s_mov_b32 m0, s59
	s_nop 0
	global_load_lds_dwordx4 v[238:239], off
	v_lshl_add_u64 v[238:239], s[42:43], 0, v[128:129]
	s_mov_b32 m0, s33
	s_nop 0
	global_load_lds_dwordx4 v[238:239], off
	s_mov_b32 m0, s46
	s_nop 0
	global_load_lds_dwordx4 v[240:241], off
	s_waitcnt vmcnt(8)
	s_waitcnt lgkmcnt(0)
	s_barrier
; #define PG8_STAGE(bufoff, gbase, voff) do { _Pragma("unroll") for (int _i = 0; _i < 2; ++_i) \
;         __builtin_amdgcn_global_load_lds((const unsigned*)((const char*)(gbase) + (voff)[_i]), (PG8_LAS unsigned*)(lds + (bufoff) + ldsw + _i * 8192), 16, 0, 0); } while (0)
; #define PG8_LDA(dst, b, h) do { _Pragma("unroll") for (int m = 0; m < 4; ++m) _Pragma("unroll") for (int k = 0; k < 2; ++k) dst[m][k] = *(const PG8_LAS bf16x8*)(lds + PG8_SA(b, h) + aoff + m * 2048 + k * 1024); } while (0)
; #define PG8_LDB(dst, b, h) do { _Pragma("unroll") for (int n = 0; n < 2; ++n) _Pragma("unroll") for (int k = 0; k < 2; ++k) dst[n][k] = *(const PG8_LAS bf16x8*)(lds + PG8_SB(b, h) + boff + n * 2048 + k * 1024); } while (0)
; #define PG8_MMA(ai, bj, At, Bt) do { __builtin_amdgcn_s_setprio(1); _Pragma("unroll") for (int m = 0; m < 4; ++m) _Pragma("unroll") for (int n = 0; n < 2; ++n) _Pragma("unroll") for (int k = 0; k < 2; ++k) \
;         acc[ai][bj][m][n] = __builtin_amdgcn_mfma_f32_16x16x32_bf16(Bt[n][k], At[m][k], acc[ai][bj][m][n], 0, 0, 0); __builtin_amdgcn_s_setprio(0); } while (0)
; #define PG8_BAR __builtin_amdgcn_s_barrier()
; template <class Epi, class Sched, bool ALIGN_EPI = false, bool SP2 = false>
; __device__ __forceinline__ void gemm_phase(PG8_LAS unsigned char* lds, const Gemm g, const Sched& S, const Epi& E) {
;     ...
;             if constexpr (SP2) {
;             PG8_LDB(B0, 0, 0); PG8_LDB(B1, 0, 1); PG8_SCHED; PG8_LDA(At, 0, 0); PG8_STAGE(PG8_SA(1, 1), a1 + hstep, voffA);
;             PG8_WAIT_V(8); PG8_WAIT_L(0); PG8_BAR; PG8_MMA(0, 0, At, B0); PG8_MMA(0, 1, At, B1); PG8_BAR; PG8_SCHED;
;             PG8_LDA(At, 0, 1); PG8_STAGE(PG8_SB(0, 0), b2, voffB); PG8_STAGE(PG8_SB(0, 1), b2 + hstep, voffB); PG8_STAGE(PG8_SA(0, 0), a2, voffA);
;             PG8_WAIT_V(8); PG8_WAIT_L(0); PG8_BAR; PG8_MMA(1, 0, At, B0); PG8_MMA(1, 1, At, B1); PG8_BAR; PG8_SCHED;
;             PG8_LDB(B0, 1, 0); PG8_LDB(B1, 1, 1); PG8_SCHED; PG8_LDA(At, 1, 0); PG8_STAGE(PG8_SA(0, 1), a2 + hstep, voffA);
;             PG8_WAIT_V(8); PG8_WAIT_L(0); PG8_BAR; PG8_MMA(0, 0, At, B0); PG8_MMA(0, 1, At, B1); PG8_BAR; PG8_SCHED;
;             PG8_LDA(At, 1, 1); PG8_STAGE(PG8_SB(1, 0), b3, voffB); PG8_STAGE(PG8_SB(1, 1), b3 + hstep, voffB); PG8_STAGE(PG8_SA(1, 0), a3, voffA);
;             PG8_WAIT_V(8); PG8_WAIT_L(0); PG8_BAR; PG8_MMA(1, 0, At, B0); PG8_MMA(1, 1, At, B1); PG8_BAR; PG8_SCHED;
	s_setprio 1
	s_waitcnt lgkmcnt(0)
	v_mfma_f32_16x16x32_bf16 v[60:63], v[140:143], v[204:207], v[60:63]
	v_mfma_f32_16x16x32_bf16 v[56:59], v[180:183], v[204:207], v[56:59]
	v_mfma_f32_16x16x32_bf16 v[44:47], v[140:143], v[212:215], v[44:47]
	v_mfma_f32_16x16x32_bf16 v[40:43], v[180:183], v[212:215], v[40:43]
	v_mfma_f32_16x16x32_bf16 v[28:31], v[140:143], v[220:223], v[28:31]
	v_mfma_f32_16x16x32_bf16 v[24:27], v[180:183], v[220:223], v[24:27]
	v_mfma_f32_16x16x32_bf16 v[12:15], v[140:143], v[228:231], v[12:15]
	v_mfma_f32_16x16x32_bf16 v[8:11], v[180:183], v[228:231], v[8:11]
	v_mfma_f32_16x16x32_bf16 v[60:63], v[176:179], v[208:211], v[60:63]
	v_mfma_f32_16x16x32_bf16 v[56:59], v[184:187], v[208:211], v[56:59]
	v_mfma_f32_16x16x32_bf16 v[44:47], v[176:179], v[216:219], v[44:47]
	v_mfma_f32_16x16x32_bf16 v[40:43], v[184:187], v[216:219], v[40:43]
	v_mfma_f32_16x16x32_bf16 v[28:31], v[176:179], v[224:227], v[28:31]
	v_mfma_f32_16x16x32_bf16 v[24:27], v[184:187], v[224:227], v[24:27]
	v_mfma_f32_16x16x32_bf16 v[12:15], v[176:179], v[232:235], v[12:15]
	v_mfma_f32_16x16x32_bf16 v[8:11], v[184:187], v[232:235], v[8:11]
	s_setprio 0
	s_setprio 1
	v_mfma_f32_16x16x32_bf16 v[52:55], v[188:191], v[204:207], v[52:55]
	v_mfma_f32_16x16x32_bf16 v[48:51], v[196:199], v[204:207], v[48:51]
	v_mfma_f32_16x16x32_bf16 v[36:39], v[188:191], v[212:215], v[36:39]
	v_mfma_f32_16x16x32_bf16 v[32:35], v[196:199], v[212:215], v[32:35]
	v_mfma_f32_16x16x32_bf16 v[20:23], v[188:191], v[220:223], v[20:23]
	v_mfma_f32_16x16x32_bf16 v[16:19], v[196:199], v[220:223], v[16:19]
	v_mfma_f32_16x16x32_bf16 v[4:7], v[188:191], v[228:231], v[4:7]
	v_mfma_f32_16x16x32_bf16 v[0:3], v[196:199], v[228:231], v[0:3]
	v_mfma_f32_16x16x32_bf16 v[52:55], v[192:195], v[208:211], v[52:55]
	v_mfma_f32_16x16x32_bf16 v[48:51], v[200:203], v[208:211], v[48:51]
	v_mfma_f32_16x16x32_bf16 v[36:39], v[192:195], v[216:219], v[36:39]
	v_mfma_f32_16x16x32_bf16 v[32:35], v[200:203], v[216:219], v[32:35]
	v_mfma_f32_16x16x32_bf16 v[20:23], v[192:195], v[224:227], v[20:23]
	v_mfma_f32_16x16x32_bf16 v[16:19], v[200:203], v[224:227], v[16:19]
	v_mfma_f32_16x16x32_bf16 v[4:7], v[192:195], v[232:235], v[4:7]
	v_mfma_f32_16x16x32_bf16 v[0:3], v[200:203], v[232:235], v[0:3]
	s_setprio 0
	s_barrier
	s_sleep 2
	s_add_i32 s66, 0, 0x1c000
	v_add_u32_e32 v175, s66, v147
	ds_read_b128 v[140:143], v173
	ds_read_b128 v[176:179], v173 offset:1024
	ds_read_b128 v[180:183], v173 offset:2048
	ds_read_b128 v[184:187], v173 offset:3072
	ds_read_b128 v[188:191], v175
	ds_read_b128 v[192:195], v175 offset:1024
	ds_read_b128 v[196:199], v175 offset:2048
	ds_read_b128 v[200:203], v175 offset:3072
	s_add_u32 s42, s42, 0x160000
	s_addc_u32 s43, s43, 0
	s_mov_b32 m0, s47
	v_lshl_add_u64 v[242:243], s[42:43], 0, v[128:129]
	ds_read_b128 v[204:207], v167 offset:32768
	ds_read_b128 v[208:211], v167 offset:33792
	ds_read_b128 v[212:215], v167 offset:34816
	ds_read_b128 v[216:219], v167 offset:35840
	ds_read_b128 v[220:223], v167 offset:36864
	ds_read_b128 v[224:227], v167 offset:37888
	ds_read_b128 v[228:231], v167 offset:38912
	ds_read_b128 v[232:235], v167 offset:39936
	global_load_lds_dwordx4 v[242:243], off
	v_lshl_add_u64 v[242:243], s[42:43], 0, v[130:131]
	s_mov_b32 m0, s48
	s_nop 0
	global_load_lds_dwordx4 v[242:243], off
	s_waitcnt vmcnt(8)
	s_waitcnt lgkmcnt(0)
	s_barrier
	s_setprio 1
	s_waitcnt lgkmcnt(0)
	v_mfma_f32_16x16x32_bf16 v[124:127], v[140:143], v[204:207], v[124:127]
	v_mfma_f32_16x16x32_bf16 v[120:123], v[180:183], v[204:207], v[120:123]
	v_mfma_f32_16x16x32_bf16 v[108:111], v[140:143], v[212:215], v[108:111]
	v_mfma_f32_16x16x32_bf16 v[104:107], v[180:183], v[212:215], v[104:107]
	v_mfma_f32_16x16x32_bf16 v[92:95], v[140:143], v[220:223], v[92:95]
	v_mfma_f32_16x16x32_bf16 v[88:91], v[180:183], v[220:223], v[88:91]
	v_mfma_f32_16x16x32_bf16 v[76:79], v[140:143], v[228:231], v[76:79]
	v_mfma_f32_16x16x32_bf16 v[72:75], v[180:183], v[228:231], v[72:75]
	v_mfma_f32_16x16x32_bf16 v[124:127], v[176:179], v[208:211], v[124:127]
	v_mfma_f32_16x16x32_bf16 v[120:123], v[184:187], v[208:211], v[120:123]
	v_mfma_f32_16x16x32_bf16 v[108:111], v[176:179], v[216:219], v[108:111]
	v_mfma_f32_16x16x32_bf16 v[104:107], v[184:187], v[216:219], v[104:107]
	v_mfma_f32_16x16x32_bf16 v[92:95], v[176:179], v[224:227], v[92:95]
	v_mfma_f32_16x16x32_bf16 v[88:91], v[184:187], v[224:227], v[88:91]
	v_mfma_f32_16x16x32_bf16 v[76:79], v[176:179], v[232:235], v[76:79]
	v_mfma_f32_16x16x32_bf16 v[72:75], v[184:187], v[232:235], v[72:75]
	s_setprio 0
	s_setprio 1
	v_mfma_f32_16x16x32_bf16 v[116:119], v[188:191], v[204:207], v[116:119]
	v_mfma_f32_16x16x32_bf16 v[112:115], v[196:199], v[204:207], v[112:115]
	v_mfma_f32_16x16x32_bf16 v[100:103], v[188:191], v[212:215], v[100:103]
	v_mfma_f32_16x16x32_bf16 v[96:99], v[196:199], v[212:215], v[96:99]
	v_mfma_f32_16x16x32_bf16 v[84:87], v[188:191], v[220:223], v[84:87]
	v_mfma_f32_16x16x32_bf16 v[80:83], v[196:199], v[220:223], v[80:83]
	v_mfma_f32_16x16x32_bf16 v[68:71], v[188:191], v[228:231], v[68:71]
	v_mfma_f32_16x16x32_bf16 v[64:67], v[196:199], v[228:231], v[64:67]
	v_mfma_f32_16x16x32_bf16 v[116:119], v[192:195], v[208:211], v[116:119]
	v_mfma_f32_16x16x32_bf16 v[112:115], v[200:203], v[208:211], v[112:115]
	v_mfma_f32_16x16x32_bf16 v[100:103], v[192:195], v[216:219], v[100:103]
	v_mfma_f32_16x16x32_bf16 v[96:99], v[200:203], v[216:219], v[96:99]
	v_mfma_f32_16x16x32_bf16 v[84:87], v[192:195], v[224:227], v[84:87]
	v_mfma_f32_16x16x32_bf16 v[80:83], v[200:203], v[224:227], v[80:83]
	v_mfma_f32_16x16x32_bf16 v[68:71], v[192:195], v[232:235], v[68:71]
	v_mfma_f32_16x16x32_bf16 v[64:67], v[200:203], v[232:235], v[64:67]
	s_setprio 0
	s_barrier
; #define PG8_STAGE(bufoff, gbase, voff) do { _Pragma("unroll") for (int _i = 0; _i < 2; ++_i) \
;         __builtin_amdgcn_global_load_lds((const unsigned*)((const char*)(gbase) + (voff)[_i]), (PG8_LAS unsigned*)(lds + (bufoff) + ldsw + _i * 8192), 16, 0, 0); } while (0)
; #define PG8_LDA(dst, b, h) do { _Pragma("unroll") for (int m = 0; m < 4; ++m) _Pragma("unroll") for (int k = 0; k < 2; ++k) dst[m][k] = *(const PG8_LAS bf16x8*)(lds + PG8_SA(b, h) + aoff + m * 2048 + k * 1024); } while (0)
; #define PG8_LDB(dst, b, h) do { _Pragma("unroll") for (int n = 0; n < 2; ++n) _Pragma("unroll") for (int k = 0; k < 2; ++k) dst[n][k] = *(const PG8_LAS bf16x8*)(lds + PG8_SB(b, h) + boff + n * 2048 + k * 1024); } while (0)
; #define PG8_MMA(ai, bj, At, Bt) do { __builtin_amdgcn_s_setprio(1); _Pragma("unroll") for (int m = 0; m < 4; ++m) _Pragma("unroll") for (int n = 0; n < 2; ++n) _Pragma("unroll") for (int k = 0; k < 2; ++k) \
;         acc[ai][bj][m][n] = __builtin_amdgcn_mfma_f32_16x16x32_bf16(Bt[n][k], At[m][k], acc[ai][bj][m][n], 0, 0, 0); __builtin_amdgcn_s_setprio(0); } while (0)
; template <class Epi, class Sched, bool ALIGN_EPI = false, bool SP2 = false>
; __device__ __forceinline__ void gemm_phase(PG8_LAS unsigned char* lds, const Gemm g, const Sched& S, const Epi& E) {
;     ...
;         for (int t = 0; t < nt; t += 2) {
;     ...
;             if constexpr (SP2) {
;             PG8_LDB(B0, 0, 0); PG8_LDB(B1, 0, 1); PG8_SCHED; PG8_LDA(At, 0, 0); PG8_STAGE(PG8_SA(1, 1), a1 + hstep, voffA);
;             PG8_WAIT_V(8); PG8_WAIT_L(0); PG8_BAR; PG8_MMA(0, 0, At, B0); PG8_MMA(0, 1, At, B1); PG8_BAR; PG8_SCHED;
;             PG8_LDA(At, 0, 1); PG8_STAGE(PG8_SB(0, 0), b2, voffB); PG8_STAGE(PG8_SB(0, 1), b2 + hstep, voffB); PG8_STAGE(PG8_SA(0, 0), a2, voffA);
;             PG8_WAIT_V(8); PG8_WAIT_L(0); PG8_BAR; PG8_MMA(1, 0, At, B0); PG8_MMA(1, 1, At, B1); PG8_BAR; PG8_SCHED;
;             PG8_LDB(B0, 1, 0); PG8_LDB(B1, 1, 1); PG8_SCHED; PG8_LDA(At, 1, 0); PG8_STAGE(PG8_SA(0, 1), a2 + hstep, voffA);
;             PG8_WAIT_V(8); PG8_WAIT_L(0); PG8_BAR; PG8_MMA(0, 0, At, B0); PG8_MMA(0, 1, At, B1); PG8_BAR; PG8_SCHED;
;             PG8_LDA(At, 1, 1); PG8_STAGE(PG8_SB(1, 0), b3, voffB); PG8_STAGE(PG8_SB(1, 1), b3 + hstep, voffB); PG8_STAGE(PG8_SA(1, 0), a3, voffA);
;             PG8_WAIT_V(8); PG8_WAIT_L(0); PG8_BAR; PG8_MMA(1, 0, At, B0); PG8_MMA(1, 1, At, B1); PG8_BAR; PG8_SCHED;
	s_sleep 2
	s_add_i32 s42, s60, s45
	v_lshl_add_u64 v[144:145], v[144:145], 0, s[18:19]
	s_mov_b32 m0, s42
	ds_read_b128 v[204:207], v167 offset:49152
	ds_read_b128 v[208:211], v167 offset:50176
	ds_read_b128 v[212:215], v167 offset:51200
	ds_read_b128 v[216:219], v167 offset:52224
	ds_read_b128 v[220:223], v167 offset:53248
	ds_read_b128 v[224:227], v167 offset:54272
	ds_read_b128 v[228:231], v167 offset:55296
	ds_read_b128 v[232:235], v167 offset:56320
	global_load_lds_dwordx4 v[144:145], off
	s_add_i32 m0, s42, 0x2000
	s_add_u32 s40, s40, 0x160080
	v_lshl_add_u64 v[144:145], v[236:237], 0, s[18:19]
	s_addc_u32 s41, s41, 0
	s_add_i32 s42, s66, s45
	global_load_lds_dwordx4 v[144:145], off
	v_lshl_add_u64 v[144:145], s[40:41], 0, v[128:129]
	s_mov_b32 m0, s42
	s_nop 0
	global_load_lds_dwordx4 v[144:145], off
	v_lshl_add_u64 v[144:145], s[40:41], 0, v[130:131]
	s_add_i32 m0, s42, 0x2000
	s_nop 0
	global_load_lds_dwordx4 v[144:145], off
	v_lshl_add_u64 v[144:145], v[238:239], 0, s[18:19]
	s_mov_b32 m0, s51
	s_nop 0
	global_load_lds_dwordx4 v[144:145], off
	v_lshl_add_u64 v[144:145], v[240:241], 0, s[18:19]
	s_mov_b32 m0, s52
	s_nop 0
	global_load_lds_dwordx4 v[144:145], off
	s_waitcnt vmcnt(8)
	s_waitcnt lgkmcnt(0)
	s_barrier
	s_setprio 1
	s_waitcnt lgkmcnt(0)
	v_mfma_f32_16x16x32_bf16 v[60:63], v[140:143], v[204:207], v[60:63]
	v_mfma_f32_16x16x32_bf16 v[56:59], v[180:183], v[204:207], v[56:59]
	v_mfma_f32_16x16x32_bf16 v[44:47], v[140:143], v[212:215], v[44:47]
	v_mfma_f32_16x16x32_bf16 v[40:43], v[180:183], v[212:215], v[40:43]
	v_mfma_f32_16x16x32_bf16 v[28:31], v[140:143], v[220:223], v[28:31]
	v_mfma_f32_16x16x32_bf16 v[24:27], v[180:183], v[220:223], v[24:27]
	v_mfma_f32_16x16x32_bf16 v[12:15], v[140:143], v[228:231], v[12:15]
	v_mfma_f32_16x16x32_bf16 v[8:11], v[180:183], v[228:231], v[8:11]
	v_mfma_f32_16x16x32_bf16 v[60:63], v[176:179], v[208:211], v[60:63]
	v_mfma_f32_16x16x32_bf16 v[56:59], v[184:187], v[208:211], v[56:59]
	v_mfma_f32_16x16x32_bf16 v[44:47], v[176:179], v[216:219], v[44:47]
	v_mfma_f32_16x16x32_bf16 v[40:43], v[184:187], v[216:219], v[40:43]
	v_mfma_f32_16x16x32_bf16 v[28:31], v[176:179], v[224:227], v[28:31]
	v_mfma_f32_16x16x32_bf16 v[24:27], v[184:187], v[224:227], v[24:27]
	v_mfma_f32_16x16x32_bf16 v[12:15], v[176:179], v[232:235], v[12:15]
	v_mfma_f32_16x16x32_bf16 v[8:11], v[184:187], v[232:235], v[8:11]
	s_setprio 0
	s_setprio 1
	v_mfma_f32_16x16x32_bf16 v[52:55], v[188:191], v[204:207], v[52:55]
	v_mfma_f32_16x16x32_bf16 v[48:51], v[196:199], v[204:207], v[48:51]
	v_mfma_f32_16x16x32_bf16 v[36:39], v[188:191], v[212:215], v[36:39]
	v_mfma_f32_16x16x32_bf16 v[32:35], v[196:199], v[212:215], v[32:35]
	v_mfma_f32_16x16x32_bf16 v[20:23], v[188:191], v[220:223], v[20:23]
	v_mfma_f32_16x16x32_bf16 v[16:19], v[196:199], v[220:223], v[16:19]
	v_mfma_f32_16x16x32_bf16 v[4:7], v[188:191], v[228:231], v[4:7]
	v_mfma_f32_16x16x32_bf16 v[0:3], v[196:199], v[228:231], v[0:3]
	v_mfma_f32_16x16x32_bf16 v[52:55], v[192:195], v[208:211], v[52:55]
	v_mfma_f32_16x16x32_bf16 v[48:51], v[200:203], v[208:211], v[48:51]
	v_mfma_f32_16x16x32_bf16 v[36:39], v[192:195], v[216:219], v[36:39]
	v_mfma_f32_16x16x32_bf16 v[32:35], v[200:203], v[216:219], v[32:35]
	v_mfma_f32_16x16x32_bf16 v[20:23], v[192:195], v[224:227], v[20:23]
	v_mfma_f32_16x16x32_bf16 v[16:19], v[200:203], v[224:227], v[16:19]
	v_mfma_f32_16x16x32_bf16 v[4:7], v[192:195], v[232:235], v[4:7]
	v_mfma_f32_16x16x32_bf16 v[0:3], v[200:203], v[232:235], v[0:3]
	s_setprio 0
	s_barrier
	s_sleep 2
	s_add_i32 s65, s65, 2
	s_add_u32 s8, s8, 0x100
	s_addc_u32 s9, s9, 0
	s_add_u32 s38, s38, 0x100
	s_addc_u32 s39, s39, 0
	s_cmpk_gt_u32 s65, 0x55
	s_cbranch_scc0 .LBB0_649
	s_and_b64 vcc, exec, s[22:23]
	s_cbranch_vccz .LBB0_652
	s_barrier
